# FFN-up epilogue: the two 8-byte stores per output row merged into one 16-byte store (first half kept in spare VGPRs)
# speedup vs baseline: 1.0076x; 1.0076x over previous
;     DI void operator()(const AccT& acc, const Unit& u, int wr, int wc, int fr, int fq) const {
;         const int cl = u.pn * 128 + wc * 32 + 8 * fq;
;         LAS float* P = (LAS float*)(plds + (wr * 4 + wc) * 1024);
;         { const int lane = fq * 16 + fr, kind = lane >> 3, c4 = 4 * (lane & 7), k3 = kind & 3;
;           const float* src = (k3 == 0 ? cb : cw + (k3 - 1) * 5632) + (kind >= 4 ? 2816 : 0) + u.pn * 128 + wc * 32 + c4;
;           *(LAS f32x4*)(P + kind * 32 + c4) = *(const f32x4*)src; }
; #pragma unroll
;         for (int ai = 0; ai < 2; ++ai) {
;             const int tok0 = u.pm * 248 + 62 * (2 * ai + wr) - 2 + fr;
;             float rs[4];
; #pragma unroll
;             for (int m = 0; m < 4; ++m) { const int t = tok0 + 16 * m; const int tc = t < 0 ? 0 : (t >= S ? S - 1 : t); const float r = rs_from_ss(rowss[tc]); rs[m] = t < 0 ? 0.f : r; }
;             const int row0 = fr < 2 ? (S + 236 + fr) : tok0;
; #pragma unroll
;             for (int n = 0; n < 2; ++n) {
;                 const int lc = 8 * fq + 4 * n;
;                 unsigned wpk[4][2];
; #pragma unroll
;                 for (int jp = 0; jp < 2; ++jp) {
;                     const f32x2 bg = *(const LAS f32x2*)(P + lc + 2 * jp), g0 = *(const LAS f32x2*)(P + 32 + lc + 2 * jp), g1 = *(const LAS f32x2*)(P + 64 + lc + 2 * jp), g2 = *(const LAS f32x2*)(P + 96 + lc + 2 * jp);
;                     const f32x2 bv = *(const LAS f32x2*)(P + 128 + lc + 2 * jp), v0 = *(const LAS f32x2*)(P + 160 + lc + 2 * jp), v1 = *(const LAS f32x2*)(P + 192 + lc + 2 * jp), v2 = *(const LAS f32x2*)(P + 224 + lc + 2 * jp);
;                     f32x2 G[4], V[4];
; #pragma unroll
;                     for (int m = 0; m < 4; ++m) { G[m] = (f32x2){acc[ai][0][m][n][2 * jp], acc[ai][0][m][n][2 * jp + 1]} * rs[m]; V[m] = (f32x2){acc[ai][1][m][n][2 * jp], acc[ai][1][m][n][2 * jp + 1]} * rs[m]; }
; #pragma unroll
;                     for (int m = 0; m < 4; ++m) {
;                         const f32x2 zz = {0.f, 0.f}; const f32x2 Gp = m ? G[m - 1] : zz, Vp = m ? V[m - 1] : zz;
;                         const f32x2 gp1 = {dpp_prev1(G[m].x, Gp.x), dpp_prev1(G[m].y, Gp.y)}, gp2 = {dpp_prev2(G[m].x, Gp.x), dpp_prev2(G[m].y, Gp.y)};
;                         const f32x2 vp1 = {dpp_prev1(V[m].x, Vp.x), dpp_prev1(V[m].y, Vp.y)}, vp2 = {dpp_prev2(V[m].x, Vp.x), dpp_prev2(V[m].y, Vp.y)};
.LBB0_1122:
	s_lshl_b32 s10, s58, 7
	s_ashr_i32 s11, s10, 31
	v_lshl_add_u64 v[128:129], s[10:11], 2, v[168:169]
	s_mul_i32 s11, s57, 0xf8
	v_add_u32_e32 v204, s11, v170
	v_med3_i32 v132, v204, 0, s51
	v_lshlrev_b32_e32 v132, 3, v132
	global_load_dwordx2 v[180:181], v132, s[16:17]
	v_add_u32_e32 v205, 16, v204
	v_med3_i32 v132, v205, 0, s51
	v_add_u32_e32 v206, 32, v204
	v_add_u32_e32 v207, 48, v204
	v_lshlrev_b32_e32 v132, 3, v132
	v_med3_i32 v133, v206, 0, s51
	v_med3_i32 v134, v207, 0, s51
	global_load_dwordx4 v[128:131], v[128:129], off
	v_lshlrev_b32_e32 v133, 3, v133
	v_lshlrev_b32_e32 v134, 3, v134
	global_load_dwordx2 v[182:183], v132, s[16:17]
	global_load_dwordx2 v[210:211], v133, s[16:17]
	global_load_dwordx2 v[212:213], v134, s[16:17]
	v_or_b32_e32 v188, s10, v187
	v_ashrrev_i32_e32 v189, 31, v188
	v_cndmask_b32_e64 v208, v204, v190, s[6:7]
	s_waitcnt vmcnt(0)
	v_add_u32_e32 v250, 0x7c, v204
	v_med3_i32 v250, v250, 0, s51
	v_lshlrev_b32_e32 v250, 3, v250
	global_load_dwordx2 v[242:243], v250, s[16:17]
	v_add_u32_e32 v250, 0x8c, v204
	v_med3_i32 v250, v250, 0, s51
	v_lshlrev_b32_e32 v250, 3, v250
	global_load_dwordx2 v[244:245], v250, s[16:17]
	v_add_u32_e32 v250, 0x9c, v204
	v_med3_i32 v250, v250, 0, s51
	v_lshlrev_b32_e32 v250, 3, v250
	global_load_dwordx2 v[246:247], v250, s[16:17]
	v_add_u32_e32 v250, 0xac, v204
	v_med3_i32 v250, v250, 0, s51
	v_lshlrev_b32_e32 v250, 3, v250
	global_load_dwordx2 v[248:249], v250, s[16:17]
	v_ffbh_u32_e32 v184, v181
	v_min_u32_e32 v184, 32, v184
	v_lshlrev_b64 v[180:181], v184, v[180:181]
	v_min_u32_e32 v180, 1, v180
	v_or_b32_e32 v180, v181, v180
	v_cvt_f32_u32_e32 v180, v180
	v_sub_u32_e32 v184, 32, v184
	ds_write_b128 v191, v[128:131]
	v_ffbh_u32_e32 v186, v183
	v_ffbh_u32_e32 v209, v211
	v_min_u32_e32 v186, 32, v186
	v_ffbh_u32_e32 v214, v213
	v_min_u32_e32 v209, 32, v209
	v_lshlrev_b64 v[182:183], v186, v[182:183]
	v_min_u32_e32 v214, 32, v214
	v_lshlrev_b64 v[210:211], v209, v[210:211]
	v_min_u32_e32 v181, 1, v182
	v_lshlrev_b64 v[212:213], v214, v[212:213]
	v_min_u32_e32 v182, 1, v210
	v_or_b32_e32 v181, v183, v181
	v_min_u32_e32 v210, 1, v212
	v_or_b32_e32 v182, v211, v182
	v_cvt_f32_u32_e32 v181, v181
	v_or_b32_e32 v183, v213, v210
	v_cvt_f32_u32_e32 v182, v182
	v_cvt_f32_u32_e32 v183, v183
	v_sub_u32_e32 v186, 32, v186
	v_ldexp_f32 v180, v180, v184
	v_sub_u32_e32 v209, 32, v209
	v_fmamk_f32 v180, v180, 0x30800000, v203
	v_ldexp_f32 v181, v181, v186
	v_sub_u32_e32 v214, 32, v214
	v_ldexp_f32 v182, v182, v209
	v_mul_f32_e32 v184, 0x4b800000, v180
	v_fmamk_f32 v181, v181, 0x30800000, v203
	v_cmp_gt_f32_e32 vcc, s52, v180
	v_ldexp_f32 v183, v183, v214
	v_fmamk_f32 v182, v182, 0x30800000, v203
	v_cndmask_b32_e32 v180, v180, v184, vcc
	v_mul_f32_e32 v184, 0x4b800000, v181
	v_cmp_gt_f32_e64 s[10:11], s52, v181
	v_fmamk_f32 v183, v183, 0x30800000, v203
	v_mul_f32_e32 v186, 0x4b800000, v182
	v_rsq_f32_e32 v180, v180
	v_cndmask_b32_e64 v181, v181, v184, s[10:11]
	v_cmp_gt_f32_e64 s[12:13], s52, v182
	v_mul_f32_e32 v209, 0x4b800000, v183
	v_cmp_gt_f32_e64 s[14:15], s52, v183
	v_cndmask_b32_e64 v182, v182, v186, s[12:13]
	v_rsq_f32_e32 v181, v181
	v_cndmask_b32_e64 v183, v183, v209, s[14:15]
	v_rsq_f32_e32 v182, v182
	v_rsq_f32_e32 v183, v183
	v_mul_f32_e32 v184, 0x45800000, v180
	v_cndmask_b32_e32 v180, v180, v184, vcc
	v_mul_f32_e32 v184, 0x45800000, v181
	v_cmp_lt_i32_e32 vcc, -1, v204
	v_mul_f32_e32 v209, 0x45800000, v182
	v_mul_f32_e32 v210, 0x45800000, v183
	v_cndmask_b32_e32 v186, 0, v180, vcc
	v_cndmask_b32_e64 v180, v181, v184, s[10:11]
	v_cmp_lt_i32_e32 vcc, s53, v204
	v_cndmask_b32_e64 v181, v182, v209, s[12:13]
	v_cndmask_b32_e64 v183, v183, v210, s[14:15]
	v_cndmask_b32_e32 v184, 0, v180, vcc
	v_cmp_lt_i32_e32 vcc, s54, v204
	v_pk_mul_f32 v[124:125], v[124:125], v[186:187] op_sel_hi:[1,0]
	ds_read_b128 v[136:139], v200
	ds_read_b128 v[148:151], v200 offset:128
	ds_read_b128 v[152:155], v200 offset:256
	ds_read_b128 v[156:159], v200 offset:384
	ds_read_b128 v[128:131], v200 offset:512
	ds_read_b128 v[132:135], v200 offset:640
	ds_read_b128 v[140:143], v200 offset:768
	ds_read_b128 v[144:147], v200 offset:896
	v_cndmask_b32_e32 v182, 0, v181, vcc
	v_cmp_lt_i32_e32 vcc, s55, v204
	v_pk_mul_f32 v[108:109], v[108:109], v[182:183] op_sel_hi:[1,0]
	v_pk_mul_f32 v[210:211], v[104:105], v[182:183] op_sel_hi:[1,0]
	v_cndmask_b32_e32 v180, 0, v183, vcc
	v_mov_b32_e32 v183, 0
	v_pk_mul_f32 v[212:213], v[100:101], v[180:181] op_sel_hi:[1,0]
	v_pk_mul_f32 v[214:215], v[96:97], v[180:181] op_sel_hi:[1,0]
	v_mov_b32_e32 v181, 0
	v_mov_b32_dpp v183, v183 row_ror:2 row_mask:0xf bank_mask:0xf
	v_mov_b32_e32 v100, v183
	v_mov_b32_dpp v181, v181 row_ror:1 row_mask:0xf bank_mask:0xf
	v_mov_b32_e32 v101, v183
	v_mov_b32_e32 v96, v181
	v_mov_b32_e32 v97, v181
	v_mov_b32_dpp v100, v124 row_shr:2 row_mask:0xf bank_mask:0xf
	v_mov_b32_dpp v101, v125 row_shr:2 row_mask:0xf bank_mask:0xf
	v_mov_b32_dpp v96, v124 row_shr:1 row_mask:0xf bank_mask:0xf
	v_mov_b32_dpp v97, v125 row_shr:1 row_mask:0xf bank_mask:0xf
	s_waitcnt lgkmcnt(6)
	v_pk_fma_f32 v[100:101], v[148:149], v[100:101], v[136:137]
	v_pk_mul_f32 v[120:121], v[120:121], v[186:187] op_sel_hi:[1,0]
	s_waitcnt lgkmcnt(5)
	v_pk_fma_f32 v[96:97], v[152:153], v[96:97], v[100:101]
	v_mov_b32_e32 v216, v183
	s_waitcnt lgkmcnt(4)
	v_pk_fma_f32 v[96:97], v[156:157], v[124:125], v[96:97]
	v_mov_b32_e32 v217, v183
	v_pk_mul_f32 v[100:101], v[96:97], s[0:1] op_sel_hi:[1,0]
	v_mov_b32_e32 v104, v181
	v_exp_f32_e32 v100, v100
	v_exp_f32_e32 v101, v101
	v_mov_b32_e32 v105, v181
	v_mov_b32_dpp v216, v120 row_shr:2 row_mask:0xf bank_mask:0xf
	v_mov_b32_dpp v217, v121 row_shr:2 row_mask:0xf bank_mask:0xf
	v_pk_add_f32 v[100:101], v[100:101], 1.0 op_sel_hi:[1,0]
	v_mov_b32_dpp v104, v120 row_shr:1 row_mask:0xf bank_mask:0xf
	v_rcp_f32_e32 v100, v100
	v_rcp_f32_e32 v101, v101
	v_mov_b32_dpp v105, v121 row_shr:1 row_mask:0xf bank_mask:0xf
	s_waitcnt lgkmcnt(2)
;     DI void operator()(const AccT& acc, const Unit& u, int wr, int wc, int fr, int fq) const {
;     ...
;                     for (int m = 0; m < 4; ++m) { G[m] = (f32x2){acc[ai][0][m][n][2 * jp], acc[ai][0][m][n][2 * jp + 1]} * rs[m]; V[m] = (f32x2){acc[ai][1][m][n][2 * jp], acc[ai][1][m][n][2 * jp + 1]} * rs[m]; }
; #pragma unroll
;                     for (int m = 0; m < 4; ++m) {
;                         const f32x2 zz = {0.f, 0.f}; const f32x2 Gp = m ? G[m - 1] : zz, Vp = m ? V[m - 1] : zz;
;                         const f32x2 gp1 = {dpp_prev1(G[m].x, Gp.x), dpp_prev1(G[m].y, Gp.y)}, gp2 = {dpp_prev2(G[m].x, Gp.x), dpp_prev2(G[m].y, Gp.y)};
;                         const f32x2 vp1 = {dpp_prev1(V[m].x, Vp.x), dpp_prev1(V[m].y, Vp.y)}, vp2 = {dpp_prev2(V[m].x, Vp.x), dpp_prev2(V[m].y, Vp.y)};
;                         const f32x2 gc = bg + g0 * gp2 + g1 * gp1 + g2 * G[m];
;                         const f32x2 vc = bv + v0 * vp2 + v1 * vp1 + v2 * V[m];
;                         const f32x2 xe = gc * (-LOG2E);
;                         f32x2 dn = {__builtin_amdgcn_exp2f(xe.x), __builtin_amdgcn_exp2f(xe.y)}; dn = dn + 1.0f;
;                         const f32x2 rc = {__builtin_amdgcn_rcpf(dn.x), __builtin_amdgcn_rcpf(dn.y)};
;                         const f32x2 rr = gc * rc * vc;
	v_pk_fma_f32 v[216:217], v[132:133], v[216:217], v[128:129]
	v_pk_mul_f32 v[116:117], v[116:117], v[184:185] op_sel_hi:[1,0]
	s_waitcnt lgkmcnt(1)
	v_pk_fma_f32 v[104:105], v[140:141], v[104:105], v[216:217]
	v_pk_mul_f32 v[96:97], v[96:97], v[100:101]
	s_waitcnt lgkmcnt(0)
	v_pk_fma_f32 v[104:105], v[144:145], v[120:121], v[104:105]
	v_pk_mul_f32 v[96:97], v[104:105], v[96:97]
	v_mov_b32_dpp v104, v124 row_ror:2 row_mask:0xf bank_mask:0xf
	v_mov_b32_dpp v105, v125 row_ror:2 row_mask:0xf bank_mask:0xf
	v_mov_b32_dpp v100, v124 row_ror:1 row_mask:0xf bank_mask:0xf
	v_mov_b32_dpp v101, v125 row_ror:1 row_mask:0xf bank_mask:0xf
	v_mov_b32_dpp v104, v116 row_shr:2 row_mask:0xf bank_mask:0xf
	v_mov_b32_dpp v105, v117 row_shr:2 row_mask:0xf bank_mask:0xf
	v_mov_b32_dpp v100, v116 row_shr:1 row_mask:0xf bank_mask:0xf
	v_mov_b32_dpp v101, v117 row_shr:1 row_mask:0xf bank_mask:0xf
	v_pk_fma_f32 v[104:105], v[148:149], v[104:105], v[136:137]
	v_pk_fma_f32 v[100:101], v[152:153], v[100:101], v[104:105]
	v_pk_fma_f32 v[100:101], v[156:157], v[116:117], v[100:101]
	v_pk_mul_f32 v[112:113], v[112:113], v[184:185] op_sel_hi:[1,0]
	v_pk_mul_f32 v[104:105], v[100:101], s[0:1] op_sel_hi:[1,0]
	v_exp_f32_e32 v104, v104
	v_exp_f32_e32 v105, v105
	v_mov_b32_dpp v216, v120 row_ror:2 row_mask:0xf bank_mask:0xf
	v_mov_b32_dpp v217, v121 row_ror:2 row_mask:0xf bank_mask:0xf
	v_pk_add_f32 v[104:105], v[104:105], 1.0 op_sel_hi:[1,0]
	v_mov_b32_dpp v124, v120 row_ror:1 row_mask:0xf bank_mask:0xf
	v_rcp_f32_e32 v104, v104
	v_rcp_f32_e32 v105, v105
	v_mov_b32_dpp v125, v121 row_ror:1 row_mask:0xf bank_mask:0xf
	v_mov_b32_dpp v216, v112 row_shr:2 row_mask:0xf bank_mask:0xf
	v_mov_b32_dpp v217, v113 row_shr:2 row_mask:0xf bank_mask:0xf
	v_mov_b32_dpp v124, v112 row_shr:1 row_mask:0xf bank_mask:0xf
	v_mov_b32_dpp v125, v113 row_shr:1 row_mask:0xf bank_mask:0xf
	v_pk_fma_f32 v[120:121], v[132:133], v[216:217], v[128:129]
	v_pk_mul_f32 v[100:101], v[100:101], v[104:105]
	v_pk_fma_f32 v[120:121], v[140:141], v[124:125], v[120:121]
	v_pk_fma_f32 v[120:121], v[144:145], v[112:113], v[120:121]
	v_pk_mul_f32 v[100:101], v[120:121], v[100:101]
	v_mov_b32_dpp v104, v116 row_ror:1 row_mask:0xf bank_mask:0xf
	v_mov_b32_dpp v120, v116 row_ror:2 row_mask:0xf bank_mask:0xf
	v_mov_b32_dpp v121, v117 row_ror:2 row_mask:0xf bank_mask:0xf
	v_mov_b32_dpp v105, v117 row_ror:1 row_mask:0xf bank_mask:0xf
	v_mov_b32_dpp v120, v108 row_shr:2 row_mask:0xf bank_mask:0xf
	v_mov_b32_dpp v121, v109 row_shr:2 row_mask:0xf bank_mask:0xf
	v_mov_b32_dpp v104, v108 row_shr:1 row_mask:0xf bank_mask:0xf
	v_mov_b32_dpp v105, v109 row_shr:1 row_mask:0xf bank_mask:0xf
	v_pk_fma_f32 v[120:121], v[148:149], v[120:121], v[136:137]
	v_pk_fma_f32 v[104:105], v[152:153], v[104:105], v[120:121]
	v_pk_fma_f32 v[104:105], v[156:157], v[108:109], v[104:105]
	v_pk_mul_f32 v[120:121], v[104:105], s[0:1] op_sel_hi:[1,0]
	v_exp_f32_e32 v120, v120
	v_exp_f32_e32 v121, v121
	v_mov_b32_dpp v116, v112 row_ror:1 row_mask:0xf bank_mask:0xf
	v_mov_b32_dpp v117, v113 row_ror:1 row_mask:0xf bank_mask:0xf
	v_mov_b32_dpp v124, v112 row_ror:2 row_mask:0xf bank_mask:0xf
	v_mov_b32_dpp v125, v113 row_ror:2 row_mask:0xf bank_mask:0xf
	v_pk_add_f32 v[112:113], v[120:121], 1.0 op_sel_hi:[1,0]
	v_mov_b32_dpp v124, v210 row_shr:2 row_mask:0xf bank_mask:0xf
	v_rcp_f32_e32 v112, v112
	v_rcp_f32_e32 v113, v113
	v_mov_b32_dpp v125, v211 row_shr:2 row_mask:0xf bank_mask:0xf
	v_mov_b32_dpp v116, v210 row_shr:1 row_mask:0xf bank_mask:0xf
	v_mov_b32_dpp v117, v211 row_shr:1 row_mask:0xf bank_mask:0xf
	v_pk_fma_f32 v[120:121], v[132:133], v[124:125], v[128:129]
	v_pk_mul_f32 v[104:105], v[104:105], v[112:113]
	v_pk_fma_f32 v[116:117], v[140:141], v[116:117], v[120:121]
	v_pk_fma_f32 v[116:117], v[144:145], v[210:211], v[116:117]
	v_pk_mul_f32 v[104:105], v[116:117], v[104:105]
	v_mov_b32_dpp v112, v108 row_ror:1 row_mask:0xf bank_mask:0xf
	v_mov_b32_dpp v116, v108 row_ror:2 row_mask:0xf bank_mask:0xf
	v_mov_b32_dpp v117, v109 row_ror:2 row_mask:0xf bank_mask:0xf
	v_mov_b32_dpp v113, v109 row_ror:1 row_mask:0xf bank_mask:0xf
	v_mov_b32_dpp v116, v212 row_shr:2 row_mask:0xf bank_mask:0xf
	v_mov_b32_dpp v117, v213 row_shr:2 row_mask:0xf bank_mask:0xf
	v_mov_b32_dpp v112, v212 row_shr:1 row_mask:0xf bank_mask:0xf
	v_mov_b32_dpp v113, v213 row_shr:1 row_mask:0xf bank_mask:0xf
	v_pk_fma_f32 v[116:117], v[148:149], v[116:117], v[136:137]
	v_pk_fma_f32 v[112:113], v[152:153], v[112:113], v[116:117]
	v_pk_fma_f32 v[112:113], v[156:157], v[212:213], v[112:113]
	v_pk_mul_f32 v[116:117], v[112:113], s[0:1] op_sel_hi:[1,0]
	v_exp_f32_e32 v116, v116
	v_exp_f32_e32 v117, v117
	v_mov_b32_dpp v120, v210 row_ror:2 row_mask:0xf bank_mask:0xf
	v_mov_b32_dpp v121, v211 row_ror:2 row_mask:0xf bank_mask:0xf
	v_mov_b32_dpp v108, v210 row_ror:1 row_mask:0xf bank_mask:0xf
	v_pk_add_f32 v[116:117], v[116:117], 1.0 op_sel_hi:[1,0]
	v_mov_b32_dpp v109, v211 row_ror:1 row_mask:0xf bank_mask:0xf
	v_rcp_f32_e32 v116, v116
	v_rcp_f32_e32 v117, v117
	v_mov_b32_dpp v120, v214 row_shr:2 row_mask:0xf bank_mask:0xf
	v_mov_b32_dpp v121, v215 row_shr:2 row_mask:0xf bank_mask:0xf
	v_mov_b32_dpp v108, v214 row_shr:1 row_mask:0xf bank_mask:0xf
	v_mov_b32_dpp v109, v215 row_shr:1 row_mask:0xf bank_mask:0xf
	v_pk_fma_f32 v[120:121], v[132:133], v[120:121], v[128:129]
	v_pk_mul_f32 v[112:113], v[112:113], v[116:117]
	v_pk_fma_f32 v[108:109], v[140:141], v[108:109], v[120:121]
	v_pk_mul_f32 v[116:117], v[122:123], v[186:187] op_sel_hi:[1,0]
	v_pk_fma_f32 v[108:109], v[144:145], v[214:215], v[108:109]
	v_mov_b32_e32 v122, v183
	v_pk_mul_f32 v[108:109], v[108:109], v[112:113]
; DI unsigned pk2(float lo, float hi) { f32x2 v = {lo, hi}; bf16x2_t b = __builtin_convertvector(v, bf16x2_t); return __builtin_bit_cast(unsigned, b); }
;     DI void operator()(const AccT& acc, const Unit& u, int wr, int wc, int fr, int fq) const {
;     ...
;                     for (int m = 0; m < 4; ++m) { G[m] = (f32x2){acc[ai][0][m][n][2 * jp], acc[ai][0][m][n][2 * jp + 1]} * rs[m]; V[m] = (f32x2){acc[ai][1][m][n][2 * jp], acc[ai][1][m][n][2 * jp + 1]} * rs[m]; }
; #pragma unroll
;                     for (int m = 0; m < 4; ++m) {
;                         const f32x2 zz = {0.f, 0.f}; const f32x2 Gp = m ? G[m - 1] : zz, Vp = m ? V[m - 1] : zz;
;                         const f32x2 gp1 = {dpp_prev1(G[m].x, Gp.x), dpp_prev1(G[m].y, Gp.y)}, gp2 = {dpp_prev2(G[m].x, Gp.x), dpp_prev2(G[m].y, Gp.y)};
;                         const f32x2 vp1 = {dpp_prev1(V[m].x, Vp.x), dpp_prev1(V[m].y, Vp.y)}, vp2 = {dpp_prev2(V[m].x, Vp.x), dpp_prev2(V[m].y, Vp.y)};
;                         const f32x2 gc = bg + g0 * gp2 + g1 * gp1 + g2 * G[m];
;                         const f32x2 vc = bv + v0 * vp2 + v1 * vp1 + v2 * V[m];
;                         const f32x2 xe = gc * (-LOG2E);
;                         f32x2 dn = {__builtin_amdgcn_exp2f(xe.x), __builtin_amdgcn_exp2f(xe.y)}; dn = dn + 1.0f;
;                         const f32x2 rc = {__builtin_amdgcn_rcpf(dn.x), __builtin_amdgcn_rcpf(dn.y)};
;                         const f32x2 rr = gc * rc * vc;
;                         wpk[m][jp] = pk2(rr.x, rr.y); }
	v_pk_mul_f32 v[112:113], v[126:127], v[186:187] op_sel_hi:[1,0]
	v_mov_b32_e32 v123, v183
	v_mov_b32_e32 v120, v181
	v_mov_b32_e32 v121, v181
	v_mov_b32_dpp v122, v112 row_shr:2 row_mask:0xf bank_mask:0xf
	v_mov_b32_dpp v123, v113 row_shr:2 row_mask:0xf bank_mask:0xf
	v_mov_b32_dpp v120, v112 row_shr:1 row_mask:0xf bank_mask:0xf
	v_mov_b32_dpp v121, v113 row_shr:1 row_mask:0xf bank_mask:0xf
	v_pk_fma_f32 v[122:123], v[150:151], v[122:123], v[138:139]
	v_mov_b32_e32 v126, v183
	v_pk_fma_f32 v[120:121], v[154:155], v[120:121], v[122:123]
	v_mov_b32_e32 v127, v183
	v_pk_fma_f32 v[120:121], v[112:113], v[158:159], v[120:121]
	v_mov_b32_e32 v124, v181
	v_pk_mul_f32 v[122:123], v[120:121], s[0:1] op_sel_hi:[1,0]
	v_mov_b32_e32 v125, v181
	v_exp_f32_e32 v122, v122
	v_exp_f32_e32 v123, v123
	v_mov_b32_dpp v126, v116 row_shr:2 row_mask:0xf bank_mask:0xf
	v_mov_b32_dpp v127, v117 row_shr:2 row_mask:0xf bank_mask:0xf
	v_mov_b32_dpp v124, v116 row_shr:1 row_mask:0xf bank_mask:0xf
	v_pk_add_f32 v[122:123], v[122:123], 1.0 op_sel_hi:[1,0]
	v_mov_b32_dpp v125, v117 row_shr:1 row_mask:0xf bank_mask:0xf
	v_rcp_f32_e32 v122, v122
	v_rcp_f32_e32 v123, v123
	v_pk_fma_f32 v[126:127], v[134:135], v[126:127], v[130:131]
	v_cvt_pk_bf16_f32 v228, v96, v97
	v_pk_fma_f32 v[124:125], v[142:143], v[124:125], v[126:127]
	v_pk_mul_f32 v[120:121], v[120:121], v[122:123]
	v_pk_fma_f32 v[124:125], v[116:117], v[146:147], v[124:125]
	v_pk_mul_f32 v[120:121], v[124:125], v[120:121]
	v_pk_mul_f32 v[118:119], v[118:119], v[184:185] op_sel_hi:[1,0]
	v_cvt_pk_bf16_f32 v229, v120, v121
	v_mov_b32_dpp v122, v112 row_ror:2 row_mask:0xf bank_mask:0xf
	v_mov_b32_dpp v123, v113 row_ror:2 row_mask:0xf bank_mask:0xf
	v_mov_b32_dpp v120, v112 row_ror:1 row_mask:0xf bank_mask:0xf
	v_mov_b32_dpp v121, v113 row_ror:1 row_mask:0xf bank_mask:0xf
	v_mov_b32_dpp v122, v118 row_shr:2 row_mask:0xf bank_mask:0xf
	v_mov_b32_dpp v123, v119 row_shr:2 row_mask:0xf bank_mask:0xf
	v_mov_b32_dpp v120, v118 row_shr:1 row_mask:0xf bank_mask:0xf
	v_mov_b32_dpp v121, v119 row_shr:1 row_mask:0xf bank_mask:0xf
	v_pk_fma_f32 v[122:123], v[150:151], v[122:123], v[138:139]
	v_pk_fma_f32 v[120:121], v[154:155], v[120:121], v[122:123]
	v_pk_fma_f32 v[120:121], v[118:119], v[158:159], v[120:121]
	v_pk_mul_f32 v[122:123], v[120:121], s[0:1] op_sel_hi:[1,0]
	v_exp_f32_e32 v122, v122
	v_exp_f32_e32 v123, v123
	v_mov_b32_dpp v112, v116 row_ror:1 row_mask:0xf bank_mask:0xf
	v_mov_b32_dpp v113, v117 row_ror:1 row_mask:0xf bank_mask:0xf
	v_mov_b32_dpp v124, v116 row_ror:2 row_mask:0xf bank_mask:0xf
	v_mov_b32_dpp v125, v117 row_ror:2 row_mask:0xf bank_mask:0xf
	v_pk_add_f32 v[116:117], v[122:123], 1.0 op_sel_hi:[1,0]
	v_pk_mul_f32 v[114:115], v[114:115], v[184:185] op_sel_hi:[1,0]
	v_rcp_f32_e32 v116, v116
	v_rcp_f32_e32 v117, v117
	v_mov_b32_dpp v124, v114 row_shr:2 row_mask:0xf bank_mask:0xf
	v_mov_b32_dpp v125, v115 row_shr:2 row_mask:0xf bank_mask:0xf
	v_mov_b32_dpp v112, v114 row_shr:1 row_mask:0xf bank_mask:0xf
	v_mov_b32_dpp v113, v115 row_shr:1 row_mask:0xf bank_mask:0xf
	v_pk_fma_f32 v[122:123], v[134:135], v[124:125], v[130:131]
	v_pk_mul_f32 v[116:117], v[120:121], v[116:117]
	v_pk_fma_f32 v[112:113], v[142:143], v[112:113], v[122:123]
	v_cvt_pk_bf16_f32 v232, v100, v101
	v_pk_fma_f32 v[112:113], v[114:115], v[146:147], v[112:113]
	v_pk_mul_f32 v[110:111], v[110:111], v[182:183] op_sel_hi:[1,0]
	v_pk_mul_f32 v[112:113], v[112:113], v[116:117]
	v_cvt_pk_bf16_f32 v233, v112, v113
	v_mov_b32_dpp v116, v118 row_ror:2 row_mask:0xf bank_mask:0xf
	v_mov_b32_dpp v117, v119 row_ror:2 row_mask:0xf bank_mask:0xf
	v_mov_b32_dpp v112, v118 row_ror:1 row_mask:0xf bank_mask:0xf
	v_mov_b32_dpp v113, v119 row_ror:1 row_mask:0xf bank_mask:0xf
	v_mov_b32_dpp v116, v110 row_shr:2 row_mask:0xf bank_mask:0xf
	v_mov_b32_dpp v117, v111 row_shr:2 row_mask:0xf bank_mask:0xf
	v_mov_b32_dpp v112, v110 row_shr:1 row_mask:0xf bank_mask:0xf
	v_mov_b32_dpp v113, v111 row_shr:1 row_mask:0xf bank_mask:0xf
	v_pk_fma_f32 v[116:117], v[150:151], v[116:117], v[138:139]
	v_pk_fma_f32 v[112:113], v[154:155], v[112:113], v[116:117]
	v_pk_fma_f32 v[112:113], v[110:111], v[158:159], v[112:113]
	v_pk_mul_f32 v[116:117], v[112:113], s[0:1] op_sel_hi:[1,0]
	v_exp_f32_e32 v116, v116
	v_exp_f32_e32 v117, v117
	v_mov_b32_dpp v118, v114 row_ror:1 row_mask:0xf bank_mask:0xf
	v_mov_b32_dpp v119, v115 row_ror:1 row_mask:0xf bank_mask:0xf
	v_mov_b32_dpp v120, v114 row_ror:2 row_mask:0xf bank_mask:0xf
	v_mov_b32_dpp v121, v115 row_ror:2 row_mask:0xf bank_mask:0xf
	v_pk_add_f32 v[114:115], v[116:117], 1.0 op_sel_hi:[1,0]
	v_pk_mul_f32 v[106:107], v[106:107], v[182:183] op_sel_hi:[1,0]
	v_rcp_f32_e32 v114, v114
	v_rcp_f32_e32 v115, v115
	v_mov_b32_dpp v120, v106 row_shr:2 row_mask:0xf bank_mask:0xf
	v_mov_b32_dpp v121, v107 row_shr:2 row_mask:0xf bank_mask:0xf
	v_mov_b32_dpp v118, v106 row_shr:1 row_mask:0xf bank_mask:0xf
	v_mov_b32_dpp v119, v107 row_shr:1 row_mask:0xf bank_mask:0xf
	v_pk_fma_f32 v[116:117], v[134:135], v[120:121], v[130:131]
	v_pk_mul_f32 v[112:113], v[112:113], v[114:115]
	v_pk_fma_f32 v[116:117], v[142:143], v[118:119], v[116:117]
	v_pk_fma_f32 v[116:117], v[106:107], v[146:147], v[116:117]
	v_pk_mul_f32 v[112:113], v[116:117], v[112:113]
	v_cvt_pk_bf16_f32 v236, v104, v105
	v_pk_mul_f32 v[102:103], v[102:103], v[180:181] op_sel_hi:[1,0]
	v_cvt_pk_bf16_f32 v237, v112, v113
	v_mov_b32_dpp v114, v110 row_ror:2 row_mask:0xf bank_mask:0xf
	v_mov_b32_dpp v115, v111 row_ror:2 row_mask:0xf bank_mask:0xf
	v_mov_b32_dpp v112, v110 row_ror:1 row_mask:0xf bank_mask:0xf
	v_mov_b32_dpp v113, v111 row_ror:1 row_mask:0xf bank_mask:0xf
; DI unsigned pk2(float lo, float hi) { f32x2 v = {lo, hi}; bf16x2_t b = __builtin_convertvector(v, bf16x2_t); return __builtin_bit_cast(unsigned, b); }
;     DI void operator()(const AccT& acc, const Unit& u, int wr, int wc, int fr, int fq) const {
;     ...
;                     for (int m = 0; m < 4; ++m) {
;                         const f32x2 zz = {0.f, 0.f}; const f32x2 Gp = m ? G[m - 1] : zz, Vp = m ? V[m - 1] : zz;
;                         const f32x2 gp1 = {dpp_prev1(G[m].x, Gp.x), dpp_prev1(G[m].y, Gp.y)}, gp2 = {dpp_prev2(G[m].x, Gp.x), dpp_prev2(G[m].y, Gp.y)};
;                         const f32x2 vp1 = {dpp_prev1(V[m].x, Vp.x), dpp_prev1(V[m].y, Vp.y)}, vp2 = {dpp_prev2(V[m].x, Vp.x), dpp_prev2(V[m].y, Vp.y)};
;                         const f32x2 gc = bg + g0 * gp2 + g1 * gp1 + g2 * G[m];
;                         const f32x2 vc = bv + v0 * vp2 + v1 * vp1 + v2 * V[m];
;                         const f32x2 xe = gc * (-LOG2E);
;                         f32x2 dn = {__builtin_amdgcn_exp2f(xe.x), __builtin_amdgcn_exp2f(xe.y)}; dn = dn + 1.0f;
;                         const f32x2 rc = {__builtin_amdgcn_rcpf(dn.x), __builtin_amdgcn_rcpf(dn.y)};
;                         const f32x2 rr = gc * rc * vc;
;                         wpk[m][jp] = pk2(rr.x, rr.y); }
;                 }
; #pragma unroll
;                 for (int m = 0; m < 4; ++m) { const int row = m ? tok0 + 16 * m : row0;
;                     *(u32x2*)(ACT + (size_t)row * 2816 + cl + 4 * n) = (u32x2){wpk[m][0], wpk[m][1]}; }
	v_mov_b32_dpp v114, v102 row_shr:2 row_mask:0xf bank_mask:0xf
	v_mov_b32_dpp v115, v103 row_shr:2 row_mask:0xf bank_mask:0xf
	v_mov_b32_dpp v112, v102 row_shr:1 row_mask:0xf bank_mask:0xf
	v_mov_b32_dpp v113, v103 row_shr:1 row_mask:0xf bank_mask:0xf
	v_pk_fma_f32 v[114:115], v[150:151], v[114:115], v[138:139]
	v_pk_fma_f32 v[112:113], v[154:155], v[112:113], v[114:115]
	v_pk_fma_f32 v[102:103], v[102:103], v[158:159], v[112:113]
	v_pk_mul_f32 v[112:113], v[102:103], s[0:1] op_sel_hi:[1,0]
	v_exp_f32_e32 v112, v112
	v_exp_f32_e32 v113, v113
	v_mov_b32_dpp v110, v106 row_ror:1 row_mask:0xf bank_mask:0xf
	v_mov_b32_dpp v111, v107 row_ror:1 row_mask:0xf bank_mask:0xf
	v_mov_b32_dpp v116, v106 row_ror:2 row_mask:0xf bank_mask:0xf
	v_mov_b32_dpp v117, v107 row_ror:2 row_mask:0xf bank_mask:0xf
	v_pk_add_f32 v[106:107], v[112:113], 1.0 op_sel_hi:[1,0]
	v_pk_mul_f32 v[98:99], v[98:99], v[180:181] op_sel_hi:[1,0]
	v_rcp_f32_e32 v106, v106
	v_rcp_f32_e32 v107, v107
	v_mov_b32_dpp v116, v98 row_shr:2 row_mask:0xf bank_mask:0xf
	v_mov_b32_dpp v117, v99 row_shr:2 row_mask:0xf bank_mask:0xf
	v_mov_b32_dpp v110, v98 row_shr:1 row_mask:0xf bank_mask:0xf
	v_mov_b32_dpp v111, v99 row_shr:1 row_mask:0xf bank_mask:0xf
	v_pk_fma_f32 v[112:113], v[134:135], v[116:117], v[130:131]
	v_pk_mul_f32 v[102:103], v[102:103], v[106:107]
	v_pk_fma_f32 v[110:111], v[142:143], v[110:111], v[112:113]
	v_mov_b64_e32 v[128:129], s[4:5]
	v_pk_fma_f32 v[98:99], v[98:99], v[146:147], v[110:111]
	v_cvt_pk_bf16_f32 v252, v108, v109
	v_pk_mul_f32 v[98:99], v[98:99], v[102:103]
	v_lshlrev_b64 v[130:131], 1, v[188:189]
	v_cvt_pk_bf16_f32 v253, v98, v99
	v_mad_i64_i32 v[98:99], s[10:11], v208, s48, v[128:129]
	v_lshl_add_u64 v[132:133], v[98:99], 0, v[130:131]
	v_mad_i64_i32 v[96:97], s[10:11], v205, s48, v[128:129]
	v_lshl_add_u64 v[134:135], v[96:97], 0, v[130:131]
	v_mad_i64_i32 v[96:97], s[10:11], v206, s48, v[128:129]
	v_lshl_add_u64 v[136:137], v[96:97], 0, v[130:131]
	v_mad_i64_i32 v[96:97], s[10:11], v207, s48, v[128:129]
	v_lshl_add_u64 v[138:139], v[96:97], 0, v[130:131]
	v_pk_mul_f32 v[92:93], v[92:93], v[186:187] op_sel_hi:[1,0]
	v_pk_mul_f32 v[142:143], v[68:69], v[180:181] op_sel_hi:[1,0]
	v_mov_b32_e32 v68, v183
	v_mov_b32_e32 v69, v183
	v_pk_mul_f32 v[144:145], v[64:65], v[180:181] op_sel_hi:[1,0]
	v_mov_b32_e32 v64, v181
	v_mov_b32_e32 v65, v181
	v_mov_b32_dpp v68, v92 row_shr:2 row_mask:0xf bank_mask:0xf
	v_mov_b32_dpp v69, v93 row_shr:2 row_mask:0xf bank_mask:0xf
	ds_read_b128 v[104:107], v200 offset:16
	ds_read_b128 v[116:119], v200 offset:144
	ds_read_b128 v[120:123], v200 offset:272
	ds_read_b128 v[124:127], v200 offset:400
	ds_read_b128 v[96:99], v200 offset:528
	ds_read_b128 v[100:103], v200 offset:656
	ds_read_b128 v[108:111], v200 offset:784
	ds_read_b128 v[112:115], v200 offset:912
	v_mov_b32_dpp v64, v92 row_shr:1 row_mask:0xf bank_mask:0xf
	v_mov_b32_dpp v65, v93 row_shr:1 row_mask:0xf bank_mask:0xf
	s_waitcnt lgkmcnt(6)
	v_pk_fma_f32 v[68:69], v[116:117], v[68:69], v[104:105]
	v_pk_mul_f32 v[88:89], v[88:89], v[186:187] op_sel_hi:[1,0]
	s_waitcnt lgkmcnt(5)
	v_pk_fma_f32 v[64:65], v[120:121], v[64:65], v[68:69]
	v_mov_b32_e32 v146, v183
	s_waitcnt lgkmcnt(4)
	v_pk_fma_f32 v[64:65], v[92:93], v[124:125], v[64:65]
	v_mov_b32_e32 v147, v183
	v_pk_mul_f32 v[68:69], v[64:65], s[0:1] op_sel_hi:[1,0]
	v_pk_mul_f32 v[140:141], v[72:73], v[182:183] op_sel_hi:[1,0]
	v_exp_f32_e32 v68, v68
	v_exp_f32_e32 v69, v69
	v_mov_b32_e32 v72, v181
	v_mov_b32_e32 v73, v181
	v_mov_b32_dpp v146, v88 row_shr:2 row_mask:0xf bank_mask:0xf
	v_pk_add_f32 v[68:69], v[68:69], 1.0 op_sel_hi:[1,0]
	v_mov_b32_dpp v147, v89 row_shr:2 row_mask:0xf bank_mask:0xf
	v_rcp_f32_e32 v68, v68
	v_rcp_f32_e32 v69, v69
	v_mov_b32_dpp v72, v88 row_shr:1 row_mask:0xf bank_mask:0xf
	v_mov_b32_dpp v73, v89 row_shr:1 row_mask:0xf bank_mask:0xf
	s_waitcnt lgkmcnt(2)
	v_pk_fma_f32 v[146:147], v[100:101], v[146:147], v[96:97]
	v_pk_mul_f32 v[64:65], v[64:65], v[68:69]
	s_waitcnt lgkmcnt(1)
	v_pk_fma_f32 v[72:73], v[108:109], v[72:73], v[146:147]
	v_pk_mul_f32 v[84:85], v[84:85], v[184:185] op_sel_hi:[1,0]
	s_waitcnt lgkmcnt(0)
	v_pk_fma_f32 v[72:73], v[88:89], v[112:113], v[72:73]
	v_pk_mul_f32 v[64:65], v[72:73], v[64:65]
	v_mov_b32_dpp v72, v92 row_ror:2 row_mask:0xf bank_mask:0xf
	v_mov_b32_dpp v73, v93 row_ror:2 row_mask:0xf bank_mask:0xf
	v_mov_b32_dpp v68, v92 row_ror:1 row_mask:0xf bank_mask:0xf
	v_mov_b32_dpp v69, v93 row_ror:1 row_mask:0xf bank_mask:0xf
	v_mov_b32_dpp v72, v84 row_shr:2 row_mask:0xf bank_mask:0xf
	v_mov_b32_dpp v73, v85 row_shr:2 row_mask:0xf bank_mask:0xf
	v_mov_b32_dpp v68, v84 row_shr:1 row_mask:0xf bank_mask:0xf
	v_mov_b32_dpp v69, v85 row_shr:1 row_mask:0xf bank_mask:0xf
	v_pk_fma_f32 v[72:73], v[116:117], v[72:73], v[104:105]
	v_pk_fma_f32 v[68:69], v[120:121], v[68:69], v[72:73]
	v_pk_fma_f32 v[68:69], v[84:85], v[124:125], v[68:69]
	v_pk_mul_f32 v[80:81], v[80:81], v[184:185] op_sel_hi:[1,0]
	v_pk_mul_f32 v[72:73], v[68:69], s[0:1] op_sel_hi:[1,0]
	v_exp_f32_e32 v72, v72
	v_exp_f32_e32 v73, v73
	v_mov_b32_dpp v146, v88 row_ror:2 row_mask:0xf bank_mask:0xf
	v_mov_b32_dpp v147, v89 row_ror:2 row_mask:0xf bank_mask:0xf
	v_pk_add_f32 v[72:73], v[72:73], 1.0 op_sel_hi:[1,0]
	v_mov_b32_dpp v92, v88 row_ror:1 row_mask:0xf bank_mask:0xf
	v_rcp_f32_e32 v72, v72
	v_rcp_f32_e32 v73, v73
	v_mov_b32_dpp v93, v89 row_ror:1 row_mask:0xf bank_mask:0xf
	v_mov_b32_dpp v146, v80 row_shr:2 row_mask:0xf bank_mask:0xf
	v_mov_b32_dpp v147, v81 row_shr:2 row_mask:0xf bank_mask:0xf
	v_mov_b32_dpp v92, v80 row_shr:1 row_mask:0xf bank_mask:0xf
	v_mov_b32_dpp v93, v81 row_shr:1 row_mask:0xf bank_mask:0xf
; #define LAS __attribute__((address_space(3)))
; DI unsigned pk2(float lo, float hi) { f32x2 v = {lo, hi}; bf16x2_t b = __builtin_convertvector(v, bf16x2_t); return __builtin_bit_cast(unsigned, b); }
;     DI void operator()(const AccT& acc, const Unit& u, int wr, int wc, int fr, int fq) const {
;     ...
;                     const f32x2 bg = *(const LAS f32x2*)(P + lc + 2 * jp), g0 = *(const LAS f32x2*)(P + 32 + lc + 2 * jp), g1 = *(const LAS f32x2*)(P + 64 + lc + 2 * jp), g2 = *(const LAS f32x2*)(P + 96 + lc + 2 * jp);
;                     const f32x2 bv = *(const LAS f32x2*)(P + 128 + lc + 2 * jp), v0 = *(const LAS f32x2*)(P + 160 + lc + 2 * jp), v1 = *(const LAS f32x2*)(P + 192 + lc + 2 * jp), v2 = *(const LAS f32x2*)(P + 224 + lc + 2 * jp);
;                     f32x2 G[4], V[4];
; #pragma unroll
;                     for (int m = 0; m < 4; ++m) { G[m] = (f32x2){acc[ai][0][m][n][2 * jp], acc[ai][0][m][n][2 * jp + 1]} * rs[m]; V[m] = (f32x2){acc[ai][1][m][n][2 * jp], acc[ai][1][m][n][2 * jp + 1]} * rs[m]; }
; #pragma unroll
;                     for (int m = 0; m < 4; ++m) {
;                         const f32x2 zz = {0.f, 0.f}; const f32x2 Gp = m ? G[m - 1] : zz, Vp = m ? V[m - 1] : zz;
;                         const f32x2 gp1 = {dpp_prev1(G[m].x, Gp.x), dpp_prev1(G[m].y, Gp.y)}, gp2 = {dpp_prev2(G[m].x, Gp.x), dpp_prev2(G[m].y, Gp.y)};
;                         const f32x2 vp1 = {dpp_prev1(V[m].x, Vp.x), dpp_prev1(V[m].y, Vp.y)}, vp2 = {dpp_prev2(V[m].x, Vp.x), dpp_prev2(V[m].y, Vp.y)};
;                         const f32x2 gc = bg + g0 * gp2 + g1 * gp1 + g2 * G[m];
;                         const f32x2 vc = bv + v0 * vp2 + v1 * vp1 + v2 * V[m];
;                         const f32x2 xe = gc * (-LOG2E);
;                         f32x2 dn = {__builtin_amdgcn_exp2f(xe.x), __builtin_amdgcn_exp2f(xe.y)}; dn = dn + 1.0f;
;                         const f32x2 rc = {__builtin_amdgcn_rcpf(dn.x), __builtin_amdgcn_rcpf(dn.y)};
;                         const f32x2 rr = gc * rc * vc;
;                         wpk[m][jp] = pk2(rr.x, rr.y); }
	v_pk_fma_f32 v[88:89], v[100:101], v[146:147], v[96:97]
	v_pk_mul_f32 v[68:69], v[68:69], v[72:73]
	v_pk_fma_f32 v[88:89], v[108:109], v[92:93], v[88:89]
	v_pk_mul_f32 v[76:77], v[76:77], v[182:183] op_sel_hi:[1,0]
	v_pk_fma_f32 v[88:89], v[80:81], v[112:113], v[88:89]
	v_pk_mul_f32 v[68:69], v[88:89], v[68:69]
	v_mov_b32_dpp v88, v84 row_ror:2 row_mask:0xf bank_mask:0xf
	v_mov_b32_dpp v89, v85 row_ror:2 row_mask:0xf bank_mask:0xf
	v_mov_b32_dpp v72, v84 row_ror:1 row_mask:0xf bank_mask:0xf
	v_mov_b32_dpp v73, v85 row_ror:1 row_mask:0xf bank_mask:0xf
	v_mov_b32_dpp v88, v76 row_shr:2 row_mask:0xf bank_mask:0xf
	v_mov_b32_dpp v89, v77 row_shr:2 row_mask:0xf bank_mask:0xf
	v_mov_b32_dpp v72, v76 row_shr:1 row_mask:0xf bank_mask:0xf
	v_mov_b32_dpp v73, v77 row_shr:1 row_mask:0xf bank_mask:0xf
	v_pk_fma_f32 v[88:89], v[116:117], v[88:89], v[104:105]
	v_pk_fma_f32 v[72:73], v[120:121], v[72:73], v[88:89]
	v_pk_fma_f32 v[72:73], v[76:77], v[124:125], v[72:73]
	v_pk_mul_f32 v[88:89], v[72:73], s[0:1] op_sel_hi:[1,0]
	v_exp_f32_e32 v88, v88
	v_exp_f32_e32 v89, v89
	v_mov_b32_dpp v84, v80 row_ror:1 row_mask:0xf bank_mask:0xf
	v_mov_b32_dpp v85, v81 row_ror:1 row_mask:0xf bank_mask:0xf
	v_mov_b32_dpp v92, v80 row_ror:2 row_mask:0xf bank_mask:0xf
	v_mov_b32_dpp v93, v81 row_ror:2 row_mask:0xf bank_mask:0xf
	v_pk_add_f32 v[80:81], v[88:89], 1.0 op_sel_hi:[1,0]
	v_mov_b32_dpp v92, v140 row_shr:2 row_mask:0xf bank_mask:0xf
	v_rcp_f32_e32 v80, v80
	v_rcp_f32_e32 v81, v81
	v_mov_b32_dpp v93, v141 row_shr:2 row_mask:0xf bank_mask:0xf
	v_mov_b32_dpp v84, v140 row_shr:1 row_mask:0xf bank_mask:0xf
	v_mov_b32_dpp v85, v141 row_shr:1 row_mask:0xf bank_mask:0xf
	v_pk_fma_f32 v[88:89], v[100:101], v[92:93], v[96:97]
	v_pk_mul_f32 v[72:73], v[72:73], v[80:81]
	v_pk_fma_f32 v[84:85], v[108:109], v[84:85], v[88:89]
	v_pk_fma_f32 v[84:85], v[140:141], v[112:113], v[84:85]
	v_pk_mul_f32 v[72:73], v[84:85], v[72:73]
	v_mov_b32_dpp v80, v76 row_ror:1 row_mask:0xf bank_mask:0xf
	v_mov_b32_dpp v84, v76 row_ror:2 row_mask:0xf bank_mask:0xf
	v_mov_b32_dpp v85, v77 row_ror:2 row_mask:0xf bank_mask:0xf
	v_mov_b32_dpp v81, v77 row_ror:1 row_mask:0xf bank_mask:0xf
	v_mov_b32_dpp v84, v142 row_shr:2 row_mask:0xf bank_mask:0xf
	v_mov_b32_dpp v85, v143 row_shr:2 row_mask:0xf bank_mask:0xf
	v_mov_b32_dpp v80, v142 row_shr:1 row_mask:0xf bank_mask:0xf
	v_mov_b32_dpp v81, v143 row_shr:1 row_mask:0xf bank_mask:0xf
	v_pk_fma_f32 v[84:85], v[116:117], v[84:85], v[104:105]
	v_pk_fma_f32 v[80:81], v[120:121], v[80:81], v[84:85]
	v_pk_fma_f32 v[80:81], v[142:143], v[124:125], v[80:81]
	v_pk_mul_f32 v[84:85], v[80:81], s[0:1] op_sel_hi:[1,0]
	v_exp_f32_e32 v84, v84
	v_exp_f32_e32 v85, v85
	v_mov_b32_dpp v88, v140 row_ror:2 row_mask:0xf bank_mask:0xf
	v_mov_b32_dpp v89, v141 row_ror:2 row_mask:0xf bank_mask:0xf
	v_mov_b32_dpp v76, v140 row_ror:1 row_mask:0xf bank_mask:0xf
	v_pk_add_f32 v[84:85], v[84:85], 1.0 op_sel_hi:[1,0]
	v_mov_b32_dpp v77, v141 row_ror:1 row_mask:0xf bank_mask:0xf
	v_rcp_f32_e32 v84, v84
	v_rcp_f32_e32 v85, v85
	v_mov_b32_dpp v88, v144 row_shr:2 row_mask:0xf bank_mask:0xf
	v_mov_b32_dpp v89, v145 row_shr:2 row_mask:0xf bank_mask:0xf
	v_mov_b32_dpp v76, v144 row_shr:1 row_mask:0xf bank_mask:0xf
	v_mov_b32_dpp v77, v145 row_shr:1 row_mask:0xf bank_mask:0xf
	v_pk_fma_f32 v[88:89], v[100:101], v[88:89], v[96:97]
	v_pk_mul_f32 v[80:81], v[80:81], v[84:85]
	v_pk_fma_f32 v[76:77], v[108:109], v[76:77], v[88:89]
	v_pk_mul_f32 v[84:85], v[90:91], v[186:187] op_sel_hi:[1,0]
	v_pk_fma_f32 v[76:77], v[144:145], v[112:113], v[76:77]
	v_mov_b32_e32 v90, v183
	v_pk_mul_f32 v[76:77], v[76:77], v[80:81]
	v_pk_mul_f32 v[80:81], v[94:95], v[186:187] op_sel_hi:[1,0]
	v_mov_b32_e32 v91, v183
	v_mov_b32_e32 v88, v181
	v_mov_b32_e32 v89, v181
	v_mov_b32_dpp v90, v80 row_shr:2 row_mask:0xf bank_mask:0xf
	v_mov_b32_dpp v91, v81 row_shr:2 row_mask:0xf bank_mask:0xf
	v_mov_b32_dpp v88, v80 row_shr:1 row_mask:0xf bank_mask:0xf
	v_mov_b32_dpp v89, v81 row_shr:1 row_mask:0xf bank_mask:0xf
	v_pk_fma_f32 v[90:91], v[118:119], v[90:91], v[106:107]
	v_mov_b32_e32 v94, v183
	v_pk_fma_f32 v[88:89], v[122:123], v[88:89], v[90:91]
	v_mov_b32_e32 v95, v183
	v_pk_fma_f32 v[88:89], v[80:81], v[126:127], v[88:89]
	v_mov_b32_e32 v92, v181
	v_pk_mul_f32 v[90:91], v[88:89], s[0:1] op_sel_hi:[1,0]
	v_mov_b32_e32 v93, v181
	v_exp_f32_e32 v90, v90
	v_exp_f32_e32 v91, v91
	v_mov_b32_dpp v94, v84 row_shr:2 row_mask:0xf bank_mask:0xf
	v_mov_b32_dpp v95, v85 row_shr:2 row_mask:0xf bank_mask:0xf
	v_mov_b32_dpp v92, v84 row_shr:1 row_mask:0xf bank_mask:0xf
	v_pk_add_f32 v[90:91], v[90:91], 1.0 op_sel_hi:[1,0]
	v_mov_b32_dpp v93, v85 row_shr:1 row_mask:0xf bank_mask:0xf
	v_rcp_f32_e32 v90, v90
	v_rcp_f32_e32 v91, v91
	v_pk_fma_f32 v[94:95], v[102:103], v[94:95], v[98:99]
	v_cvt_pk_bf16_f32 v230, v64, v65
	v_pk_fma_f32 v[92:93], v[110:111], v[92:93], v[94:95]
	v_pk_mul_f32 v[88:89], v[88:89], v[90:91]
	v_pk_fma_f32 v[92:93], v[84:85], v[114:115], v[92:93]
	v_pk_mul_f32 v[88:89], v[92:93], v[88:89]
	v_pk_mul_f32 v[86:87], v[86:87], v[184:185] op_sel_hi:[1,0]
	v_cvt_pk_bf16_f32 v231, v88, v89
	v_mov_b32_dpp v90, v80 row_ror:2 row_mask:0xf bank_mask:0xf
	v_mov_b32_dpp v91, v81 row_ror:2 row_mask:0xf bank_mask:0xf
	v_mov_b32_dpp v88, v80 row_ror:1 row_mask:0xf bank_mask:0xf
	v_mov_b32_dpp v89, v81 row_ror:1 row_mask:0xf bank_mask:0xf
	v_mov_b32_dpp v90, v86 row_shr:2 row_mask:0xf bank_mask:0xf
	v_mov_b32_dpp v91, v87 row_shr:2 row_mask:0xf bank_mask:0xf
	v_mov_b32_dpp v88, v86 row_shr:1 row_mask:0xf bank_mask:0xf
	v_mov_b32_dpp v89, v87 row_shr:1 row_mask:0xf bank_mask:0xf
	v_pk_fma_f32 v[90:91], v[118:119], v[90:91], v[106:107]
; DI unsigned pk2(float lo, float hi) { f32x2 v = {lo, hi}; bf16x2_t b = __builtin_convertvector(v, bf16x2_t); return __builtin_bit_cast(unsigned, b); }
;     DI void operator()(const AccT& acc, const Unit& u, int wr, int wc, int fr, int fq) const {
;     ...
;                     for (int m = 0; m < 4; ++m) {
;                         const f32x2 zz = {0.f, 0.f}; const f32x2 Gp = m ? G[m - 1] : zz, Vp = m ? V[m - 1] : zz;
;                         const f32x2 gp1 = {dpp_prev1(G[m].x, Gp.x), dpp_prev1(G[m].y, Gp.y)}, gp2 = {dpp_prev2(G[m].x, Gp.x), dpp_prev2(G[m].y, Gp.y)};
;                         const f32x2 vp1 = {dpp_prev1(V[m].x, Vp.x), dpp_prev1(V[m].y, Vp.y)}, vp2 = {dpp_prev2(V[m].x, Vp.x), dpp_prev2(V[m].y, Vp.y)};
;                         const f32x2 gc = bg + g0 * gp2 + g1 * gp1 + g2 * G[m];
;                         const f32x2 vc = bv + v0 * vp2 + v1 * vp1 + v2 * V[m];
;                         const f32x2 xe = gc * (-LOG2E);
;                         f32x2 dn = {__builtin_amdgcn_exp2f(xe.x), __builtin_amdgcn_exp2f(xe.y)}; dn = dn + 1.0f;
;                         const f32x2 rc = {__builtin_amdgcn_rcpf(dn.x), __builtin_amdgcn_rcpf(dn.y)};
;                         const f32x2 rr = gc * rc * vc;
;                         wpk[m][jp] = pk2(rr.x, rr.y); }
;                 }
; #pragma unroll
;                 for (int m = 0; m < 4; ++m) { const int row = m ? tok0 + 16 * m : row0;
;                     *(u32x2*)(ACT + (size_t)row * 2816 + cl + 4 * n) = (u32x2){wpk[m][0], wpk[m][1]}; }
	v_pk_fma_f32 v[88:89], v[122:123], v[88:89], v[90:91]
	v_pk_fma_f32 v[88:89], v[86:87], v[126:127], v[88:89]
	v_pk_mul_f32 v[90:91], v[88:89], s[0:1] op_sel_hi:[1,0]
	v_exp_f32_e32 v90, v90
	v_exp_f32_e32 v91, v91
	v_mov_b32_dpp v80, v84 row_ror:1 row_mask:0xf bank_mask:0xf
	v_mov_b32_dpp v81, v85 row_ror:1 row_mask:0xf bank_mask:0xf
	v_mov_b32_dpp v92, v84 row_ror:2 row_mask:0xf bank_mask:0xf
	v_mov_b32_dpp v93, v85 row_ror:2 row_mask:0xf bank_mask:0xf
	v_pk_add_f32 v[84:85], v[90:91], 1.0 op_sel_hi:[1,0]
	v_pk_mul_f32 v[82:83], v[82:83], v[184:185] op_sel_hi:[1,0]
	v_rcp_f32_e32 v84, v84
	v_rcp_f32_e32 v85, v85
	v_mov_b32_dpp v92, v82 row_shr:2 row_mask:0xf bank_mask:0xf
	v_mov_b32_dpp v93, v83 row_shr:2 row_mask:0xf bank_mask:0xf
	v_mov_b32_dpp v80, v82 row_shr:1 row_mask:0xf bank_mask:0xf
	v_mov_b32_dpp v81, v83 row_shr:1 row_mask:0xf bank_mask:0xf
	v_pk_fma_f32 v[90:91], v[102:103], v[92:93], v[98:99]
	v_pk_mul_f32 v[84:85], v[88:89], v[84:85]
	v_pk_fma_f32 v[80:81], v[110:111], v[80:81], v[90:91]
	v_cvt_pk_bf16_f32 v234, v68, v69
	v_pk_fma_f32 v[80:81], v[82:83], v[114:115], v[80:81]
	v_pk_mul_f32 v[78:79], v[78:79], v[182:183] op_sel_hi:[1,0]
	v_pk_mul_f32 v[80:81], v[80:81], v[84:85]
	v_cvt_pk_bf16_f32 v235, v80, v81
	v_mov_b32_dpp v84, v86 row_ror:2 row_mask:0xf bank_mask:0xf
	v_mov_b32_dpp v85, v87 row_ror:2 row_mask:0xf bank_mask:0xf
	v_mov_b32_dpp v80, v86 row_ror:1 row_mask:0xf bank_mask:0xf
	v_mov_b32_dpp v81, v87 row_ror:1 row_mask:0xf bank_mask:0xf
	v_mov_b32_dpp v84, v78 row_shr:2 row_mask:0xf bank_mask:0xf
	v_mov_b32_dpp v85, v79 row_shr:2 row_mask:0xf bank_mask:0xf
	v_mov_b32_dpp v80, v78 row_shr:1 row_mask:0xf bank_mask:0xf
	v_mov_b32_dpp v81, v79 row_shr:1 row_mask:0xf bank_mask:0xf
	v_pk_fma_f32 v[84:85], v[118:119], v[84:85], v[106:107]
	v_pk_fma_f32 v[80:81], v[122:123], v[80:81], v[84:85]
	v_pk_fma_f32 v[80:81], v[78:79], v[126:127], v[80:81]
	v_pk_mul_f32 v[84:85], v[80:81], s[0:1] op_sel_hi:[1,0]
	v_exp_f32_e32 v84, v84
	v_exp_f32_e32 v85, v85
	v_mov_b32_dpp v86, v82 row_ror:1 row_mask:0xf bank_mask:0xf
	v_mov_b32_dpp v87, v83 row_ror:1 row_mask:0xf bank_mask:0xf
	v_mov_b32_dpp v88, v82 row_ror:2 row_mask:0xf bank_mask:0xf
	v_mov_b32_dpp v89, v83 row_ror:2 row_mask:0xf bank_mask:0xf
	v_pk_add_f32 v[82:83], v[84:85], 1.0 op_sel_hi:[1,0]
	v_pk_mul_f32 v[74:75], v[74:75], v[182:183] op_sel_hi:[1,0]
	v_rcp_f32_e32 v82, v82
	v_rcp_f32_e32 v83, v83
	v_mov_b32_dpp v88, v74 row_shr:2 row_mask:0xf bank_mask:0xf
	v_mov_b32_dpp v89, v75 row_shr:2 row_mask:0xf bank_mask:0xf
	v_mov_b32_dpp v86, v74 row_shr:1 row_mask:0xf bank_mask:0xf
	v_mov_b32_dpp v87, v75 row_shr:1 row_mask:0xf bank_mask:0xf
	v_pk_fma_f32 v[84:85], v[102:103], v[88:89], v[98:99]
	v_pk_mul_f32 v[80:81], v[80:81], v[82:83]
	v_pk_fma_f32 v[84:85], v[110:111], v[86:87], v[84:85]
	v_pk_fma_f32 v[84:85], v[74:75], v[114:115], v[84:85]
	v_pk_mul_f32 v[80:81], v[84:85], v[80:81]
	v_cvt_pk_bf16_f32 v238, v72, v73
	v_pk_mul_f32 v[70:71], v[70:71], v[180:181] op_sel_hi:[1,0]
	v_cvt_pk_bf16_f32 v239, v80, v81
	v_mov_b32_dpp v82, v78 row_ror:2 row_mask:0xf bank_mask:0xf
	v_mov_b32_dpp v83, v79 row_ror:2 row_mask:0xf bank_mask:0xf
	v_mov_b32_dpp v80, v78 row_ror:1 row_mask:0xf bank_mask:0xf
	v_mov_b32_dpp v81, v79 row_ror:1 row_mask:0xf bank_mask:0xf
	v_mov_b32_dpp v82, v70 row_shr:2 row_mask:0xf bank_mask:0xf
	v_mov_b32_dpp v83, v71 row_shr:2 row_mask:0xf bank_mask:0xf
	v_mov_b32_dpp v80, v70 row_shr:1 row_mask:0xf bank_mask:0xf
	v_mov_b32_dpp v81, v71 row_shr:1 row_mask:0xf bank_mask:0xf
	v_pk_fma_f32 v[82:83], v[118:119], v[82:83], v[106:107]
	v_pk_fma_f32 v[80:81], v[122:123], v[80:81], v[82:83]
	v_pk_fma_f32 v[70:71], v[70:71], v[126:127], v[80:81]
	v_pk_mul_f32 v[80:81], v[70:71], s[0:1] op_sel_hi:[1,0]
	v_exp_f32_e32 v80, v80
	v_exp_f32_e32 v81, v81
	v_mov_b32_dpp v78, v74 row_ror:1 row_mask:0xf bank_mask:0xf
	v_mov_b32_dpp v79, v75 row_ror:1 row_mask:0xf bank_mask:0xf
	v_mov_b32_dpp v84, v74 row_ror:2 row_mask:0xf bank_mask:0xf
	v_mov_b32_dpp v85, v75 row_ror:2 row_mask:0xf bank_mask:0xf
	v_pk_add_f32 v[74:75], v[80:81], 1.0 op_sel_hi:[1,0]
	v_pk_mul_f32 v[66:67], v[66:67], v[180:181] op_sel_hi:[1,0]
	v_rcp_f32_e32 v74, v74
	v_rcp_f32_e32 v75, v75
	v_mov_b32_dpp v84, v66 row_shr:2 row_mask:0xf bank_mask:0xf
	v_mov_b32_dpp v85, v67 row_shr:2 row_mask:0xf bank_mask:0xf
	v_mov_b32_dpp v78, v66 row_shr:1 row_mask:0xf bank_mask:0xf
	v_mov_b32_dpp v79, v67 row_shr:1 row_mask:0xf bank_mask:0xf
	v_pk_fma_f32 v[80:81], v[102:103], v[84:85], v[98:99]
	v_pk_mul_f32 v[70:71], v[70:71], v[74:75]
	v_pk_fma_f32 v[78:79], v[110:111], v[78:79], v[80:81]
	v_cvt_pk_bf16_f32 v254, v76, v77
	v_pk_fma_f32 v[66:67], v[66:67], v[114:115], v[78:79]
	s_nop 0
	v_pk_mul_f32 v[66:67], v[66:67], v[70:71]
	s_nop 0
	v_cvt_pk_bf16_f32 v255, v66, v67
	global_store_dwordx4 v[132:133], v[228:231], off
	global_store_dwordx4 v[134:135], v[232:235], off
	global_store_dwordx4 v[136:137], v[236:239], off
	global_store_dwordx4 v[138:139], v[252:255], off
	v_add_u32_e32 v96, 0x7c, v204
	v_med3_i32 v64, v96, 0, s51
	v_add_u32_e32 v97, 0x8c, v204
	v_add_u32_e32 v99, 0x9c, v204
	v_add_u32_e32 v101, 0xac, v204
	v_lshlrev_b32_e32 v64, 3, v64
	v_med3_i32 v65, v97, 0, s51
	v_med3_i32 v66, v99, 0, s51
	v_med3_i32 v67, v101, 0, s51
	v_lshlrev_b32_e32 v65, 3, v65
	v_lshlrev_b32_e32 v66, 3, v66
	v_lshlrev_b32_e32 v67, 3, v67
	v_cndmask_b32_e64 v103, v96, v190, s[6:7]
	v_mov_b32_e32 v112, v181
	v_mov_b32_e32 v113, v181
	ds_read_b128 v[72:75], v200
	ds_read_b128 v[84:87], v200 offset:128
	ds_read_b128 v[88:91], v200 offset:256
	ds_read_b128 v[92:95], v200 offset:384
	ds_read_b128 v[64:67], v200 offset:512
	ds_read_b128 v[68:71], v200 offset:640
	ds_read_b128 v[76:79], v200 offset:768
	ds_read_b128 v[80:83], v200 offset:896
	s_waitcnt vmcnt(4)
; #define LAS __attribute__((address_space(3)))
; DI float rs_from_ss(u64 ssq) { return rsqrtf((float)ssq * (1.f / (1048576.f * 1024.f)) + EPS); }
;     DI void operator()(const AccT& acc, const Unit& u, int wr, int wc, int fr, int fq) const {
;     ...
;             for (int m = 0; m < 4; ++m) { const int t = tok0 + 16 * m; const int tc = t < 0 ? 0 : (t >= S ? S - 1 : t); const float r = rs_from_ss(rowss[tc]); rs[m] = t < 0 ? 0.f : r; }
;             const int row0 = fr < 2 ? (S + 236 + fr) : tok0;
; #pragma unroll
;             for (int n = 0; n < 2; ++n) {
;                 const int lc = 8 * fq + 4 * n;
;                 unsigned wpk[4][2];
; #pragma unroll
;                 for (int jp = 0; jp < 2; ++jp) {
;                     const f32x2 bg = *(const LAS f32x2*)(P + lc + 2 * jp), g0 = *(const LAS f32x2*)(P + 32 + lc + 2 * jp), g1 = *(const LAS f32x2*)(P + 64 + lc + 2 * jp), g2 = *(const LAS f32x2*)(P + 96 + lc + 2 * jp);
;                     const f32x2 bv = *(const LAS f32x2*)(P + 128 + lc + 2 * jp), v0 = *(const LAS f32x2*)(P + 160 + lc + 2 * jp), v1 = *(const LAS f32x2*)(P + 192 + lc + 2 * jp), v2 = *(const LAS f32x2*)(P + 224 + lc + 2 * jp);
;                     f32x2 G[4], V[4];
; #pragma unroll
;                     for (int m = 0; m < 4; ++m) { G[m] = (f32x2){acc[ai][0][m][n][2 * jp], acc[ai][0][m][n][2 * jp + 1]} * rs[m]; V[m] = (f32x2){acc[ai][1][m][n][2 * jp], acc[ai][1][m][n][2 * jp + 1]} * rs[m]; }
; #pragma unroll
;                     for (int m = 0; m < 4; ++m) {
;                         const f32x2 zz = {0.f, 0.f}; const f32x2 Gp = m ? G[m - 1] : zz, Vp = m ? V[m - 1] : zz;
;                         const f32x2 gp1 = {dpp_prev1(G[m].x, Gp.x), dpp_prev1(G[m].y, Gp.y)}, gp2 = {dpp_prev2(G[m].x, Gp.x), dpp_prev2(G[m].y, Gp.y)};
;                         const f32x2 vp1 = {dpp_prev1(V[m].x, Vp.x), dpp_prev1(V[m].y, Vp.y)}, vp2 = {dpp_prev2(V[m].x, Vp.x), dpp_prev2(V[m].y, Vp.y)};
;                         const f32x2 gc = bg + g0 * gp2 + g1 * gp1 + g2 * G[m];
;                         const f32x2 vc = bv + v0 * vp2 + v1 * vp1 + v2 * V[m];
	v_mov_b32_e32 v104, v242
	v_mov_b32_e32 v105, v243
	v_mov_b32_e32 v106, v244
	v_mov_b32_e32 v107, v245
	v_mov_b32_e32 v108, v246
	v_mov_b32_e32 v109, v247
	v_mov_b32_e32 v110, v248
	v_mov_b32_e32 v111, v249
	v_ffbh_u32_e32 v98, v105
	v_ffbh_u32_e32 v100, v107
	v_ffbh_u32_e32 v102, v109
	v_min_u32_e32 v98, 32, v98
	v_min_u32_e32 v100, 32, v100
	v_min_u32_e32 v102, 32, v102
	v_lshlrev_b64 v[104:105], v98, v[104:105]
	v_ffbh_u32_e32 v114, v111
	v_lshlrev_b64 v[106:107], v100, v[106:107]
	v_lshlrev_b64 v[108:109], v102, v[108:109]
	v_min_u32_e32 v104, 1, v104
	v_min_u32_e32 v114, 32, v114
	v_min_u32_e32 v106, 1, v106
	v_min_u32_e32 v108, 1, v108
	v_or_b32_e32 v104, v105, v104
	v_lshlrev_b64 v[110:111], v114, v[110:111]
	v_or_b32_e32 v105, v107, v106
	v_or_b32_e32 v106, v109, v108
	v_cvt_f32_u32_e32 v104, v104
	v_min_u32_e32 v110, 1, v110
	v_cvt_f32_u32_e32 v105, v105
	v_cvt_f32_u32_e32 v106, v106
	v_or_b32_e32 v107, v111, v110
	v_sub_u32_e32 v98, 32, v98
	v_cvt_f32_u32_e32 v107, v107
	v_sub_u32_e32 v100, 32, v100
	v_sub_u32_e32 v102, 32, v102
	v_ldexp_f32 v98, v104, v98
	v_ldexp_f32 v100, v105, v100
	v_ldexp_f32 v102, v106, v102
	v_fmamk_f32 v98, v98, 0x30800000, v203
	v_sub_u32_e32 v114, 32, v114
	v_fmamk_f32 v100, v100, 0x30800000, v203
	v_fmamk_f32 v102, v102, 0x30800000, v203
	v_mul_f32_e32 v105, 0x4b800000, v98
	v_cmp_gt_f32_e32 vcc, s52, v98
	v_ldexp_f32 v104, v107, v114
	v_mul_f32_e32 v106, 0x4b800000, v100
	v_mul_f32_e32 v107, 0x4b800000, v102
	v_cndmask_b32_e32 v98, v98, v105, vcc
	v_cmp_gt_f32_e64 s[10:11], s52, v100
	v_cmp_gt_f32_e64 s[12:13], s52, v102
	v_fmamk_f32 v104, v104, 0x30800000, v203
	v_cndmask_b32_e64 v100, v100, v106, s[10:11]
	v_cndmask_b32_e64 v102, v102, v107, s[12:13]
	v_rsq_f32_e32 v98, v98
	v_mul_f32_e32 v108, 0x4b800000, v104
	v_cmp_gt_f32_e64 s[14:15], s52, v104
	v_rsq_f32_e32 v100, v100
	v_rsq_f32_e32 v102, v102
	v_cndmask_b32_e64 v104, v104, v108, s[14:15]
	v_rsq_f32_e32 v104, v104
	v_mul_f32_e32 v105, 0x45800000, v98
	v_mul_f32_e32 v106, 0x45800000, v100
	v_mul_f32_e32 v107, 0x45800000, v102
	v_cndmask_b32_e32 v98, v98, v105, vcc
	v_cmp_lt_i32_e32 vcc, -1, v96
	v_cndmask_b32_e64 v100, v100, v106, s[10:11]
	v_cndmask_b32_e64 v105, v102, v107, s[12:13]
	v_cndmask_b32_e32 v102, 0, v98, vcc
	v_cmp_lt_i32_e32 vcc, s53, v96
	v_mul_f32_e32 v108, 0x45800000, v104
	v_cndmask_b32_e64 v104, v104, v108, s[14:15]
	v_cndmask_b32_e32 v100, 0, v100, vcc
	v_cmp_lt_i32_e32 vcc, s54, v96
	v_pk_mul_f32 v[60:61], v[60:61], v[102:103] op_sel_hi:[1,0]
	v_pk_mul_f32 v[56:57], v[56:57], v[102:103] op_sel_hi:[1,0]
	v_cndmask_b32_e32 v98, 0, v105, vcc
	v_cmp_lt_i32_e32 vcc, s55, v96
	v_mov_b32_dpp v112, v60 row_shr:1 row_mask:0xf bank_mask:0xf
	v_mov_b32_dpp v113, v61 row_shr:1 row_mask:0xf bank_mask:0xf
	v_cndmask_b32_e32 v96, 0, v104, vcc
	v_pk_mul_f32 v[108:109], v[32:33], v[96:97] op_sel_hi:[1,0]
	v_mov_b32_e32 v32, v183
	v_mov_b32_e32 v33, v183
	v_pk_mul_f32 v[104:105], v[40:41], v[98:99] op_sel_hi:[1,0]
	v_mov_b32_dpp v32, v60 row_shr:2 row_mask:0xf bank_mask:0xf
	v_mov_b32_dpp v33, v61 row_shr:2 row_mask:0xf bank_mask:0xf
	s_waitcnt lgkmcnt(6)
	v_pk_fma_f32 v[32:33], v[84:85], v[32:33], v[72:73]
	v_mov_b32_e32 v40, v183
	s_waitcnt lgkmcnt(5)
	v_pk_fma_f32 v[32:33], v[88:89], v[112:113], v[32:33]
	v_mov_b32_e32 v41, v183
	s_waitcnt lgkmcnt(4)
	v_pk_fma_f32 v[32:33], v[92:93], v[60:61], v[32:33]
	v_pk_mul_f32 v[106:107], v[36:37], v[96:97] op_sel_hi:[1,0]
	v_pk_mul_f32 v[110:111], v[32:33], s[0:1] op_sel_hi:[1,0]
	v_mov_b32_e32 v36, v181
	v_exp_f32_e32 v110, v110
	v_exp_f32_e32 v111, v111
	v_mov_b32_e32 v37, v181
	v_mov_b32_dpp v40, v56 row_shr:2 row_mask:0xf bank_mask:0xf
	v_mov_b32_dpp v41, v57 row_shr:2 row_mask:0xf bank_mask:0xf
	v_pk_add_f32 v[110:111], v[110:111], 1.0 op_sel_hi:[1,0]
	v_mov_b32_dpp v36, v56 row_shr:1 row_mask:0xf bank_mask:0xf
	v_rcp_f32_e32 v110, v110
	v_rcp_f32_e32 v111, v111
	v_mov_b32_dpp v37, v57 row_shr:1 row_mask:0xf bank_mask:0xf
	s_waitcnt lgkmcnt(2)
	v_pk_fma_f32 v[40:41], v[68:69], v[40:41], v[64:65]
	v_pk_mul_f32 v[52:53], v[52:53], v[100:101] op_sel_hi:[1,0]
	s_waitcnt lgkmcnt(1)
	v_pk_fma_f32 v[36:37], v[76:77], v[36:37], v[40:41]
	v_pk_mul_f32 v[32:33], v[32:33], v[110:111]
	s_waitcnt lgkmcnt(0)
	v_pk_fma_f32 v[36:37], v[80:81], v[56:57], v[36:37]
	v_pk_mul_f32 v[32:33], v[36:37], v[32:33]
	v_mov_b32_dpp v40, v60 row_ror:2 row_mask:0xf bank_mask:0xf
	v_mov_b32_dpp v41, v61 row_ror:2 row_mask:0xf bank_mask:0xf
	v_mov_b32_dpp v36, v60 row_ror:1 row_mask:0xf bank_mask:0xf
	v_mov_b32_dpp v37, v61 row_ror:1 row_mask:0xf bank_mask:0xf
	v_mov_b32_dpp v40, v52 row_shr:2 row_mask:0xf bank_mask:0xf
	v_mov_b32_dpp v41, v53 row_shr:2 row_mask:0xf bank_mask:0xf
	v_mov_b32_dpp v36, v52 row_shr:1 row_mask:0xf bank_mask:0xf
	v_mov_b32_dpp v37, v53 row_shr:1 row_mask:0xf bank_mask:0xf
	v_pk_fma_f32 v[40:41], v[84:85], v[40:41], v[72:73]
	v_pk_fma_f32 v[36:37], v[88:89], v[36:37], v[40:41]
	v_pk_fma_f32 v[36:37], v[92:93], v[52:53], v[36:37]
	v_pk_mul_f32 v[48:49], v[48:49], v[100:101] op_sel_hi:[1,0]
	v_pk_mul_f32 v[40:41], v[36:37], s[0:1] op_sel_hi:[1,0]
	v_exp_f32_e32 v40, v40
	v_exp_f32_e32 v41, v41
	v_mov_b32_dpp v110, v56 row_ror:2 row_mask:0xf bank_mask:0xf
	v_mov_b32_dpp v111, v57 row_ror:2 row_mask:0xf bank_mask:0xf
	v_pk_add_f32 v[40:41], v[40:41], 1.0 op_sel_hi:[1,0]
	v_mov_b32_dpp v60, v56 row_ror:1 row_mask:0xf bank_mask:0xf
	v_rcp_f32_e32 v40, v40
	v_rcp_f32_e32 v41, v41
	v_mov_b32_dpp v61, v57 row_ror:1 row_mask:0xf bank_mask:0xf
	v_mov_b32_dpp v110, v48 row_shr:2 row_mask:0xf bank_mask:0xf
	v_mov_b32_dpp v111, v49 row_shr:2 row_mask:0xf bank_mask:0xf
	v_mov_b32_dpp v60, v48 row_shr:1 row_mask:0xf bank_mask:0xf
; DI unsigned pk2(float lo, float hi) { f32x2 v = {lo, hi}; bf16x2_t b = __builtin_convertvector(v, bf16x2_t); return __builtin_bit_cast(unsigned, b); }
;     DI void operator()(const AccT& acc, const Unit& u, int wr, int wc, int fr, int fq) const {
;     ...
;                     for (int m = 0; m < 4; ++m) { G[m] = (f32x2){acc[ai][0][m][n][2 * jp], acc[ai][0][m][n][2 * jp + 1]} * rs[m]; V[m] = (f32x2){acc[ai][1][m][n][2 * jp], acc[ai][1][m][n][2 * jp + 1]} * rs[m]; }
; #pragma unroll
;                     for (int m = 0; m < 4; ++m) {
;                         const f32x2 zz = {0.f, 0.f}; const f32x2 Gp = m ? G[m - 1] : zz, Vp = m ? V[m - 1] : zz;
;                         const f32x2 gp1 = {dpp_prev1(G[m].x, Gp.x), dpp_prev1(G[m].y, Gp.y)}, gp2 = {dpp_prev2(G[m].x, Gp.x), dpp_prev2(G[m].y, Gp.y)};
;                         const f32x2 vp1 = {dpp_prev1(V[m].x, Vp.x), dpp_prev1(V[m].y, Vp.y)}, vp2 = {dpp_prev2(V[m].x, Vp.x), dpp_prev2(V[m].y, Vp.y)};
;                         const f32x2 gc = bg + g0 * gp2 + g1 * gp1 + g2 * G[m];
;                         const f32x2 vc = bv + v0 * vp2 + v1 * vp1 + v2 * V[m];
;                         const f32x2 xe = gc * (-LOG2E);
;                         f32x2 dn = {__builtin_amdgcn_exp2f(xe.x), __builtin_amdgcn_exp2f(xe.y)}; dn = dn + 1.0f;
;                         const f32x2 rc = {__builtin_amdgcn_rcpf(dn.x), __builtin_amdgcn_rcpf(dn.y)};
;                         const f32x2 rr = gc * rc * vc;
;                         wpk[m][jp] = pk2(rr.x, rr.y); }
	v_mov_b32_dpp v61, v49 row_shr:1 row_mask:0xf bank_mask:0xf
	v_pk_fma_f32 v[56:57], v[68:69], v[110:111], v[64:65]
	v_pk_mul_f32 v[36:37], v[36:37], v[40:41]
	v_pk_fma_f32 v[56:57], v[76:77], v[60:61], v[56:57]
	v_pk_mul_f32 v[44:45], v[44:45], v[98:99] op_sel_hi:[1,0]
	v_pk_fma_f32 v[56:57], v[80:81], v[48:49], v[56:57]
	v_pk_mul_f32 v[36:37], v[56:57], v[36:37]
	v_mov_b32_dpp v56, v52 row_ror:2 row_mask:0xf bank_mask:0xf
	v_mov_b32_dpp v57, v53 row_ror:2 row_mask:0xf bank_mask:0xf
	v_mov_b32_dpp v40, v52 row_ror:1 row_mask:0xf bank_mask:0xf
	v_mov_b32_dpp v41, v53 row_ror:1 row_mask:0xf bank_mask:0xf
	v_mov_b32_dpp v56, v44 row_shr:2 row_mask:0xf bank_mask:0xf
	v_mov_b32_dpp v57, v45 row_shr:2 row_mask:0xf bank_mask:0xf
	v_mov_b32_dpp v40, v44 row_shr:1 row_mask:0xf bank_mask:0xf
	v_mov_b32_dpp v41, v45 row_shr:1 row_mask:0xf bank_mask:0xf
	v_pk_fma_f32 v[56:57], v[84:85], v[56:57], v[72:73]
	v_pk_fma_f32 v[40:41], v[88:89], v[40:41], v[56:57]
	v_pk_fma_f32 v[40:41], v[92:93], v[44:45], v[40:41]
	v_pk_mul_f32 v[56:57], v[40:41], s[0:1] op_sel_hi:[1,0]
	v_exp_f32_e32 v56, v56
	v_exp_f32_e32 v57, v57
	v_mov_b32_dpp v52, v48 row_ror:1 row_mask:0xf bank_mask:0xf
	v_mov_b32_dpp v53, v49 row_ror:1 row_mask:0xf bank_mask:0xf
	v_mov_b32_dpp v60, v48 row_ror:2 row_mask:0xf bank_mask:0xf
	v_mov_b32_dpp v61, v49 row_ror:2 row_mask:0xf bank_mask:0xf
	v_pk_add_f32 v[48:49], v[56:57], 1.0 op_sel_hi:[1,0]
	v_mov_b32_dpp v60, v104 row_shr:2 row_mask:0xf bank_mask:0xf
	v_rcp_f32_e32 v48, v48
	v_rcp_f32_e32 v49, v49
	v_mov_b32_dpp v61, v105 row_shr:2 row_mask:0xf bank_mask:0xf
	v_mov_b32_dpp v52, v104 row_shr:1 row_mask:0xf bank_mask:0xf
	v_mov_b32_dpp v53, v105 row_shr:1 row_mask:0xf bank_mask:0xf
	v_pk_fma_f32 v[56:57], v[68:69], v[60:61], v[64:65]
	v_pk_mul_f32 v[40:41], v[40:41], v[48:49]
	v_pk_fma_f32 v[52:53], v[76:77], v[52:53], v[56:57]
	v_pk_fma_f32 v[52:53], v[80:81], v[104:105], v[52:53]
	v_pk_mul_f32 v[40:41], v[52:53], v[40:41]
	v_mov_b32_dpp v48, v44 row_ror:1 row_mask:0xf bank_mask:0xf
	v_mov_b32_dpp v52, v44 row_ror:2 row_mask:0xf bank_mask:0xf
	v_mov_b32_dpp v53, v45 row_ror:2 row_mask:0xf bank_mask:0xf
	v_mov_b32_dpp v49, v45 row_ror:1 row_mask:0xf bank_mask:0xf
	v_mov_b32_dpp v52, v106 row_shr:2 row_mask:0xf bank_mask:0xf
	v_mov_b32_dpp v53, v107 row_shr:2 row_mask:0xf bank_mask:0xf
	v_mov_b32_dpp v48, v106 row_shr:1 row_mask:0xf bank_mask:0xf
	v_mov_b32_dpp v49, v107 row_shr:1 row_mask:0xf bank_mask:0xf
	v_pk_fma_f32 v[52:53], v[84:85], v[52:53], v[72:73]
	v_pk_fma_f32 v[48:49], v[88:89], v[48:49], v[52:53]
	v_pk_fma_f32 v[48:49], v[92:93], v[106:107], v[48:49]
	v_pk_mul_f32 v[52:53], v[48:49], s[0:1] op_sel_hi:[1,0]
	v_exp_f32_e32 v52, v52
	v_exp_f32_e32 v53, v53
	v_mov_b32_dpp v56, v104 row_ror:2 row_mask:0xf bank_mask:0xf
	v_mov_b32_dpp v57, v105 row_ror:2 row_mask:0xf bank_mask:0xf
	v_mov_b32_dpp v44, v104 row_ror:1 row_mask:0xf bank_mask:0xf
	v_pk_add_f32 v[52:53], v[52:53], 1.0 op_sel_hi:[1,0]
	v_mov_b32_dpp v45, v105 row_ror:1 row_mask:0xf bank_mask:0xf
	v_rcp_f32_e32 v52, v52
	v_rcp_f32_e32 v53, v53
	v_mov_b32_dpp v56, v108 row_shr:2 row_mask:0xf bank_mask:0xf
	v_mov_b32_dpp v57, v109 row_shr:2 row_mask:0xf bank_mask:0xf
	v_mov_b32_dpp v44, v108 row_shr:1 row_mask:0xf bank_mask:0xf
	v_mov_b32_dpp v45, v109 row_shr:1 row_mask:0xf bank_mask:0xf
	v_pk_fma_f32 v[56:57], v[68:69], v[56:57], v[64:65]
	v_pk_mul_f32 v[48:49], v[48:49], v[52:53]
	v_pk_fma_f32 v[44:45], v[76:77], v[44:45], v[56:57]
	v_pk_mul_f32 v[52:53], v[58:59], v[102:103] op_sel_hi:[1,0]
	v_pk_fma_f32 v[44:45], v[80:81], v[108:109], v[44:45]
	v_mov_b32_e32 v58, v183
	v_pk_mul_f32 v[44:45], v[44:45], v[48:49]
	v_pk_mul_f32 v[48:49], v[62:63], v[102:103] op_sel_hi:[1,0]
	v_mov_b32_e32 v59, v183
	v_mov_b32_e32 v56, v181
	v_mov_b32_e32 v57, v181
	v_mov_b32_dpp v58, v48 row_shr:2 row_mask:0xf bank_mask:0xf
	v_mov_b32_dpp v59, v49 row_shr:2 row_mask:0xf bank_mask:0xf
	v_mov_b32_dpp v56, v48 row_shr:1 row_mask:0xf bank_mask:0xf
	v_mov_b32_dpp v57, v49 row_shr:1 row_mask:0xf bank_mask:0xf
	v_pk_fma_f32 v[58:59], v[86:87], v[58:59], v[74:75]
	v_mov_b32_e32 v62, v183
	v_pk_fma_f32 v[56:57], v[90:91], v[56:57], v[58:59]
	v_mov_b32_e32 v63, v183
	v_pk_fma_f32 v[56:57], v[48:49], v[94:95], v[56:57]
	v_mov_b32_e32 v60, v181
	v_pk_mul_f32 v[58:59], v[56:57], s[0:1] op_sel_hi:[1,0]
	v_mov_b32_e32 v61, v181
	v_exp_f32_e32 v58, v58
	v_exp_f32_e32 v59, v59
	v_mov_b32_dpp v62, v52 row_shr:2 row_mask:0xf bank_mask:0xf
	v_mov_b32_dpp v63, v53 row_shr:2 row_mask:0xf bank_mask:0xf
	v_mov_b32_dpp v60, v52 row_shr:1 row_mask:0xf bank_mask:0xf
	v_pk_add_f32 v[58:59], v[58:59], 1.0 op_sel_hi:[1,0]
	v_mov_b32_dpp v61, v53 row_shr:1 row_mask:0xf bank_mask:0xf
	v_rcp_f32_e32 v58, v58
	v_rcp_f32_e32 v59, v59
	v_pk_fma_f32 v[62:63], v[70:71], v[62:63], v[66:67]
	v_cvt_pk_bf16_f32 v236, v32, v33
	v_pk_fma_f32 v[60:61], v[78:79], v[60:61], v[62:63]
	v_pk_mul_f32 v[56:57], v[56:57], v[58:59]
	v_pk_fma_f32 v[60:61], v[52:53], v[82:83], v[60:61]
	v_pk_mul_f32 v[56:57], v[60:61], v[56:57]
	v_pk_mul_f32 v[54:55], v[54:55], v[100:101] op_sel_hi:[1,0]
	v_cvt_pk_bf16_f32 v237, v56, v57
	v_mov_b32_dpp v58, v48 row_ror:2 row_mask:0xf bank_mask:0xf
	v_mov_b32_dpp v59, v49 row_ror:2 row_mask:0xf bank_mask:0xf
	v_mov_b32_dpp v56, v48 row_ror:1 row_mask:0xf bank_mask:0xf
	v_mov_b32_dpp v57, v49 row_ror:1 row_mask:0xf bank_mask:0xf
	v_mov_b32_dpp v58, v54 row_shr:2 row_mask:0xf bank_mask:0xf
	v_mov_b32_dpp v59, v55 row_shr:2 row_mask:0xf bank_mask:0xf
	v_mov_b32_dpp v56, v54 row_shr:1 row_mask:0xf bank_mask:0xf
	v_mov_b32_dpp v57, v55 row_shr:1 row_mask:0xf bank_mask:0xf
	v_pk_fma_f32 v[58:59], v[86:87], v[58:59], v[74:75]
; DI unsigned pk2(float lo, float hi) { f32x2 v = {lo, hi}; bf16x2_t b = __builtin_convertvector(v, bf16x2_t); return __builtin_bit_cast(unsigned, b); }
;     DI void operator()(const AccT& acc, const Unit& u, int wr, int wc, int fr, int fq) const {
;     ...
;                     for (int m = 0; m < 4; ++m) {
;                         const f32x2 zz = {0.f, 0.f}; const f32x2 Gp = m ? G[m - 1] : zz, Vp = m ? V[m - 1] : zz;
;                         const f32x2 gp1 = {dpp_prev1(G[m].x, Gp.x), dpp_prev1(G[m].y, Gp.y)}, gp2 = {dpp_prev2(G[m].x, Gp.x), dpp_prev2(G[m].y, Gp.y)};
;                         const f32x2 vp1 = {dpp_prev1(V[m].x, Vp.x), dpp_prev1(V[m].y, Vp.y)}, vp2 = {dpp_prev2(V[m].x, Vp.x), dpp_prev2(V[m].y, Vp.y)};
;                         const f32x2 gc = bg + g0 * gp2 + g1 * gp1 + g2 * G[m];
;                         const f32x2 vc = bv + v0 * vp2 + v1 * vp1 + v2 * V[m];
;                         const f32x2 xe = gc * (-LOG2E);
;                         f32x2 dn = {__builtin_amdgcn_exp2f(xe.x), __builtin_amdgcn_exp2f(xe.y)}; dn = dn + 1.0f;
;                         const f32x2 rc = {__builtin_amdgcn_rcpf(dn.x), __builtin_amdgcn_rcpf(dn.y)};
;                         const f32x2 rr = gc * rc * vc;
;                         wpk[m][jp] = pk2(rr.x, rr.y); }
;                 }
; #pragma unroll
;                 for (int m = 0; m < 4; ++m) { const int row = m ? tok0 + 16 * m : row0;
;                     *(u32x2*)(ACT + (size_t)row * 2816 + cl + 4 * n) = (u32x2){wpk[m][0], wpk[m][1]}; }
	v_pk_fma_f32 v[56:57], v[90:91], v[56:57], v[58:59]
	v_pk_fma_f32 v[56:57], v[54:55], v[94:95], v[56:57]
	v_pk_mul_f32 v[58:59], v[56:57], s[0:1] op_sel_hi:[1,0]
	v_exp_f32_e32 v58, v58
	v_exp_f32_e32 v59, v59
	v_mov_b32_dpp v48, v52 row_ror:1 row_mask:0xf bank_mask:0xf
	v_mov_b32_dpp v49, v53 row_ror:1 row_mask:0xf bank_mask:0xf
	v_mov_b32_dpp v60, v52 row_ror:2 row_mask:0xf bank_mask:0xf
	v_mov_b32_dpp v61, v53 row_ror:2 row_mask:0xf bank_mask:0xf
	v_pk_add_f32 v[52:53], v[58:59], 1.0 op_sel_hi:[1,0]
	v_pk_mul_f32 v[50:51], v[50:51], v[100:101] op_sel_hi:[1,0]
	v_rcp_f32_e32 v52, v52
	v_rcp_f32_e32 v53, v53
	v_mov_b32_dpp v60, v50 row_shr:2 row_mask:0xf bank_mask:0xf
	v_mov_b32_dpp v61, v51 row_shr:2 row_mask:0xf bank_mask:0xf
	v_mov_b32_dpp v48, v50 row_shr:1 row_mask:0xf bank_mask:0xf
	v_mov_b32_dpp v49, v51 row_shr:1 row_mask:0xf bank_mask:0xf
	v_pk_fma_f32 v[58:59], v[70:71], v[60:61], v[66:67]
	v_pk_mul_f32 v[52:53], v[56:57], v[52:53]
	v_pk_fma_f32 v[48:49], v[78:79], v[48:49], v[58:59]
	v_cvt_pk_bf16_f32 v244, v36, v37
	v_pk_fma_f32 v[48:49], v[50:51], v[82:83], v[48:49]
	v_pk_mul_f32 v[46:47], v[46:47], v[98:99] op_sel_hi:[1,0]
	v_pk_mul_f32 v[48:49], v[48:49], v[52:53]
	v_cvt_pk_bf16_f32 v245, v48, v49
	v_mov_b32_dpp v52, v54 row_ror:2 row_mask:0xf bank_mask:0xf
	v_mov_b32_dpp v53, v55 row_ror:2 row_mask:0xf bank_mask:0xf
	v_mov_b32_dpp v48, v54 row_ror:1 row_mask:0xf bank_mask:0xf
	v_mov_b32_dpp v49, v55 row_ror:1 row_mask:0xf bank_mask:0xf
	v_mov_b32_dpp v52, v46 row_shr:2 row_mask:0xf bank_mask:0xf
	v_mov_b32_dpp v53, v47 row_shr:2 row_mask:0xf bank_mask:0xf
	v_mov_b32_dpp v48, v46 row_shr:1 row_mask:0xf bank_mask:0xf
	v_mov_b32_dpp v49, v47 row_shr:1 row_mask:0xf bank_mask:0xf
	v_pk_fma_f32 v[52:53], v[86:87], v[52:53], v[74:75]
	v_pk_fma_f32 v[48:49], v[90:91], v[48:49], v[52:53]
	v_pk_fma_f32 v[48:49], v[46:47], v[94:95], v[48:49]
	v_pk_mul_f32 v[52:53], v[48:49], s[0:1] op_sel_hi:[1,0]
	v_exp_f32_e32 v52, v52
	v_exp_f32_e32 v53, v53
	v_mov_b32_dpp v54, v50 row_ror:1 row_mask:0xf bank_mask:0xf
	v_mov_b32_dpp v55, v51 row_ror:1 row_mask:0xf bank_mask:0xf
	v_mov_b32_dpp v56, v50 row_ror:2 row_mask:0xf bank_mask:0xf
	v_mov_b32_dpp v57, v51 row_ror:2 row_mask:0xf bank_mask:0xf
	v_pk_add_f32 v[50:51], v[52:53], 1.0 op_sel_hi:[1,0]
	v_pk_mul_f32 v[42:43], v[42:43], v[98:99] op_sel_hi:[1,0]
	v_rcp_f32_e32 v50, v50
	v_rcp_f32_e32 v51, v51
	v_mov_b32_dpp v56, v42 row_shr:2 row_mask:0xf bank_mask:0xf
	v_mov_b32_dpp v57, v43 row_shr:2 row_mask:0xf bank_mask:0xf
	v_mov_b32_dpp v54, v42 row_shr:1 row_mask:0xf bank_mask:0xf
	v_mov_b32_dpp v55, v43 row_shr:1 row_mask:0xf bank_mask:0xf
	v_pk_fma_f32 v[52:53], v[70:71], v[56:57], v[66:67]
	v_pk_mul_f32 v[48:49], v[48:49], v[50:51]
	v_pk_fma_f32 v[52:53], v[78:79], v[54:55], v[52:53]
	v_pk_fma_f32 v[52:53], v[42:43], v[82:83], v[52:53]
	v_pk_mul_f32 v[48:49], v[52:53], v[48:49]
	v_cvt_pk_bf16_f32 v248, v40, v41
	v_pk_mul_f32 v[38:39], v[38:39], v[96:97] op_sel_hi:[1,0]
	v_cvt_pk_bf16_f32 v249, v48, v49
	v_mov_b32_dpp v50, v46 row_ror:2 row_mask:0xf bank_mask:0xf
	v_mov_b32_dpp v51, v47 row_ror:2 row_mask:0xf bank_mask:0xf
	v_mov_b32_dpp v48, v46 row_ror:1 row_mask:0xf bank_mask:0xf
	v_mov_b32_dpp v49, v47 row_ror:1 row_mask:0xf bank_mask:0xf
	v_mov_b32_dpp v50, v38 row_shr:2 row_mask:0xf bank_mask:0xf
	v_mov_b32_dpp v51, v39 row_shr:2 row_mask:0xf bank_mask:0xf
	v_mov_b32_dpp v48, v38 row_shr:1 row_mask:0xf bank_mask:0xf
	v_mov_b32_dpp v49, v39 row_shr:1 row_mask:0xf bank_mask:0xf
	v_pk_fma_f32 v[50:51], v[86:87], v[50:51], v[74:75]
	v_pk_fma_f32 v[48:49], v[90:91], v[48:49], v[50:51]
	v_pk_fma_f32 v[38:39], v[38:39], v[94:95], v[48:49]
	v_pk_mul_f32 v[48:49], v[38:39], s[0:1] op_sel_hi:[1,0]
	v_exp_f32_e32 v48, v48
	v_exp_f32_e32 v49, v49
	v_mov_b32_dpp v46, v42 row_ror:1 row_mask:0xf bank_mask:0xf
	v_mov_b32_dpp v47, v43 row_ror:1 row_mask:0xf bank_mask:0xf
	v_mov_b32_dpp v52, v42 row_ror:2 row_mask:0xf bank_mask:0xf
	v_mov_b32_dpp v53, v43 row_ror:2 row_mask:0xf bank_mask:0xf
	v_pk_add_f32 v[42:43], v[48:49], 1.0 op_sel_hi:[1,0]
	v_pk_mul_f32 v[34:35], v[34:35], v[96:97] op_sel_hi:[1,0]
	v_rcp_f32_e32 v42, v42
	v_rcp_f32_e32 v43, v43
	v_mov_b32_dpp v52, v34 row_shr:2 row_mask:0xf bank_mask:0xf
	v_mov_b32_dpp v53, v35 row_shr:2 row_mask:0xf bank_mask:0xf
	v_mov_b32_dpp v46, v34 row_shr:1 row_mask:0xf bank_mask:0xf
	v_mov_b32_dpp v47, v35 row_shr:1 row_mask:0xf bank_mask:0xf
	v_pk_fma_f32 v[48:49], v[70:71], v[52:53], v[66:67]
	v_pk_mul_f32 v[38:39], v[38:39], v[42:43]
	v_pk_fma_f32 v[46:47], v[78:79], v[46:47], v[48:49]
	v_cvt_pk_bf16_f32 v252, v44, v45
	v_pk_fma_f32 v[34:35], v[34:35], v[82:83], v[46:47]
	s_nop 0
	v_pk_mul_f32 v[34:35], v[34:35], v[38:39]
	s_nop 0
	v_cvt_pk_bf16_f32 v253, v34, v35
	v_mad_i64_i32 v[34:35], s[10:11], v103, s48, v[128:129]
	v_lshl_add_u64 v[64:65], v[34:35], 0, v[130:131]
	v_mad_i64_i32 v[32:33], s[10:11], v97, s48, v[128:129]
	v_lshl_add_u64 v[66:67], v[32:33], 0, v[130:131]
	v_mad_i64_i32 v[32:33], s[10:11], v99, s48, v[128:129]
	v_lshl_add_u64 v[68:69], v[32:33], 0, v[130:131]
	v_mad_i64_i32 v[32:33], s[10:11], v101, s48, v[128:129]
	v_lshl_add_u64 v[70:71], v[32:33], 0, v[130:131]
	v_pk_mul_f32 v[30:31], v[30:31], v[102:103] op_sel_hi:[1,0]
	v_pk_mul_f32 v[22:23], v[22:23], v[100:101] op_sel_hi:[1,0]
	s_nop 0
	v_mov_b32_dpp v114, v30 row_ror:2 row_mask:0xf bank_mask:0xf
	v_mov_b32_dpp v115, v31 row_ror:2 row_mask:0xf bank_mask:0xf
	v_mov_b32_dpp v112, v30 row_ror:1 row_mask:0xf bank_mask:0xf
	v_mov_b32_dpp v113, v31 row_ror:1 row_mask:0xf bank_mask:0xf
	v_mov_b32_dpp v114, v22 row_shr:2 row_mask:0xf bank_mask:0xf
	v_mov_b32_dpp v115, v23 row_shr:2 row_mask:0xf bank_mask:0xf
	ds_read_b128 v[40:43], v200 offset:16
	ds_read_b128 v[52:55], v200 offset:144
	ds_read_b128 v[56:59], v200 offset:272
	ds_read_b128 v[60:63], v200 offset:400
	ds_read_b128 v[32:35], v200 offset:528
	ds_read_b128 v[36:39], v200 offset:656
	ds_read_b128 v[44:47], v200 offset:784
	ds_read_b128 v[48:51], v200 offset:912
	v_mov_b32_dpp v112, v22 row_shr:1 row_mask:0xf bank_mask:0xf
	v_mov_b32_dpp v113, v23 row_shr:1 row_mask:0xf bank_mask:0xf
	s_waitcnt lgkmcnt(6)
; #define LAS __attribute__((address_space(3)))
;     DI void operator()(const AccT& acc, const Unit& u, int wr, int wc, int fr, int fq) const {
;     ...
;                     const f32x2 bg = *(const LAS f32x2*)(P + lc + 2 * jp), g0 = *(const LAS f32x2*)(P + 32 + lc + 2 * jp), g1 = *(const LAS f32x2*)(P + 64 + lc + 2 * jp), g2 = *(const LAS f32x2*)(P + 96 + lc + 2 * jp);
;                     const f32x2 bv = *(const LAS f32x2*)(P + 128 + lc + 2 * jp), v0 = *(const LAS f32x2*)(P + 160 + lc + 2 * jp), v1 = *(const LAS f32x2*)(P + 192 + lc + 2 * jp), v2 = *(const LAS f32x2*)(P + 224 + lc + 2 * jp);
;                     f32x2 G[4], V[4];
; #pragma unroll
;                     for (int m = 0; m < 4; ++m) { G[m] = (f32x2){acc[ai][0][m][n][2 * jp], acc[ai][0][m][n][2 * jp + 1]} * rs[m]; V[m] = (f32x2){acc[ai][1][m][n][2 * jp], acc[ai][1][m][n][2 * jp + 1]} * rs[m]; }
; #pragma unroll
;                     for (int m = 0; m < 4; ++m) {
;                         const f32x2 zz = {0.f, 0.f}; const f32x2 Gp = m ? G[m - 1] : zz, Vp = m ? V[m - 1] : zz;
;                         const f32x2 gp1 = {dpp_prev1(G[m].x, Gp.x), dpp_prev1(G[m].y, Gp.y)}, gp2 = {dpp_prev2(G[m].x, Gp.x), dpp_prev2(G[m].y, Gp.y)};
;                         const f32x2 vp1 = {dpp_prev1(V[m].x, Vp.x), dpp_prev1(V[m].y, Vp.y)}, vp2 = {dpp_prev2(V[m].x, Vp.x), dpp_prev2(V[m].y, Vp.y)};
;                         const f32x2 gc = bg + g0 * gp2 + g1 * gp1 + g2 * G[m];
;                         const f32x2 vc = bv + v0 * vp2 + v1 * vp1 + v2 * V[m];
;                         const f32x2 xe = gc * (-LOG2E);
;                         f32x2 dn = {__builtin_amdgcn_exp2f(xe.x), __builtin_amdgcn_exp2f(xe.y)}; dn = dn + 1.0f;
;                         const f32x2 rc = {__builtin_amdgcn_rcpf(dn.x), __builtin_amdgcn_rcpf(dn.y)};
;                         const f32x2 rr = gc * rc * vc;
	v_pk_fma_f32 v[114:115], v[54:55], v[114:115], v[42:43]
	v_pk_mul_f32 v[28:29], v[28:29], v[102:103] op_sel_hi:[1,0]
	v_pk_mul_f32 v[24:25], v[24:25], v[102:103] op_sel_hi:[1,0]
	v_pk_mul_f32 v[20:21], v[20:21], v[100:101] op_sel_hi:[1,0]
	v_pk_mul_f32 v[16:17], v[16:17], v[100:101] op_sel_hi:[1,0]
	v_pk_mul_f32 v[26:27], v[26:27], v[102:103] op_sel_hi:[1,0]
	v_pk_mul_f32 v[100:101], v[18:19], v[100:101] op_sel_hi:[1,0]
	v_mov_b32_e32 v102, v183
	v_mov_b32_e32 v103, v183
	s_waitcnt lgkmcnt(5)
	v_pk_fma_f32 v[112:113], v[58:59], v[112:113], v[114:115]
	v_pk_mul_f32 v[76:77], v[12:13], v[98:99] op_sel_hi:[1,0]
	v_pk_mul_f32 v[72:73], v[8:9], v[98:99] op_sel_hi:[1,0]
	v_pk_mul_f32 v[14:15], v[14:15], v[98:99] op_sel_hi:[1,0]
	v_pk_mul_f32 v[10:11], v[10:11], v[98:99] op_sel_hi:[1,0]
	v_mov_b32_e32 v98, v181
	v_mov_b32_e32 v99, v181
	v_mov_b32_dpp v102, v30 row_shr:2 row_mask:0xf bank_mask:0xf
	v_mov_b32_dpp v103, v31 row_shr:2 row_mask:0xf bank_mask:0xf
	v_mov_b32_dpp v18, v22 row_ror:1 row_mask:0xf bank_mask:0xf
	v_mov_b32_dpp v19, v23 row_ror:1 row_mask:0xf bank_mask:0xf
	v_mov_b32_dpp v120, v22 row_ror:2 row_mask:0xf bank_mask:0xf
	v_mov_b32_dpp v121, v23 row_ror:2 row_mask:0xf bank_mask:0xf
	s_waitcnt lgkmcnt(4)
	v_pk_fma_f32 v[22:23], v[22:23], v[62:63], v[112:113]
	v_mov_b32_dpp v98, v30 row_shr:1 row_mask:0xf bank_mask:0xf
	v_mov_b32_dpp v99, v31 row_shr:1 row_mask:0xf bank_mask:0xf
	v_pk_mul_f32 v[112:113], v[22:23], s[0:1] op_sel_hi:[1,0]
	v_pk_fma_f32 v[102:103], v[54:55], v[102:103], v[42:43]
	v_exp_f32_e32 v112, v112
	v_exp_f32_e32 v113, v113
	v_pk_fma_f32 v[98:99], v[58:59], v[98:99], v[102:103]
	v_pk_fma_f32 v[30:31], v[30:31], v[62:63], v[98:99]
	v_pk_mul_f32 v[98:99], v[30:31], s[0:1] op_sel_hi:[1,0]
	v_pk_add_f32 v[112:113], v[112:113], 1.0 op_sel_hi:[1,0]
	v_exp_f32_e32 v98, v98
	v_exp_f32_e32 v99, v99
	v_mov_b32_dpp v118, v26 row_ror:2 row_mask:0xf bank_mask:0xf
	v_mov_b32_dpp v119, v27 row_ror:2 row_mask:0xf bank_mask:0xf
	v_rcp_f32_e32 v112, v112
	v_rcp_f32_e32 v113, v113
	v_mov_b32_dpp v116, v26 row_ror:1 row_mask:0xf bank_mask:0xf
	v_mov_b32_dpp v117, v27 row_ror:1 row_mask:0xf bank_mask:0xf
	v_mov_b32_dpp v118, v100 row_shr:2 row_mask:0xf bank_mask:0xf
	v_mov_b32_dpp v119, v101 row_shr:2 row_mask:0xf bank_mask:0xf
	v_mov_b32_dpp v116, v100 row_shr:1 row_mask:0xf bank_mask:0xf
	v_mov_b32_dpp v117, v101 row_shr:1 row_mask:0xf bank_mask:0xf
	s_waitcnt lgkmcnt(2)
	v_pk_fma_f32 v[114:115], v[38:39], v[118:119], v[34:35]
	v_pk_add_f32 v[98:99], v[98:99], 1.0 op_sel_hi:[1,0]
	v_mov_b32_e32 v182, v183
	s_waitcnt lgkmcnt(1)
	v_pk_fma_f32 v[114:115], v[46:47], v[116:117], v[114:115]
	v_rcp_f32_e32 v98, v98
	v_rcp_f32_e32 v99, v99
	v_pk_mul_f32 v[86:87], v[4:5], v[96:97] op_sel_hi:[1,0]
	v_mov_b32_e32 v12, v183
	v_mov_b32_e32 v13, v183
	v_mov_b32_e32 v4, v183
	v_mov_b32_e32 v5, v183
	v_mov_b32_e32 v180, v181
	v_mov_b32_dpp v182, v26 row_shr:2 row_mask:0xf bank_mask:0xf
	v_mov_b32_dpp v183, v27 row_shr:2 row_mask:0xf bank_mask:0xf
	v_mov_b32_dpp v122, v100 row_ror:1 row_mask:0xf bank_mask:0xf
	v_mov_b32_dpp v123, v101 row_ror:1 row_mask:0xf bank_mask:0xf
	v_mov_b32_dpp v124, v100 row_ror:2 row_mask:0xf bank_mask:0xf
	v_mov_b32_dpp v125, v101 row_ror:2 row_mask:0xf bank_mask:0xf
	s_waitcnt lgkmcnt(0)
	v_pk_fma_f32 v[100:101], v[100:101], v[50:51], v[114:115]
	v_pk_mul_f32 v[22:23], v[22:23], v[112:113]
	v_pk_mul_f32 v[84:85], v[0:1], v[96:97] op_sel_hi:[1,0]
	v_mov_b32_e32 v8, v181
	v_mov_b32_e32 v9, v181
	v_mov_b32_e32 v0, v181
	v_mov_b32_e32 v1, v181
	v_mov_b32_dpp v180, v26 row_shr:1 row_mask:0xf bank_mask:0xf
	v_mov_b32_dpp v181, v27 row_shr:1 row_mask:0xf bank_mask:0xf
	v_pk_mul_f32 v[22:23], v[100:101], v[22:23]
	v_pk_fma_f32 v[100:101], v[38:39], v[182:183], v[34:35]
	v_mov_b32_dpp v106, v76 row_ror:2 row_mask:0xf bank_mask:0xf
	v_mov_b32_dpp v107, v77 row_ror:2 row_mask:0xf bank_mask:0xf
	v_pk_fma_f32 v[100:101], v[46:47], v[180:181], v[100:101]
	v_mov_b32_dpp v104, v76 row_ror:1 row_mask:0xf bank_mask:0xf
	v_mov_b32_dpp v105, v77 row_ror:1 row_mask:0xf bank_mask:0xf
	v_mov_b32_dpp v106, v86 row_shr:2 row_mask:0xf bank_mask:0xf
	v_mov_b32_dpp v107, v87 row_shr:2 row_mask:0xf bank_mask:0xf
	v_pk_fma_f32 v[26:27], v[26:27], v[50:51], v[100:101]
	v_pk_mul_f32 v[30:31], v[30:31], v[98:99]
	v_mov_b32_dpp v104, v86 row_shr:1 row_mask:0xf bank_mask:0xf
	v_mov_b32_dpp v105, v87 row_shr:1 row_mask:0xf bank_mask:0xf
	v_pk_mul_f32 v[26:27], v[26:27], v[30:31]
	v_pk_fma_f32 v[30:31], v[52:53], v[106:107], v[40:41]
	v_mov_b32_dpp v12, v28 row_shr:2 row_mask:0xf bank_mask:0xf
	v_pk_fma_f32 v[30:31], v[56:57], v[104:105], v[30:31]
	v_mov_b32_dpp v13, v29 row_shr:2 row_mask:0xf bank_mask:0xf
	v_pk_fma_f32 v[30:31], v[86:87], v[60:61], v[30:31]
	v_pk_mul_f32 v[86:87], v[30:31], s[0:1] op_sel_hi:[1,0]
	v_mov_b32_dpp v8, v28 row_shr:1 row_mask:0xf bank_mask:0xf
	v_mov_b32_dpp v9, v29 row_shr:1 row_mask:0xf bank_mask:0xf
	v_mov_b32_dpp v92, v20 row_ror:2 row_mask:0xf bank_mask:0xf
	v_mov_b32_dpp v93, v21 row_ror:2 row_mask:0xf bank_mask:0xf
	v_exp_f32_e32 v86, v86
	v_exp_f32_e32 v87, v87
	v_pk_fma_f32 v[12:13], v[52:53], v[12:13], v[40:41]
	v_mov_b32_dpp v88, v20 row_ror:1 row_mask:0xf bank_mask:0xf
	v_mov_b32_dpp v89, v21 row_ror:1 row_mask:0xf bank_mask:0xf
	v_mov_b32_dpp v92, v76 row_shr:2 row_mask:0xf bank_mask:0xf
	v_mov_b32_dpp v93, v77 row_shr:2 row_mask:0xf bank_mask:0xf
	v_mov_b32_dpp v120, v14 row_shr:2 row_mask:0xf bank_mask:0xf
	v_mov_b32_dpp v121, v15 row_shr:2 row_mask:0xf bank_mask:0xf
	v_pk_fma_f32 v[8:9], v[56:57], v[8:9], v[12:13]
	v_mov_b32_dpp v88, v76 row_shr:1 row_mask:0xf bank_mask:0xf
;     DI void operator()(const AccT& acc, const Unit& u, int wr, int wc, int fr, int fq) const {
;     ...
;                     for (int m = 0; m < 4; ++m) {
;                         const f32x2 zz = {0.f, 0.f}; const f32x2 Gp = m ? G[m - 1] : zz, Vp = m ? V[m - 1] : zz;
;                         const f32x2 gp1 = {dpp_prev1(G[m].x, Gp.x), dpp_prev1(G[m].y, Gp.y)}, gp2 = {dpp_prev2(G[m].x, Gp.x), dpp_prev2(G[m].y, Gp.y)};
;                         const f32x2 vp1 = {dpp_prev1(V[m].x, Vp.x), dpp_prev1(V[m].y, Vp.y)}, vp2 = {dpp_prev2(V[m].x, Vp.x), dpp_prev2(V[m].y, Vp.y)};
;                         const f32x2 gc = bg + g0 * gp2 + g1 * gp1 + g2 * G[m];
;                         const f32x2 vc = bv + v0 * vp2 + v1 * vp1 + v2 * V[m];
;                         const f32x2 xe = gc * (-LOG2E);
;                         f32x2 dn = {__builtin_amdgcn_exp2f(xe.x), __builtin_amdgcn_exp2f(xe.y)}; dn = dn + 1.0f;
;                         const f32x2 rc = {__builtin_amdgcn_rcpf(dn.x), __builtin_amdgcn_rcpf(dn.y)};
;                         const f32x2 rr = gc * rc * vc;
	v_mov_b32_dpp v89, v77 row_shr:1 row_mask:0xf bank_mask:0xf
	v_mov_b32_dpp v18, v14 row_shr:1 row_mask:0xf bank_mask:0xf
	v_mov_b32_dpp v19, v15 row_shr:1 row_mask:0xf bank_mask:0xf
	v_pk_fma_f32 v[120:121], v[54:55], v[120:121], v[42:43]
	v_pk_fma_f32 v[92:93], v[52:53], v[92:93], v[40:41]
	v_pk_fma_f32 v[8:9], v[28:29], v[60:61], v[8:9]
	v_pk_fma_f32 v[18:19], v[58:59], v[18:19], v[120:121]
	v_pk_fma_f32 v[88:89], v[56:57], v[88:89], v[92:93]
	v_pk_mul_f32 v[12:13], v[8:9], s[0:1] op_sel_hi:[1,0]
	v_pk_fma_f32 v[18:19], v[14:15], v[62:63], v[18:19]
	v_pk_add_f32 v[86:87], v[86:87], 1.0 op_sel_hi:[1,0]
	v_pk_fma_f32 v[76:77], v[76:77], v[60:61], v[88:89]
	v_exp_f32_e32 v12, v12
	v_exp_f32_e32 v13, v13
	v_mov_b32_dpp v110, v72 row_ror:2 row_mask:0xf bank_mask:0xf
	v_mov_b32_dpp v111, v73 row_ror:2 row_mask:0xf bank_mask:0xf
	v_pk_mul_f32 v[120:121], v[18:19], s[0:1] op_sel_hi:[1,0]
	v_rcp_f32_e32 v86, v86
	v_rcp_f32_e32 v87, v87
	v_pk_mul_f32 v[88:89], v[76:77], s[0:1] op_sel_hi:[1,0]
	v_mov_b32_dpp v108, v72 row_ror:1 row_mask:0xf bank_mask:0xf
	v_mov_b32_dpp v109, v73 row_ror:1 row_mask:0xf bank_mask:0xf
	v_mov_b32_dpp v110, v84 row_shr:2 row_mask:0xf bank_mask:0xf
	v_mov_b32_dpp v111, v85 row_shr:2 row_mask:0xf bank_mask:0xf
	v_exp_f32_e32 v120, v120
	v_exp_f32_e32 v121, v121
	v_exp_f32_e32 v88, v88
	v_exp_f32_e32 v89, v89
	v_mov_b32_dpp v108, v84 row_shr:1 row_mask:0xf bank_mask:0xf
	v_mov_b32_dpp v109, v85 row_shr:1 row_mask:0xf bank_mask:0xf
	v_pk_mul_f32 v[2:3], v[2:3], v[96:97] op_sel_hi:[1,0]
	v_pk_mul_f32 v[6:7], v[6:7], v[96:97] op_sel_hi:[1,0]
	v_pk_fma_f32 v[96:97], v[36:37], v[110:111], v[32:33]
	v_pk_add_f32 v[12:13], v[12:13], 1.0 op_sel_hi:[1,0]
	v_pk_fma_f32 v[96:97], v[44:45], v[108:109], v[96:97]
	v_pk_mul_f32 v[30:31], v[30:31], v[86:87]
	v_pk_fma_f32 v[84:85], v[84:85], v[48:49], v[96:97]
	v_rcp_f32_e32 v12, v12
	v_rcp_f32_e32 v13, v13
	v_mov_b32_dpp v4, v24 row_shr:2 row_mask:0xf bank_mask:0xf
	v_mov_b32_dpp v5, v25 row_shr:2 row_mask:0xf bank_mask:0xf
	v_pk_add_f32 v[120:121], v[120:121], 1.0 op_sel_hi:[1,0]
	v_pk_mul_f32 v[30:31], v[84:85], v[30:31]
	v_pk_add_f32 v[84:85], v[88:89], 1.0 op_sel_hi:[1,0]
	v_mov_b32_dpp v0, v24 row_shr:1 row_mask:0xf bank_mask:0xf
	v_mov_b32_dpp v1, v25 row_shr:1 row_mask:0xf bank_mask:0xf
	v_mov_b32_dpp v94, v16 row_ror:2 row_mask:0xf bank_mask:0xf
	v_mov_b32_dpp v95, v17 row_ror:2 row_mask:0xf bank_mask:0xf
	v_rcp_f32_e32 v120, v120
	v_rcp_f32_e32 v121, v121
	v_rcp_f32_e32 v84, v84
	v_rcp_f32_e32 v85, v85
	v_pk_fma_f32 v[4:5], v[36:37], v[4:5], v[32:33]
	v_mov_b32_dpp v90, v16 row_ror:1 row_mask:0xf bank_mask:0xf
	v_mov_b32_dpp v91, v17 row_ror:1 row_mask:0xf bank_mask:0xf
	v_mov_b32_dpp v94, v72 row_shr:2 row_mask:0xf bank_mask:0xf
	v_mov_b32_dpp v95, v73 row_shr:2 row_mask:0xf bank_mask:0xf
	v_mov_b32_dpp v124, v10 row_shr:2 row_mask:0xf bank_mask:0xf
	v_mov_b32_dpp v125, v11 row_shr:2 row_mask:0xf bank_mask:0xf
	v_pk_fma_f32 v[0:1], v[44:45], v[0:1], v[4:5]
	v_mov_b32_dpp v90, v72 row_shr:1 row_mask:0xf bank_mask:0xf
	v_mov_b32_dpp v91, v73 row_shr:1 row_mask:0xf bank_mask:0xf
	v_mov_b32_dpp v122, v10 row_shr:1 row_mask:0xf bank_mask:0xf
	v_mov_b32_dpp v123, v11 row_shr:1 row_mask:0xf bank_mask:0xf
	v_pk_fma_f32 v[124:125], v[38:39], v[124:125], v[34:35]
	v_pk_fma_f32 v[86:87], v[36:37], v[94:95], v[32:33]
	v_pk_fma_f32 v[0:1], v[24:25], v[48:49], v[0:1]
	v_pk_mul_f32 v[4:5], v[8:9], v[12:13]
	v_pk_fma_f32 v[122:123], v[46:47], v[122:123], v[124:125]
	v_pk_fma_f32 v[86:87], v[44:45], v[90:91], v[86:87]
	v_pk_mul_f32 v[0:1], v[0:1], v[4:5]
	v_mov_b32_dpp v78, v28 row_ror:2 row_mask:0xf bank_mask:0xf
	v_mov_b32_dpp v79, v29 row_ror:2 row_mask:0xf bank_mask:0xf
	v_pk_fma_f32 v[122:123], v[10:11], v[50:51], v[122:123]
	v_pk_mul_f32 v[18:19], v[18:19], v[120:121]
; DI unsigned pk2(float lo, float hi) { f32x2 v = {lo, hi}; bf16x2_t b = __builtin_convertvector(v, bf16x2_t); return __builtin_bit_cast(unsigned, b); }
;     DI void operator()(const AccT& acc, const Unit& u, int wr, int wc, int fr, int fq) const {
;     ...
;                     for (int m = 0; m < 4; ++m) {
;                         const f32x2 zz = {0.f, 0.f}; const f32x2 Gp = m ? G[m - 1] : zz, Vp = m ? V[m - 1] : zz;
;                         const f32x2 gp1 = {dpp_prev1(G[m].x, Gp.x), dpp_prev1(G[m].y, Gp.y)}, gp2 = {dpp_prev2(G[m].x, Gp.x), dpp_prev2(G[m].y, Gp.y)};
;                         const f32x2 vp1 = {dpp_prev1(V[m].x, Vp.x), dpp_prev1(V[m].y, Vp.y)}, vp2 = {dpp_prev2(V[m].x, Vp.x), dpp_prev2(V[m].y, Vp.y)};
;                         const f32x2 gc = bg + g0 * gp2 + g1 * gp1 + g2 * G[m];
;                         const f32x2 vc = bv + v0 * vp2 + v1 * vp1 + v2 * V[m];
;                         const f32x2 xe = gc * (-LOG2E);
;                         f32x2 dn = {__builtin_amdgcn_exp2f(xe.x), __builtin_amdgcn_exp2f(xe.y)}; dn = dn + 1.0f;
;                         const f32x2 rc = {__builtin_amdgcn_rcpf(dn.x), __builtin_amdgcn_rcpf(dn.y)};
;                         const f32x2 rr = gc * rc * vc;
;                         wpk[m][jp] = pk2(rr.x, rr.y); }
;                 }
; #pragma unroll
;                 for (int m = 0; m < 4; ++m) { const int row = m ? tok0 + 16 * m : row0;
;                     *(u32x2*)(ACT + (size_t)row * 2816 + cl + 4 * n) = (u32x2){wpk[m][0], wpk[m][1]}; }
	v_cvt_pk_bf16_f32 v239, v26, v27
	v_pk_fma_f32 v[72:73], v[72:73], v[48:49], v[86:87]
	v_pk_mul_f32 v[76:77], v[76:77], v[84:85]
	v_cvt_pk_bf16_f32 v238, v0, v1
	v_mov_b32_dpp v4, v14 row_ror:2 row_mask:0xf bank_mask:0xf
	v_mov_b32_dpp v5, v15 row_ror:2 row_mask:0xf bank_mask:0xf
	v_mov_b32_dpp v74, v28 row_ror:1 row_mask:0xf bank_mask:0xf
	v_mov_b32_dpp v75, v29 row_ror:1 row_mask:0xf bank_mask:0xf
	v_mov_b32_dpp v78, v20 row_shr:2 row_mask:0xf bank_mask:0xf
	v_mov_b32_dpp v79, v21 row_shr:2 row_mask:0xf bank_mask:0xf
	v_pk_mul_f32 v[18:19], v[122:123], v[18:19]
	v_pk_mul_f32 v[72:73], v[72:73], v[76:77]
	v_mov_b32_dpp v0, v14 row_ror:1 row_mask:0xf bank_mask:0xf
	v_mov_b32_dpp v1, v15 row_ror:1 row_mask:0xf bank_mask:0xf
	v_mov_b32_dpp v4, v6 row_shr:2 row_mask:0xf bank_mask:0xf
	v_mov_b32_dpp v5, v7 row_shr:2 row_mask:0xf bank_mask:0xf
	v_mov_b32_dpp v74, v20 row_shr:1 row_mask:0xf bank_mask:0xf
	v_mov_b32_dpp v75, v21 row_shr:1 row_mask:0xf bank_mask:0xf
	v_cvt_pk_bf16_f32 v251, v18, v19
	v_cvt_pk_bf16_f32 v250, v72, v73
	v_pk_fma_f32 v[72:73], v[52:53], v[78:79], v[40:41]
	v_mov_b32_dpp v0, v6 row_shr:1 row_mask:0xf bank_mask:0xf
	v_mov_b32_dpp v1, v7 row_shr:1 row_mask:0xf bank_mask:0xf
	v_pk_fma_f32 v[4:5], v[54:55], v[4:5], v[42:43]
	v_pk_fma_f32 v[72:73], v[56:57], v[74:75], v[72:73]
	v_pk_fma_f32 v[0:1], v[58:59], v[0:1], v[4:5]
	v_pk_fma_f32 v[20:21], v[20:21], v[60:61], v[72:73]
	v_pk_fma_f32 v[0:1], v[6:7], v[62:63], v[0:1]
	v_pk_mul_f32 v[72:73], v[20:21], s[0:1] op_sel_hi:[1,0]
	v_pk_mul_f32 v[4:5], v[0:1], s[0:1] op_sel_hi:[1,0]
	v_exp_f32_e32 v72, v72
	v_exp_f32_e32 v73, v73
	v_exp_f32_e32 v4, v4
	v_exp_f32_e32 v5, v5
	v_pk_add_f32 v[72:73], v[72:73], 1.0 op_sel_hi:[1,0]
	v_pk_add_f32 v[4:5], v[4:5], 1.0 op_sel_hi:[1,0]
	v_mov_b32_dpp v82, v24 row_ror:2 row_mask:0xf bank_mask:0xf
	v_mov_b32_dpp v83, v25 row_ror:2 row_mask:0xf bank_mask:0xf
	v_rcp_f32_e32 v72, v72
	v_rcp_f32_e32 v73, v73
	v_mov_b32_dpp v12, v10 row_ror:2 row_mask:0xf bank_mask:0xf
	v_mov_b32_dpp v13, v11 row_ror:2 row_mask:0xf bank_mask:0xf
	v_rcp_f32_e32 v4, v4
	v_rcp_f32_e32 v5, v5
	v_mov_b32_dpp v80, v24 row_ror:1 row_mask:0xf bank_mask:0xf
	v_mov_b32_dpp v81, v25 row_ror:1 row_mask:0xf bank_mask:0xf
	v_mov_b32_dpp v82, v16 row_shr:2 row_mask:0xf bank_mask:0xf
	v_mov_b32_dpp v83, v17 row_shr:2 row_mask:0xf bank_mask:0xf
	v_mov_b32_dpp v8, v10 row_ror:1 row_mask:0xf bank_mask:0xf
	v_mov_b32_dpp v9, v11 row_ror:1 row_mask:0xf bank_mask:0xf
	v_mov_b32_dpp v12, v2 row_shr:2 row_mask:0xf bank_mask:0xf
	v_mov_b32_dpp v13, v3 row_shr:2 row_mask:0xf bank_mask:0xf
	v_mov_b32_dpp v80, v16 row_shr:1 row_mask:0xf bank_mask:0xf
	v_mov_b32_dpp v81, v17 row_shr:1 row_mask:0xf bank_mask:0xf
	v_pk_fma_f32 v[74:75], v[36:37], v[82:83], v[32:33]
	v_mov_b32_dpp v8, v2 row_shr:1 row_mask:0xf bank_mask:0xf
	v_mov_b32_dpp v9, v3 row_shr:1 row_mask:0xf bank_mask:0xf
	v_pk_fma_f32 v[6:7], v[38:39], v[12:13], v[34:35]
	v_pk_fma_f32 v[74:75], v[44:45], v[80:81], v[74:75]
	v_pk_fma_f32 v[6:7], v[46:47], v[8:9], v[6:7]
	v_pk_fma_f32 v[16:17], v[16:17], v[48:49], v[74:75]
	v_pk_mul_f32 v[20:21], v[20:21], v[72:73]
	v_pk_fma_f32 v[2:3], v[2:3], v[50:51], v[6:7]
	v_pk_mul_f32 v[0:1], v[0:1], v[4:5]
	v_pk_mul_f32 v[16:17], v[16:17], v[20:21]
	v_pk_mul_f32 v[0:1], v[2:3], v[0:1]
	v_cvt_pk_bf16_f32 v247, v22, v23
	v_cvt_pk_bf16_f32 v254, v30, v31
	v_cvt_pk_bf16_f32 v246, v16, v17
	v_cvt_pk_bf16_f32 v255, v0, v1
	global_store_dwordx4 v[64:65], v[236:239], off
	global_store_dwordx4 v[66:67], v[244:247], off
	global_store_dwordx4 v[68:69], v[248:251], off
	global_store_dwordx4 v[70:71], v[252:255], off
	s_and_b64 vcc, exec, s[8:9]
	s_mov_b64 s[8:9], -1
	s_cbranch_vccnz .LBB0_1108
	s_andn2_b64 vcc, exec, s[2:3]
	s_cbranch_vccnz .LBB0_1107
	s_barrier
	s_branch .LBB0_1107

;     DI void operator()(const AccT& acc, const Unit& u, int wr, int wc, int fr, int fq) const {
;         const int cl = u.pn * 128 + wc * 32 + 8 * fq;
;         LAS float* P = (LAS float*)(plds + (wr * 4 + wc) * 1024);
;         { const int lane = fq * 16 + fr, kind = lane >> 3, c4 = 4 * (lane & 7), k3 = kind & 3;
;           const float* src = (k3 == 0 ? cb : cw + (k3 - 1) * 5632) + (kind >= 4 ? 2816 : 0) + u.pn * 128 + wc * 32 + c4;
;           *(LAS f32x4*)(P + kind * 32 + c4) = *(const f32x4*)src; }
; #pragma unroll
;         for (int ai = 0; ai < 2; ++ai) {
;             const int tok0 = u.pm * 248 + 62 * (2 * ai + wr) - 2 + fr;
;             float rs[4];
; #pragma unroll
;             for (int m = 0; m < 4; ++m) { const int t = tok0 + 16 * m; const int tc = t < 0 ? 0 : (t >= S ? S - 1 : t); const float r = rs_from_ss(rowss[tc]); rs[m] = t < 0 ? 0.f : r; }
;             const int row0 = fr < 2 ? (S + 236 + fr) : tok0;
; #pragma unroll
;             for (int n = 0; n < 2; ++n) {
;                 const int lc = 8 * fq + 4 * n;
;                 unsigned wpk[4][2];
; #pragma unroll
;                 for (int jp = 0; jp < 2; ++jp) {
;                     const f32x2 bg = *(const LAS f32x2*)(P + lc + 2 * jp), g0 = *(const LAS f32x2*)(P + 32 + lc + 2 * jp), g1 = *(const LAS f32x2*)(P + 64 + lc + 2 * jp), g2 = *(const LAS f32x2*)(P + 96 + lc + 2 * jp);
;                     const f32x2 bv = *(const LAS f32x2*)(P + 128 + lc + 2 * jp), v0 = *(const LAS f32x2*)(P + 160 + lc + 2 * jp), v1 = *(const LAS f32x2*)(P + 192 + lc + 2 * jp), v2 = *(const LAS f32x2*)(P + 224 + lc + 2 * jp);
;                     f32x2 G[4], V[4];
; #pragma unroll
;                     for (int m = 0; m < 4; ++m) { G[m] = (f32x2){acc[ai][0][m][n][2 * jp], acc[ai][0][m][n][2 * jp + 1]} * rs[m]; V[m] = (f32x2){acc[ai][1][m][n][2 * jp], acc[ai][1][m][n][2 * jp + 1]} * rs[m]; }
; #pragma unroll
;                     for (int m = 0; m < 4; ++m) {
;                         const f32x2 zz = {0.f, 0.f}; const f32x2 Gp = m ? G[m - 1] : zz, Vp = m ? V[m - 1] : zz;
;                         const f32x2 gp1 = {dpp_prev1(G[m].x, Gp.x), dpp_prev1(G[m].y, Gp.y)}, gp2 = {dpp_prev2(G[m].x, Gp.x), dpp_prev2(G[m].y, Gp.y)};
;                         const f32x2 vp1 = {dpp_prev1(V[m].x, Vp.x), dpp_prev1(V[m].y, Vp.y)}, vp2 = {dpp_prev2(V[m].x, Vp.x), dpp_prev2(V[m].y, Vp.y)};
.LBB0_1831:
	s_lshl_b32 s8, s58, 7
	s_ashr_i32 s9, s8, 31
	v_lshl_add_u64 v[128:129], s[8:9], 2, v[168:169]
	s_mul_i32 s9, s57, 0xf8
	v_add_u32_e32 v197, s9, v170
	v_med3_i32 v132, v197, 0, s51
	v_lshlrev_b32_e32 v132, 3, v132
	global_load_dwordx2 v[180:181], v132, s[18:19]
	v_add_u32_e32 v198, 16, v197
	v_med3_i32 v132, v198, 0, s51
	v_add_u32_e32 v199, 32, v197
	v_add_u32_e32 v200, 48, v197
	v_lshlrev_b32_e32 v132, 3, v132
	v_med3_i32 v133, v199, 0, s51
	v_med3_i32 v134, v200, 0, s51
	global_load_dwordx4 v[128:131], v[128:129], off
	v_lshlrev_b32_e32 v133, 3, v133
	v_lshlrev_b32_e32 v134, 3, v134
	global_load_dwordx2 v[182:183], v132, s[18:19]
	global_load_dwordx2 v[202:203], v133, s[18:19]
	global_load_dwordx2 v[204:205], v134, s[18:19]
	v_or_b32_e32 v188, s8, v187
	v_ashrrev_i32_e32 v189, 31, v188
	v_cndmask_b32_e64 v201, v197, v190, s[4:5]
	s_waitcnt vmcnt(0)
	v_add_u32_e32 v250, 0x7c, v197
	v_med3_i32 v250, v250, 0, s51
	v_lshlrev_b32_e32 v250, 3, v250
	global_load_dwordx2 v[242:243], v250, s[18:19]
	v_add_u32_e32 v250, 0x8c, v197
	v_med3_i32 v250, v250, 0, s51
	v_lshlrev_b32_e32 v250, 3, v250
	global_load_dwordx2 v[244:245], v250, s[18:19]
	v_add_u32_e32 v250, 0x9c, v197
	v_med3_i32 v250, v250, 0, s51
	v_lshlrev_b32_e32 v250, 3, v250
	global_load_dwordx2 v[246:247], v250, s[18:19]
	v_add_u32_e32 v250, 0xac, v197
	v_med3_i32 v250, v250, 0, s51
	v_lshlrev_b32_e32 v250, 3, v250
	global_load_dwordx2 v[248:249], v250, s[18:19]
	v_ffbh_u32_e32 v184, v181
	v_min_u32_e32 v184, 32, v184
	v_lshlrev_b64 v[180:181], v184, v[180:181]
	v_min_u32_e32 v180, 1, v180
	v_or_b32_e32 v180, v181, v180
	v_cvt_f32_u32_e32 v180, v180
	v_sub_u32_e32 v184, 32, v184
	ds_write_b128 v191, v[128:131]
	v_ffbh_u32_e32 v186, v183
	v_ffbh_u32_e32 v206, v203
	v_min_u32_e32 v186, 32, v186
	v_ffbh_u32_e32 v207, v205
	v_min_u32_e32 v206, 32, v206
	v_lshlrev_b64 v[182:183], v186, v[182:183]
	v_min_u32_e32 v207, 32, v207
	v_lshlrev_b64 v[202:203], v206, v[202:203]
	v_min_u32_e32 v181, 1, v182
	v_lshlrev_b64 v[204:205], v207, v[204:205]
	v_min_u32_e32 v182, 1, v202
	v_or_b32_e32 v181, v183, v181
	v_min_u32_e32 v202, 1, v204
	v_or_b32_e32 v182, v203, v182
	v_cvt_f32_u32_e32 v181, v181
	v_or_b32_e32 v183, v205, v202
	v_cvt_f32_u32_e32 v182, v182
	v_cvt_f32_u32_e32 v183, v183
	v_sub_u32_e32 v186, 32, v186
	v_ldexp_f32 v180, v180, v184
	v_sub_u32_e32 v206, 32, v206
	v_fmamk_f32 v180, v180, 0x30800000, v196
	v_ldexp_f32 v181, v181, v186
	v_sub_u32_e32 v207, 32, v207
	v_ldexp_f32 v182, v182, v206
	v_mul_f32_e32 v184, 0x4b800000, v180
	v_fmamk_f32 v181, v181, 0x30800000, v196
	v_cmp_gt_f32_e32 vcc, s52, v180
	v_ldexp_f32 v183, v183, v207
	v_fmamk_f32 v182, v182, 0x30800000, v196
	v_cndmask_b32_e32 v180, v180, v184, vcc
	v_mul_f32_e32 v184, 0x4b800000, v181
	v_cmp_gt_f32_e64 s[8:9], s52, v181
	v_fmamk_f32 v183, v183, 0x30800000, v196
	v_mul_f32_e32 v186, 0x4b800000, v182
	v_rsq_f32_e32 v180, v180
	v_cndmask_b32_e64 v181, v181, v184, s[8:9]
	v_cmp_gt_f32_e64 s[10:11], s52, v182
	v_mul_f32_e32 v202, 0x4b800000, v183
	v_cmp_gt_f32_e64 s[12:13], s52, v183
	v_cndmask_b32_e64 v182, v182, v186, s[10:11]
	v_rsq_f32_e32 v181, v181
	v_cndmask_b32_e64 v183, v183, v202, s[12:13]
	v_rsq_f32_e32 v182, v182
	v_rsq_f32_e32 v183, v183
	v_mul_f32_e32 v184, 0x45800000, v180
	v_cndmask_b32_e32 v180, v180, v184, vcc
	v_mul_f32_e32 v184, 0x45800000, v181
	v_cmp_lt_i32_e32 vcc, -1, v197
	v_mul_f32_e32 v202, 0x45800000, v182
	v_mul_f32_e32 v203, 0x45800000, v183
	v_cndmask_b32_e32 v186, 0, v180, vcc
	v_cndmask_b32_e64 v180, v181, v184, s[8:9]
	v_cmp_lt_i32_e32 vcc, s53, v197
	v_cndmask_b32_e64 v181, v182, v202, s[10:11]
	v_cndmask_b32_e64 v183, v183, v203, s[12:13]
	v_cndmask_b32_e32 v184, 0, v180, vcc
	v_cmp_lt_i32_e32 vcc, s54, v197
	v_pk_mul_f32 v[124:125], v[124:125], v[186:187] op_sel_hi:[1,0]
	ds_read_b128 v[136:139], v193
	ds_read_b128 v[148:151], v193 offset:128
	ds_read_b128 v[152:155], v193 offset:256
	ds_read_b128 v[156:159], v193 offset:384
	ds_read_b128 v[128:131], v193 offset:512
	ds_read_b128 v[132:135], v193 offset:640
	ds_read_b128 v[140:143], v193 offset:768
	ds_read_b128 v[144:147], v193 offset:896
	v_cndmask_b32_e32 v182, 0, v181, vcc
	v_cmp_lt_i32_e32 vcc, s55, v197
	v_pk_mul_f32 v[108:109], v[108:109], v[182:183] op_sel_hi:[1,0]
	v_pk_mul_f32 v[202:203], v[104:105], v[182:183] op_sel_hi:[1,0]
	v_cndmask_b32_e32 v180, 0, v183, vcc
	v_mov_b32_e32 v183, 0
	v_pk_mul_f32 v[204:205], v[100:101], v[180:181] op_sel_hi:[1,0]
	v_pk_mul_f32 v[206:207], v[96:97], v[180:181] op_sel_hi:[1,0]
	v_mov_b32_e32 v181, 0
	v_mov_b32_dpp v183, v183 row_ror:2 row_mask:0xf bank_mask:0xf
	v_mov_b32_e32 v100, v183
	v_mov_b32_dpp v181, v181 row_ror:1 row_mask:0xf bank_mask:0xf
	v_mov_b32_e32 v101, v183
	v_mov_b32_e32 v96, v181
	v_mov_b32_e32 v97, v181
	v_mov_b32_dpp v100, v124 row_shr:2 row_mask:0xf bank_mask:0xf
	v_mov_b32_dpp v101, v125 row_shr:2 row_mask:0xf bank_mask:0xf
	v_mov_b32_dpp v96, v124 row_shr:1 row_mask:0xf bank_mask:0xf
	v_mov_b32_dpp v97, v125 row_shr:1 row_mask:0xf bank_mask:0xf
	s_waitcnt lgkmcnt(6)
	v_pk_fma_f32 v[100:101], v[148:149], v[100:101], v[136:137]
	v_pk_mul_f32 v[120:121], v[120:121], v[186:187] op_sel_hi:[1,0]
	s_waitcnt lgkmcnt(5)
	v_pk_fma_f32 v[96:97], v[152:153], v[96:97], v[100:101]
	v_mov_b32_e32 v208, v183
	s_waitcnt lgkmcnt(4)
	v_pk_fma_f32 v[96:97], v[156:157], v[124:125], v[96:97]
	v_mov_b32_e32 v209, v183
	v_pk_mul_f32 v[100:101], v[96:97], s[2:3] op_sel_hi:[1,0]
	v_mov_b32_e32 v104, v181
	v_exp_f32_e32 v100, v100
	v_exp_f32_e32 v101, v101
	v_mov_b32_e32 v105, v181
	v_mov_b32_dpp v208, v120 row_shr:2 row_mask:0xf bank_mask:0xf
	v_mov_b32_dpp v209, v121 row_shr:2 row_mask:0xf bank_mask:0xf
	v_pk_add_f32 v[100:101], v[100:101], 1.0 op_sel_hi:[1,0]
	v_mov_b32_dpp v104, v120 row_shr:1 row_mask:0xf bank_mask:0xf
	v_rcp_f32_e32 v100, v100
	v_rcp_f32_e32 v101, v101
	v_mov_b32_dpp v105, v121 row_shr:1 row_mask:0xf bank_mask:0xf
	s_waitcnt lgkmcnt(2)
;     DI void operator()(const AccT& acc, const Unit& u, int wr, int wc, int fr, int fq) const {
;     ...
;                     for (int m = 0; m < 4; ++m) { G[m] = (f32x2){acc[ai][0][m][n][2 * jp], acc[ai][0][m][n][2 * jp + 1]} * rs[m]; V[m] = (f32x2){acc[ai][1][m][n][2 * jp], acc[ai][1][m][n][2 * jp + 1]} * rs[m]; }
; #pragma unroll
;                     for (int m = 0; m < 4; ++m) {
;                         const f32x2 zz = {0.f, 0.f}; const f32x2 Gp = m ? G[m - 1] : zz, Vp = m ? V[m - 1] : zz;
;                         const f32x2 gp1 = {dpp_prev1(G[m].x, Gp.x), dpp_prev1(G[m].y, Gp.y)}, gp2 = {dpp_prev2(G[m].x, Gp.x), dpp_prev2(G[m].y, Gp.y)};
;                         const f32x2 vp1 = {dpp_prev1(V[m].x, Vp.x), dpp_prev1(V[m].y, Vp.y)}, vp2 = {dpp_prev2(V[m].x, Vp.x), dpp_prev2(V[m].y, Vp.y)};
;                         const f32x2 gc = bg + g0 * gp2 + g1 * gp1 + g2 * G[m];
;                         const f32x2 vc = bv + v0 * vp2 + v1 * vp1 + v2 * V[m];
;                         const f32x2 xe = gc * (-LOG2E);
;                         f32x2 dn = {__builtin_amdgcn_exp2f(xe.x), __builtin_amdgcn_exp2f(xe.y)}; dn = dn + 1.0f;
;                         const f32x2 rc = {__builtin_amdgcn_rcpf(dn.x), __builtin_amdgcn_rcpf(dn.y)};
;                         const f32x2 rr = gc * rc * vc;
	v_pk_fma_f32 v[208:209], v[132:133], v[208:209], v[128:129]
	v_pk_mul_f32 v[116:117], v[116:117], v[184:185] op_sel_hi:[1,0]
	s_waitcnt lgkmcnt(1)
	v_pk_fma_f32 v[104:105], v[140:141], v[104:105], v[208:209]
	v_pk_mul_f32 v[96:97], v[96:97], v[100:101]
	s_waitcnt lgkmcnt(0)
	v_pk_fma_f32 v[104:105], v[144:145], v[120:121], v[104:105]
	v_pk_mul_f32 v[96:97], v[104:105], v[96:97]
	v_mov_b32_dpp v104, v124 row_ror:2 row_mask:0xf bank_mask:0xf
	v_mov_b32_dpp v105, v125 row_ror:2 row_mask:0xf bank_mask:0xf
	v_mov_b32_dpp v100, v124 row_ror:1 row_mask:0xf bank_mask:0xf
	v_mov_b32_dpp v101, v125 row_ror:1 row_mask:0xf bank_mask:0xf
	v_mov_b32_dpp v104, v116 row_shr:2 row_mask:0xf bank_mask:0xf
	v_mov_b32_dpp v105, v117 row_shr:2 row_mask:0xf bank_mask:0xf
	v_mov_b32_dpp v100, v116 row_shr:1 row_mask:0xf bank_mask:0xf
	v_mov_b32_dpp v101, v117 row_shr:1 row_mask:0xf bank_mask:0xf
	v_pk_fma_f32 v[104:105], v[148:149], v[104:105], v[136:137]
	v_pk_fma_f32 v[100:101], v[152:153], v[100:101], v[104:105]
	v_pk_fma_f32 v[100:101], v[156:157], v[116:117], v[100:101]
	v_pk_mul_f32 v[112:113], v[112:113], v[184:185] op_sel_hi:[1,0]
	v_pk_mul_f32 v[104:105], v[100:101], s[2:3] op_sel_hi:[1,0]
	v_exp_f32_e32 v104, v104
	v_exp_f32_e32 v105, v105
	v_mov_b32_dpp v208, v120 row_ror:2 row_mask:0xf bank_mask:0xf
	v_mov_b32_dpp v209, v121 row_ror:2 row_mask:0xf bank_mask:0xf
	v_pk_add_f32 v[104:105], v[104:105], 1.0 op_sel_hi:[1,0]
	v_mov_b32_dpp v124, v120 row_ror:1 row_mask:0xf bank_mask:0xf
	v_rcp_f32_e32 v104, v104
	v_rcp_f32_e32 v105, v105
	v_mov_b32_dpp v125, v121 row_ror:1 row_mask:0xf bank_mask:0xf
	v_mov_b32_dpp v208, v112 row_shr:2 row_mask:0xf bank_mask:0xf
	v_mov_b32_dpp v209, v113 row_shr:2 row_mask:0xf bank_mask:0xf
	v_mov_b32_dpp v124, v112 row_shr:1 row_mask:0xf bank_mask:0xf
	v_mov_b32_dpp v125, v113 row_shr:1 row_mask:0xf bank_mask:0xf
	v_pk_fma_f32 v[120:121], v[132:133], v[208:209], v[128:129]
	v_pk_mul_f32 v[100:101], v[100:101], v[104:105]
	v_pk_fma_f32 v[120:121], v[140:141], v[124:125], v[120:121]
	v_pk_fma_f32 v[120:121], v[144:145], v[112:113], v[120:121]
	v_pk_mul_f32 v[100:101], v[120:121], v[100:101]
	v_mov_b32_dpp v104, v116 row_ror:1 row_mask:0xf bank_mask:0xf
	v_mov_b32_dpp v120, v116 row_ror:2 row_mask:0xf bank_mask:0xf
	v_mov_b32_dpp v121, v117 row_ror:2 row_mask:0xf bank_mask:0xf
	v_mov_b32_dpp v105, v117 row_ror:1 row_mask:0xf bank_mask:0xf
	v_mov_b32_dpp v120, v108 row_shr:2 row_mask:0xf bank_mask:0xf
	v_mov_b32_dpp v121, v109 row_shr:2 row_mask:0xf bank_mask:0xf
	v_mov_b32_dpp v104, v108 row_shr:1 row_mask:0xf bank_mask:0xf
	v_mov_b32_dpp v105, v109 row_shr:1 row_mask:0xf bank_mask:0xf
	v_pk_fma_f32 v[120:121], v[148:149], v[120:121], v[136:137]
	v_pk_fma_f32 v[104:105], v[152:153], v[104:105], v[120:121]
	v_pk_fma_f32 v[104:105], v[156:157], v[108:109], v[104:105]
	v_pk_mul_f32 v[120:121], v[104:105], s[2:3] op_sel_hi:[1,0]
	v_exp_f32_e32 v120, v120
	v_exp_f32_e32 v121, v121
	v_mov_b32_dpp v116, v112 row_ror:1 row_mask:0xf bank_mask:0xf
	v_mov_b32_dpp v117, v113 row_ror:1 row_mask:0xf bank_mask:0xf
	v_mov_b32_dpp v124, v112 row_ror:2 row_mask:0xf bank_mask:0xf
	v_mov_b32_dpp v125, v113 row_ror:2 row_mask:0xf bank_mask:0xf
	v_pk_add_f32 v[112:113], v[120:121], 1.0 op_sel_hi:[1,0]
	v_mov_b32_dpp v124, v202 row_shr:2 row_mask:0xf bank_mask:0xf
	v_rcp_f32_e32 v112, v112
	v_rcp_f32_e32 v113, v113
	v_mov_b32_dpp v125, v203 row_shr:2 row_mask:0xf bank_mask:0xf
	v_mov_b32_dpp v116, v202 row_shr:1 row_mask:0xf bank_mask:0xf
	v_mov_b32_dpp v117, v203 row_shr:1 row_mask:0xf bank_mask:0xf
	v_pk_fma_f32 v[120:121], v[132:133], v[124:125], v[128:129]
	v_pk_mul_f32 v[104:105], v[104:105], v[112:113]
	v_pk_fma_f32 v[116:117], v[140:141], v[116:117], v[120:121]
	v_pk_fma_f32 v[116:117], v[144:145], v[202:203], v[116:117]
	v_pk_mul_f32 v[104:105], v[116:117], v[104:105]
	v_mov_b32_dpp v112, v108 row_ror:1 row_mask:0xf bank_mask:0xf
	v_mov_b32_dpp v116, v108 row_ror:2 row_mask:0xf bank_mask:0xf
	v_mov_b32_dpp v117, v109 row_ror:2 row_mask:0xf bank_mask:0xf
	v_mov_b32_dpp v113, v109 row_ror:1 row_mask:0xf bank_mask:0xf
	v_mov_b32_dpp v116, v204 row_shr:2 row_mask:0xf bank_mask:0xf
	v_mov_b32_dpp v117, v205 row_shr:2 row_mask:0xf bank_mask:0xf
	v_mov_b32_dpp v112, v204 row_shr:1 row_mask:0xf bank_mask:0xf
	v_mov_b32_dpp v113, v205 row_shr:1 row_mask:0xf bank_mask:0xf
	v_pk_fma_f32 v[116:117], v[148:149], v[116:117], v[136:137]
	v_pk_fma_f32 v[112:113], v[152:153], v[112:113], v[116:117]
	v_pk_fma_f32 v[112:113], v[156:157], v[204:205], v[112:113]
	v_pk_mul_f32 v[116:117], v[112:113], s[2:3] op_sel_hi:[1,0]
	v_exp_f32_e32 v116, v116
	v_exp_f32_e32 v117, v117
	v_mov_b32_dpp v120, v202 row_ror:2 row_mask:0xf bank_mask:0xf
	v_mov_b32_dpp v121, v203 row_ror:2 row_mask:0xf bank_mask:0xf
	v_mov_b32_dpp v108, v202 row_ror:1 row_mask:0xf bank_mask:0xf
	v_pk_add_f32 v[116:117], v[116:117], 1.0 op_sel_hi:[1,0]
	v_mov_b32_dpp v109, v203 row_ror:1 row_mask:0xf bank_mask:0xf
	v_rcp_f32_e32 v116, v116
	v_rcp_f32_e32 v117, v117
	v_mov_b32_dpp v120, v206 row_shr:2 row_mask:0xf bank_mask:0xf
	v_mov_b32_dpp v121, v207 row_shr:2 row_mask:0xf bank_mask:0xf
	v_mov_b32_dpp v108, v206 row_shr:1 row_mask:0xf bank_mask:0xf
	v_mov_b32_dpp v109, v207 row_shr:1 row_mask:0xf bank_mask:0xf
	v_pk_fma_f32 v[120:121], v[132:133], v[120:121], v[128:129]
	v_pk_mul_f32 v[112:113], v[112:113], v[116:117]
	v_pk_fma_f32 v[108:109], v[140:141], v[108:109], v[120:121]
	v_pk_mul_f32 v[116:117], v[122:123], v[186:187] op_sel_hi:[1,0]
	v_pk_fma_f32 v[108:109], v[144:145], v[206:207], v[108:109]
	v_mov_b32_e32 v122, v183
	v_pk_mul_f32 v[108:109], v[108:109], v[112:113]
; DI unsigned pk2(float lo, float hi) { f32x2 v = {lo, hi}; bf16x2_t b = __builtin_convertvector(v, bf16x2_t); return __builtin_bit_cast(unsigned, b); }
;     DI void operator()(const AccT& acc, const Unit& u, int wr, int wc, int fr, int fq) const {
;     ...
;                     for (int m = 0; m < 4; ++m) { G[m] = (f32x2){acc[ai][0][m][n][2 * jp], acc[ai][0][m][n][2 * jp + 1]} * rs[m]; V[m] = (f32x2){acc[ai][1][m][n][2 * jp], acc[ai][1][m][n][2 * jp + 1]} * rs[m]; }
; #pragma unroll
;                     for (int m = 0; m < 4; ++m) {
;                         const f32x2 zz = {0.f, 0.f}; const f32x2 Gp = m ? G[m - 1] : zz, Vp = m ? V[m - 1] : zz;
;                         const f32x2 gp1 = {dpp_prev1(G[m].x, Gp.x), dpp_prev1(G[m].y, Gp.y)}, gp2 = {dpp_prev2(G[m].x, Gp.x), dpp_prev2(G[m].y, Gp.y)};
;                         const f32x2 vp1 = {dpp_prev1(V[m].x, Vp.x), dpp_prev1(V[m].y, Vp.y)}, vp2 = {dpp_prev2(V[m].x, Vp.x), dpp_prev2(V[m].y, Vp.y)};
;                         const f32x2 gc = bg + g0 * gp2 + g1 * gp1 + g2 * G[m];
;                         const f32x2 vc = bv + v0 * vp2 + v1 * vp1 + v2 * V[m];
;                         const f32x2 xe = gc * (-LOG2E);
;                         f32x2 dn = {__builtin_amdgcn_exp2f(xe.x), __builtin_amdgcn_exp2f(xe.y)}; dn = dn + 1.0f;
;                         const f32x2 rc = {__builtin_amdgcn_rcpf(dn.x), __builtin_amdgcn_rcpf(dn.y)};
;                         const f32x2 rr = gc * rc * vc;
;                         wpk[m][jp] = pk2(rr.x, rr.y); }
	v_pk_mul_f32 v[112:113], v[126:127], v[186:187] op_sel_hi:[1,0]
	v_mov_b32_e32 v123, v183
	v_mov_b32_e32 v120, v181
	v_mov_b32_e32 v121, v181
	v_mov_b32_dpp v122, v112 row_shr:2 row_mask:0xf bank_mask:0xf
	v_mov_b32_dpp v123, v113 row_shr:2 row_mask:0xf bank_mask:0xf
	v_mov_b32_dpp v120, v112 row_shr:1 row_mask:0xf bank_mask:0xf
	v_mov_b32_dpp v121, v113 row_shr:1 row_mask:0xf bank_mask:0xf
	v_pk_fma_f32 v[122:123], v[150:151], v[122:123], v[138:139]
	v_mov_b32_e32 v126, v183
	v_pk_fma_f32 v[120:121], v[154:155], v[120:121], v[122:123]
	v_mov_b32_e32 v127, v183
	v_pk_fma_f32 v[120:121], v[112:113], v[158:159], v[120:121]
	v_mov_b32_e32 v124, v181
	v_pk_mul_f32 v[122:123], v[120:121], s[2:3] op_sel_hi:[1,0]
	v_mov_b32_e32 v125, v181
	v_exp_f32_e32 v122, v122
	v_exp_f32_e32 v123, v123
	v_mov_b32_dpp v126, v116 row_shr:2 row_mask:0xf bank_mask:0xf
	v_mov_b32_dpp v127, v117 row_shr:2 row_mask:0xf bank_mask:0xf
	v_mov_b32_dpp v124, v116 row_shr:1 row_mask:0xf bank_mask:0xf
	v_pk_add_f32 v[122:123], v[122:123], 1.0 op_sel_hi:[1,0]
	v_mov_b32_dpp v125, v117 row_shr:1 row_mask:0xf bank_mask:0xf
	v_rcp_f32_e32 v122, v122
	v_rcp_f32_e32 v123, v123
	v_pk_fma_f32 v[126:127], v[134:135], v[126:127], v[130:131]
	v_cvt_pk_bf16_f32 v228, v96, v97
	v_pk_fma_f32 v[124:125], v[142:143], v[124:125], v[126:127]
	v_pk_mul_f32 v[120:121], v[120:121], v[122:123]
	v_pk_fma_f32 v[124:125], v[116:117], v[146:147], v[124:125]
	v_pk_mul_f32 v[120:121], v[124:125], v[120:121]
	v_pk_mul_f32 v[118:119], v[118:119], v[184:185] op_sel_hi:[1,0]
	v_cvt_pk_bf16_f32 v229, v120, v121
	v_mov_b32_dpp v122, v112 row_ror:2 row_mask:0xf bank_mask:0xf
	v_mov_b32_dpp v123, v113 row_ror:2 row_mask:0xf bank_mask:0xf
	v_mov_b32_dpp v120, v112 row_ror:1 row_mask:0xf bank_mask:0xf
	v_mov_b32_dpp v121, v113 row_ror:1 row_mask:0xf bank_mask:0xf
	v_mov_b32_dpp v122, v118 row_shr:2 row_mask:0xf bank_mask:0xf
	v_mov_b32_dpp v123, v119 row_shr:2 row_mask:0xf bank_mask:0xf
	v_mov_b32_dpp v120, v118 row_shr:1 row_mask:0xf bank_mask:0xf
	v_mov_b32_dpp v121, v119 row_shr:1 row_mask:0xf bank_mask:0xf
	v_pk_fma_f32 v[122:123], v[150:151], v[122:123], v[138:139]
	v_pk_fma_f32 v[120:121], v[154:155], v[120:121], v[122:123]
	v_pk_fma_f32 v[120:121], v[118:119], v[158:159], v[120:121]
	v_pk_mul_f32 v[122:123], v[120:121], s[2:3] op_sel_hi:[1,0]
	v_exp_f32_e32 v122, v122
	v_exp_f32_e32 v123, v123
	v_mov_b32_dpp v112, v116 row_ror:1 row_mask:0xf bank_mask:0xf
	v_mov_b32_dpp v113, v117 row_ror:1 row_mask:0xf bank_mask:0xf
	v_mov_b32_dpp v124, v116 row_ror:2 row_mask:0xf bank_mask:0xf
	v_mov_b32_dpp v125, v117 row_ror:2 row_mask:0xf bank_mask:0xf
	v_pk_add_f32 v[116:117], v[122:123], 1.0 op_sel_hi:[1,0]
	v_pk_mul_f32 v[114:115], v[114:115], v[184:185] op_sel_hi:[1,0]
	v_rcp_f32_e32 v116, v116
	v_rcp_f32_e32 v117, v117
	v_mov_b32_dpp v124, v114 row_shr:2 row_mask:0xf bank_mask:0xf
	v_mov_b32_dpp v125, v115 row_shr:2 row_mask:0xf bank_mask:0xf
	v_mov_b32_dpp v112, v114 row_shr:1 row_mask:0xf bank_mask:0xf
	v_mov_b32_dpp v113, v115 row_shr:1 row_mask:0xf bank_mask:0xf
	v_pk_fma_f32 v[122:123], v[134:135], v[124:125], v[130:131]
	v_pk_mul_f32 v[116:117], v[120:121], v[116:117]
	v_pk_fma_f32 v[112:113], v[142:143], v[112:113], v[122:123]
	v_cvt_pk_bf16_f32 v232, v100, v101
	v_pk_fma_f32 v[112:113], v[114:115], v[146:147], v[112:113]
	v_pk_mul_f32 v[110:111], v[110:111], v[182:183] op_sel_hi:[1,0]
	v_pk_mul_f32 v[112:113], v[112:113], v[116:117]
	v_cvt_pk_bf16_f32 v233, v112, v113
	v_mov_b32_dpp v116, v118 row_ror:2 row_mask:0xf bank_mask:0xf
	v_mov_b32_dpp v117, v119 row_ror:2 row_mask:0xf bank_mask:0xf
	v_mov_b32_dpp v112, v118 row_ror:1 row_mask:0xf bank_mask:0xf
	v_mov_b32_dpp v113, v119 row_ror:1 row_mask:0xf bank_mask:0xf
	v_mov_b32_dpp v116, v110 row_shr:2 row_mask:0xf bank_mask:0xf
	v_mov_b32_dpp v117, v111 row_shr:2 row_mask:0xf bank_mask:0xf
	v_mov_b32_dpp v112, v110 row_shr:1 row_mask:0xf bank_mask:0xf
	v_mov_b32_dpp v113, v111 row_shr:1 row_mask:0xf bank_mask:0xf
	v_pk_fma_f32 v[116:117], v[150:151], v[116:117], v[138:139]
	v_pk_fma_f32 v[112:113], v[154:155], v[112:113], v[116:117]
	v_pk_fma_f32 v[112:113], v[110:111], v[158:159], v[112:113]
	v_pk_mul_f32 v[116:117], v[112:113], s[2:3] op_sel_hi:[1,0]
	v_exp_f32_e32 v116, v116
	v_exp_f32_e32 v117, v117
	v_mov_b32_dpp v118, v114 row_ror:1 row_mask:0xf bank_mask:0xf
	v_mov_b32_dpp v119, v115 row_ror:1 row_mask:0xf bank_mask:0xf
	v_mov_b32_dpp v120, v114 row_ror:2 row_mask:0xf bank_mask:0xf
	v_mov_b32_dpp v121, v115 row_ror:2 row_mask:0xf bank_mask:0xf
	v_pk_add_f32 v[114:115], v[116:117], 1.0 op_sel_hi:[1,0]
	v_pk_mul_f32 v[106:107], v[106:107], v[182:183] op_sel_hi:[1,0]
	v_rcp_f32_e32 v114, v114
	v_rcp_f32_e32 v115, v115
	v_mov_b32_dpp v120, v106 row_shr:2 row_mask:0xf bank_mask:0xf
	v_mov_b32_dpp v121, v107 row_shr:2 row_mask:0xf bank_mask:0xf
	v_mov_b32_dpp v118, v106 row_shr:1 row_mask:0xf bank_mask:0xf
	v_mov_b32_dpp v119, v107 row_shr:1 row_mask:0xf bank_mask:0xf
	v_pk_fma_f32 v[116:117], v[134:135], v[120:121], v[130:131]
	v_pk_mul_f32 v[112:113], v[112:113], v[114:115]
	v_pk_fma_f32 v[116:117], v[142:143], v[118:119], v[116:117]
	v_pk_fma_f32 v[116:117], v[106:107], v[146:147], v[116:117]
	v_pk_mul_f32 v[112:113], v[116:117], v[112:113]
	v_cvt_pk_bf16_f32 v236, v104, v105
	v_pk_mul_f32 v[102:103], v[102:103], v[180:181] op_sel_hi:[1,0]
	v_cvt_pk_bf16_f32 v237, v112, v113
	v_mov_b32_dpp v114, v110 row_ror:2 row_mask:0xf bank_mask:0xf
	v_mov_b32_dpp v115, v111 row_ror:2 row_mask:0xf bank_mask:0xf
	v_mov_b32_dpp v112, v110 row_ror:1 row_mask:0xf bank_mask:0xf
	v_mov_b32_dpp v113, v111 row_ror:1 row_mask:0xf bank_mask:0xf
; DI unsigned pk2(float lo, float hi) { f32x2 v = {lo, hi}; bf16x2_t b = __builtin_convertvector(v, bf16x2_t); return __builtin_bit_cast(unsigned, b); }
;     DI void operator()(const AccT& acc, const Unit& u, int wr, int wc, int fr, int fq) const {
;     ...
;                     for (int m = 0; m < 4; ++m) {
;                         const f32x2 zz = {0.f, 0.f}; const f32x2 Gp = m ? G[m - 1] : zz, Vp = m ? V[m - 1] : zz;
;                         const f32x2 gp1 = {dpp_prev1(G[m].x, Gp.x), dpp_prev1(G[m].y, Gp.y)}, gp2 = {dpp_prev2(G[m].x, Gp.x), dpp_prev2(G[m].y, Gp.y)};
;                         const f32x2 vp1 = {dpp_prev1(V[m].x, Vp.x), dpp_prev1(V[m].y, Vp.y)}, vp2 = {dpp_prev2(V[m].x, Vp.x), dpp_prev2(V[m].y, Vp.y)};
;                         const f32x2 gc = bg + g0 * gp2 + g1 * gp1 + g2 * G[m];
;                         const f32x2 vc = bv + v0 * vp2 + v1 * vp1 + v2 * V[m];
;                         const f32x2 xe = gc * (-LOG2E);
;                         f32x2 dn = {__builtin_amdgcn_exp2f(xe.x), __builtin_amdgcn_exp2f(xe.y)}; dn = dn + 1.0f;
;                         const f32x2 rc = {__builtin_amdgcn_rcpf(dn.x), __builtin_amdgcn_rcpf(dn.y)};
;                         const f32x2 rr = gc * rc * vc;
;                         wpk[m][jp] = pk2(rr.x, rr.y); }
;                 }
; #pragma unroll
;                 for (int m = 0; m < 4; ++m) { const int row = m ? tok0 + 16 * m : row0;
;                     *(u32x2*)(ACT + (size_t)row * 2816 + cl + 4 * n) = (u32x2){wpk[m][0], wpk[m][1]}; }
	v_mov_b32_dpp v114, v102 row_shr:2 row_mask:0xf bank_mask:0xf
	v_mov_b32_dpp v115, v103 row_shr:2 row_mask:0xf bank_mask:0xf
	v_mov_b32_dpp v112, v102 row_shr:1 row_mask:0xf bank_mask:0xf
	v_mov_b32_dpp v113, v103 row_shr:1 row_mask:0xf bank_mask:0xf
	v_pk_fma_f32 v[114:115], v[150:151], v[114:115], v[138:139]
	v_pk_fma_f32 v[112:113], v[154:155], v[112:113], v[114:115]
	v_pk_fma_f32 v[102:103], v[102:103], v[158:159], v[112:113]
	v_pk_mul_f32 v[112:113], v[102:103], s[2:3] op_sel_hi:[1,0]
	v_exp_f32_e32 v112, v112
	v_exp_f32_e32 v113, v113
	v_mov_b32_dpp v110, v106 row_ror:1 row_mask:0xf bank_mask:0xf
	v_mov_b32_dpp v111, v107 row_ror:1 row_mask:0xf bank_mask:0xf
	v_mov_b32_dpp v116, v106 row_ror:2 row_mask:0xf bank_mask:0xf
	v_mov_b32_dpp v117, v107 row_ror:2 row_mask:0xf bank_mask:0xf
	v_pk_add_f32 v[106:107], v[112:113], 1.0 op_sel_hi:[1,0]
	v_pk_mul_f32 v[98:99], v[98:99], v[180:181] op_sel_hi:[1,0]
	v_rcp_f32_e32 v106, v106
	v_rcp_f32_e32 v107, v107
	v_mov_b32_dpp v116, v98 row_shr:2 row_mask:0xf bank_mask:0xf
	v_mov_b32_dpp v117, v99 row_shr:2 row_mask:0xf bank_mask:0xf
	v_mov_b32_dpp v110, v98 row_shr:1 row_mask:0xf bank_mask:0xf
	v_mov_b32_dpp v111, v99 row_shr:1 row_mask:0xf bank_mask:0xf
	v_pk_fma_f32 v[112:113], v[134:135], v[116:117], v[130:131]
	v_pk_mul_f32 v[102:103], v[102:103], v[106:107]
	v_pk_fma_f32 v[110:111], v[142:143], v[110:111], v[112:113]
	v_mov_b64_e32 v[128:129], s[16:17]
	v_pk_fma_f32 v[98:99], v[98:99], v[146:147], v[110:111]
	v_cvt_pk_bf16_f32 v252, v108, v109
	v_pk_mul_f32 v[98:99], v[98:99], v[102:103]
	v_lshlrev_b64 v[130:131], 1, v[188:189]
	v_cvt_pk_bf16_f32 v253, v98, v99
	v_mad_i64_i32 v[98:99], s[8:9], v201, s48, v[128:129]
	v_lshl_add_u64 v[132:133], v[98:99], 0, v[130:131]
	v_mad_i64_i32 v[96:97], s[8:9], v198, s48, v[128:129]
	v_lshl_add_u64 v[134:135], v[96:97], 0, v[130:131]
	v_mad_i64_i32 v[96:97], s[8:9], v199, s48, v[128:129]
	v_lshl_add_u64 v[136:137], v[96:97], 0, v[130:131]
	v_mad_i64_i32 v[96:97], s[8:9], v200, s48, v[128:129]
	v_lshl_add_u64 v[138:139], v[96:97], 0, v[130:131]
	v_pk_mul_f32 v[92:93], v[92:93], v[186:187] op_sel_hi:[1,0]
	v_pk_mul_f32 v[142:143], v[68:69], v[180:181] op_sel_hi:[1,0]
	v_mov_b32_e32 v68, v183
	v_mov_b32_e32 v69, v183
	v_pk_mul_f32 v[144:145], v[64:65], v[180:181] op_sel_hi:[1,0]
	v_mov_b32_e32 v64, v181
	v_mov_b32_e32 v65, v181
	v_mov_b32_dpp v68, v92 row_shr:2 row_mask:0xf bank_mask:0xf
	v_mov_b32_dpp v69, v93 row_shr:2 row_mask:0xf bank_mask:0xf
	ds_read_b128 v[104:107], v193 offset:16
	ds_read_b128 v[116:119], v193 offset:144
	ds_read_b128 v[120:123], v193 offset:272
	ds_read_b128 v[124:127], v193 offset:400
	ds_read_b128 v[96:99], v193 offset:528
	ds_read_b128 v[100:103], v193 offset:656
	ds_read_b128 v[108:111], v193 offset:784
	ds_read_b128 v[112:115], v193 offset:912
	v_mov_b32_dpp v64, v92 row_shr:1 row_mask:0xf bank_mask:0xf
	v_mov_b32_dpp v65, v93 row_shr:1 row_mask:0xf bank_mask:0xf
	s_waitcnt lgkmcnt(6)
	v_pk_fma_f32 v[68:69], v[116:117], v[68:69], v[104:105]
	v_pk_mul_f32 v[88:89], v[88:89], v[186:187] op_sel_hi:[1,0]
	s_waitcnt lgkmcnt(5)
	v_pk_fma_f32 v[64:65], v[120:121], v[64:65], v[68:69]
	v_mov_b32_e32 v146, v183
	s_waitcnt lgkmcnt(4)
	v_pk_fma_f32 v[64:65], v[92:93], v[124:125], v[64:65]
	v_mov_b32_e32 v147, v183
	v_pk_mul_f32 v[68:69], v[64:65], s[2:3] op_sel_hi:[1,0]
	v_pk_mul_f32 v[140:141], v[72:73], v[182:183] op_sel_hi:[1,0]
	v_exp_f32_e32 v68, v68
	v_exp_f32_e32 v69, v69
	v_mov_b32_e32 v72, v181
	v_mov_b32_e32 v73, v181
	v_mov_b32_dpp v146, v88 row_shr:2 row_mask:0xf bank_mask:0xf
	v_pk_add_f32 v[68:69], v[68:69], 1.0 op_sel_hi:[1,0]
	v_mov_b32_dpp v147, v89 row_shr:2 row_mask:0xf bank_mask:0xf
	v_rcp_f32_e32 v68, v68
	v_rcp_f32_e32 v69, v69
	v_mov_b32_dpp v72, v88 row_shr:1 row_mask:0xf bank_mask:0xf
	v_mov_b32_dpp v73, v89 row_shr:1 row_mask:0xf bank_mask:0xf
	s_waitcnt lgkmcnt(2)
	v_pk_fma_f32 v[146:147], v[100:101], v[146:147], v[96:97]
	v_pk_mul_f32 v[64:65], v[64:65], v[68:69]
	s_waitcnt lgkmcnt(1)
	v_pk_fma_f32 v[72:73], v[108:109], v[72:73], v[146:147]
	v_pk_mul_f32 v[84:85], v[84:85], v[184:185] op_sel_hi:[1,0]
	s_waitcnt lgkmcnt(0)
	v_pk_fma_f32 v[72:73], v[88:89], v[112:113], v[72:73]
	v_pk_mul_f32 v[64:65], v[72:73], v[64:65]
	v_mov_b32_dpp v72, v92 row_ror:2 row_mask:0xf bank_mask:0xf
	v_mov_b32_dpp v73, v93 row_ror:2 row_mask:0xf bank_mask:0xf
	v_mov_b32_dpp v68, v92 row_ror:1 row_mask:0xf bank_mask:0xf
	v_mov_b32_dpp v69, v93 row_ror:1 row_mask:0xf bank_mask:0xf
	v_mov_b32_dpp v72, v84 row_shr:2 row_mask:0xf bank_mask:0xf
	v_mov_b32_dpp v73, v85 row_shr:2 row_mask:0xf bank_mask:0xf
	v_mov_b32_dpp v68, v84 row_shr:1 row_mask:0xf bank_mask:0xf
	v_mov_b32_dpp v69, v85 row_shr:1 row_mask:0xf bank_mask:0xf
	v_pk_fma_f32 v[72:73], v[116:117], v[72:73], v[104:105]
	v_pk_fma_f32 v[68:69], v[120:121], v[68:69], v[72:73]
	v_pk_fma_f32 v[68:69], v[84:85], v[124:125], v[68:69]
	v_pk_mul_f32 v[80:81], v[80:81], v[184:185] op_sel_hi:[1,0]
	v_pk_mul_f32 v[72:73], v[68:69], s[2:3] op_sel_hi:[1,0]
	v_exp_f32_e32 v72, v72
	v_exp_f32_e32 v73, v73
	v_mov_b32_dpp v146, v88 row_ror:2 row_mask:0xf bank_mask:0xf
	v_mov_b32_dpp v147, v89 row_ror:2 row_mask:0xf bank_mask:0xf
	v_pk_add_f32 v[72:73], v[72:73], 1.0 op_sel_hi:[1,0]
	v_mov_b32_dpp v92, v88 row_ror:1 row_mask:0xf bank_mask:0xf
	v_rcp_f32_e32 v72, v72
	v_rcp_f32_e32 v73, v73
	v_mov_b32_dpp v93, v89 row_ror:1 row_mask:0xf bank_mask:0xf
	v_mov_b32_dpp v146, v80 row_shr:2 row_mask:0xf bank_mask:0xf
	v_mov_b32_dpp v147, v81 row_shr:2 row_mask:0xf bank_mask:0xf
	v_mov_b32_dpp v92, v80 row_shr:1 row_mask:0xf bank_mask:0xf
	v_mov_b32_dpp v93, v81 row_shr:1 row_mask:0xf bank_mask:0xf
; #define LAS __attribute__((address_space(3)))
; DI unsigned pk2(float lo, float hi) { f32x2 v = {lo, hi}; bf16x2_t b = __builtin_convertvector(v, bf16x2_t); return __builtin_bit_cast(unsigned, b); }
;     DI void operator()(const AccT& acc, const Unit& u, int wr, int wc, int fr, int fq) const {
;     ...
;                     const f32x2 bg = *(const LAS f32x2*)(P + lc + 2 * jp), g0 = *(const LAS f32x2*)(P + 32 + lc + 2 * jp), g1 = *(const LAS f32x2*)(P + 64 + lc + 2 * jp), g2 = *(const LAS f32x2*)(P + 96 + lc + 2 * jp);
;                     const f32x2 bv = *(const LAS f32x2*)(P + 128 + lc + 2 * jp), v0 = *(const LAS f32x2*)(P + 160 + lc + 2 * jp), v1 = *(const LAS f32x2*)(P + 192 + lc + 2 * jp), v2 = *(const LAS f32x2*)(P + 224 + lc + 2 * jp);
;                     f32x2 G[4], V[4];
; #pragma unroll
;                     for (int m = 0; m < 4; ++m) { G[m] = (f32x2){acc[ai][0][m][n][2 * jp], acc[ai][0][m][n][2 * jp + 1]} * rs[m]; V[m] = (f32x2){acc[ai][1][m][n][2 * jp], acc[ai][1][m][n][2 * jp + 1]} * rs[m]; }
; #pragma unroll
;                     for (int m = 0; m < 4; ++m) {
;                         const f32x2 zz = {0.f, 0.f}; const f32x2 Gp = m ? G[m - 1] : zz, Vp = m ? V[m - 1] : zz;
;                         const f32x2 gp1 = {dpp_prev1(G[m].x, Gp.x), dpp_prev1(G[m].y, Gp.y)}, gp2 = {dpp_prev2(G[m].x, Gp.x), dpp_prev2(G[m].y, Gp.y)};
;                         const f32x2 vp1 = {dpp_prev1(V[m].x, Vp.x), dpp_prev1(V[m].y, Vp.y)}, vp2 = {dpp_prev2(V[m].x, Vp.x), dpp_prev2(V[m].y, Vp.y)};
;                         const f32x2 gc = bg + g0 * gp2 + g1 * gp1 + g2 * G[m];
;                         const f32x2 vc = bv + v0 * vp2 + v1 * vp1 + v2 * V[m];
;                         const f32x2 xe = gc * (-LOG2E);
;                         f32x2 dn = {__builtin_amdgcn_exp2f(xe.x), __builtin_amdgcn_exp2f(xe.y)}; dn = dn + 1.0f;
;                         const f32x2 rc = {__builtin_amdgcn_rcpf(dn.x), __builtin_amdgcn_rcpf(dn.y)};
;                         const f32x2 rr = gc * rc * vc;
;                         wpk[m][jp] = pk2(rr.x, rr.y); }
	v_pk_fma_f32 v[88:89], v[100:101], v[146:147], v[96:97]
	v_pk_mul_f32 v[68:69], v[68:69], v[72:73]
	v_pk_fma_f32 v[88:89], v[108:109], v[92:93], v[88:89]
	v_pk_mul_f32 v[76:77], v[76:77], v[182:183] op_sel_hi:[1,0]
	v_pk_fma_f32 v[88:89], v[80:81], v[112:113], v[88:89]
	v_pk_mul_f32 v[68:69], v[88:89], v[68:69]
	v_mov_b32_dpp v88, v84 row_ror:2 row_mask:0xf bank_mask:0xf
	v_mov_b32_dpp v89, v85 row_ror:2 row_mask:0xf bank_mask:0xf
	v_mov_b32_dpp v72, v84 row_ror:1 row_mask:0xf bank_mask:0xf
	v_mov_b32_dpp v73, v85 row_ror:1 row_mask:0xf bank_mask:0xf
	v_mov_b32_dpp v88, v76 row_shr:2 row_mask:0xf bank_mask:0xf
	v_mov_b32_dpp v89, v77 row_shr:2 row_mask:0xf bank_mask:0xf
	v_mov_b32_dpp v72, v76 row_shr:1 row_mask:0xf bank_mask:0xf
	v_mov_b32_dpp v73, v77 row_shr:1 row_mask:0xf bank_mask:0xf
	v_pk_fma_f32 v[88:89], v[116:117], v[88:89], v[104:105]
	v_pk_fma_f32 v[72:73], v[120:121], v[72:73], v[88:89]
	v_pk_fma_f32 v[72:73], v[76:77], v[124:125], v[72:73]
	v_pk_mul_f32 v[88:89], v[72:73], s[2:3] op_sel_hi:[1,0]
	v_exp_f32_e32 v88, v88
	v_exp_f32_e32 v89, v89
	v_mov_b32_dpp v84, v80 row_ror:1 row_mask:0xf bank_mask:0xf
	v_mov_b32_dpp v85, v81 row_ror:1 row_mask:0xf bank_mask:0xf
	v_mov_b32_dpp v92, v80 row_ror:2 row_mask:0xf bank_mask:0xf
	v_mov_b32_dpp v93, v81 row_ror:2 row_mask:0xf bank_mask:0xf
	v_pk_add_f32 v[80:81], v[88:89], 1.0 op_sel_hi:[1,0]
	v_mov_b32_dpp v92, v140 row_shr:2 row_mask:0xf bank_mask:0xf
	v_rcp_f32_e32 v80, v80
	v_rcp_f32_e32 v81, v81
	v_mov_b32_dpp v93, v141 row_shr:2 row_mask:0xf bank_mask:0xf
	v_mov_b32_dpp v84, v140 row_shr:1 row_mask:0xf bank_mask:0xf
	v_mov_b32_dpp v85, v141 row_shr:1 row_mask:0xf bank_mask:0xf
	v_pk_fma_f32 v[88:89], v[100:101], v[92:93], v[96:97]
	v_pk_mul_f32 v[72:73], v[72:73], v[80:81]
	v_pk_fma_f32 v[84:85], v[108:109], v[84:85], v[88:89]
	v_pk_fma_f32 v[84:85], v[140:141], v[112:113], v[84:85]
	v_pk_mul_f32 v[72:73], v[84:85], v[72:73]
	v_mov_b32_dpp v80, v76 row_ror:1 row_mask:0xf bank_mask:0xf
	v_mov_b32_dpp v84, v76 row_ror:2 row_mask:0xf bank_mask:0xf
	v_mov_b32_dpp v85, v77 row_ror:2 row_mask:0xf bank_mask:0xf
	v_mov_b32_dpp v81, v77 row_ror:1 row_mask:0xf bank_mask:0xf
	v_mov_b32_dpp v84, v142 row_shr:2 row_mask:0xf bank_mask:0xf
	v_mov_b32_dpp v85, v143 row_shr:2 row_mask:0xf bank_mask:0xf
	v_mov_b32_dpp v80, v142 row_shr:1 row_mask:0xf bank_mask:0xf
	v_mov_b32_dpp v81, v143 row_shr:1 row_mask:0xf bank_mask:0xf
	v_pk_fma_f32 v[84:85], v[116:117], v[84:85], v[104:105]
	v_pk_fma_f32 v[80:81], v[120:121], v[80:81], v[84:85]
	v_pk_fma_f32 v[80:81], v[142:143], v[124:125], v[80:81]
	v_pk_mul_f32 v[84:85], v[80:81], s[2:3] op_sel_hi:[1,0]
	v_exp_f32_e32 v84, v84
	v_exp_f32_e32 v85, v85
	v_mov_b32_dpp v88, v140 row_ror:2 row_mask:0xf bank_mask:0xf
	v_mov_b32_dpp v89, v141 row_ror:2 row_mask:0xf bank_mask:0xf
	v_mov_b32_dpp v76, v140 row_ror:1 row_mask:0xf bank_mask:0xf
	v_pk_add_f32 v[84:85], v[84:85], 1.0 op_sel_hi:[1,0]
	v_mov_b32_dpp v77, v141 row_ror:1 row_mask:0xf bank_mask:0xf
	v_rcp_f32_e32 v84, v84
	v_rcp_f32_e32 v85, v85
	v_mov_b32_dpp v88, v144 row_shr:2 row_mask:0xf bank_mask:0xf
	v_mov_b32_dpp v89, v145 row_shr:2 row_mask:0xf bank_mask:0xf
	v_mov_b32_dpp v76, v144 row_shr:1 row_mask:0xf bank_mask:0xf
	v_mov_b32_dpp v77, v145 row_shr:1 row_mask:0xf bank_mask:0xf
	v_pk_fma_f32 v[88:89], v[100:101], v[88:89], v[96:97]
	v_pk_mul_f32 v[80:81], v[80:81], v[84:85]
	v_pk_fma_f32 v[76:77], v[108:109], v[76:77], v[88:89]
	v_pk_mul_f32 v[84:85], v[90:91], v[186:187] op_sel_hi:[1,0]
	v_pk_fma_f32 v[76:77], v[144:145], v[112:113], v[76:77]
	v_mov_b32_e32 v90, v183
	v_pk_mul_f32 v[76:77], v[76:77], v[80:81]
	v_pk_mul_f32 v[80:81], v[94:95], v[186:187] op_sel_hi:[1,0]
	v_mov_b32_e32 v91, v183
	v_mov_b32_e32 v88, v181
	v_mov_b32_e32 v89, v181
	v_mov_b32_dpp v90, v80 row_shr:2 row_mask:0xf bank_mask:0xf
	v_mov_b32_dpp v91, v81 row_shr:2 row_mask:0xf bank_mask:0xf
	v_mov_b32_dpp v88, v80 row_shr:1 row_mask:0xf bank_mask:0xf
	v_mov_b32_dpp v89, v81 row_shr:1 row_mask:0xf bank_mask:0xf
	v_pk_fma_f32 v[90:91], v[118:119], v[90:91], v[106:107]
	v_mov_b32_e32 v94, v183
	v_pk_fma_f32 v[88:89], v[122:123], v[88:89], v[90:91]
	v_mov_b32_e32 v95, v183
	v_pk_fma_f32 v[88:89], v[80:81], v[126:127], v[88:89]
	v_mov_b32_e32 v92, v181
	v_pk_mul_f32 v[90:91], v[88:89], s[2:3] op_sel_hi:[1,0]
	v_mov_b32_e32 v93, v181
	v_exp_f32_e32 v90, v90
	v_exp_f32_e32 v91, v91
	v_mov_b32_dpp v94, v84 row_shr:2 row_mask:0xf bank_mask:0xf
	v_mov_b32_dpp v95, v85 row_shr:2 row_mask:0xf bank_mask:0xf
	v_mov_b32_dpp v92, v84 row_shr:1 row_mask:0xf bank_mask:0xf
	v_pk_add_f32 v[90:91], v[90:91], 1.0 op_sel_hi:[1,0]
	v_mov_b32_dpp v93, v85 row_shr:1 row_mask:0xf bank_mask:0xf
	v_rcp_f32_e32 v90, v90
	v_rcp_f32_e32 v91, v91
	v_pk_fma_f32 v[94:95], v[102:103], v[94:95], v[98:99]
	v_cvt_pk_bf16_f32 v230, v64, v65
	v_pk_fma_f32 v[92:93], v[110:111], v[92:93], v[94:95]
	v_pk_mul_f32 v[88:89], v[88:89], v[90:91]
	v_pk_fma_f32 v[92:93], v[84:85], v[114:115], v[92:93]
	v_pk_mul_f32 v[88:89], v[92:93], v[88:89]
	v_pk_mul_f32 v[86:87], v[86:87], v[184:185] op_sel_hi:[1,0]
	v_cvt_pk_bf16_f32 v231, v88, v89
	v_mov_b32_dpp v90, v80 row_ror:2 row_mask:0xf bank_mask:0xf
	v_mov_b32_dpp v91, v81 row_ror:2 row_mask:0xf bank_mask:0xf
	v_mov_b32_dpp v88, v80 row_ror:1 row_mask:0xf bank_mask:0xf
	v_mov_b32_dpp v89, v81 row_ror:1 row_mask:0xf bank_mask:0xf
	v_mov_b32_dpp v90, v86 row_shr:2 row_mask:0xf bank_mask:0xf
	v_mov_b32_dpp v91, v87 row_shr:2 row_mask:0xf bank_mask:0xf
	v_mov_b32_dpp v88, v86 row_shr:1 row_mask:0xf bank_mask:0xf
	v_mov_b32_dpp v89, v87 row_shr:1 row_mask:0xf bank_mask:0xf
	v_pk_fma_f32 v[90:91], v[118:119], v[90:91], v[106:107]
; DI unsigned pk2(float lo, float hi) { f32x2 v = {lo, hi}; bf16x2_t b = __builtin_convertvector(v, bf16x2_t); return __builtin_bit_cast(unsigned, b); }
;     DI void operator()(const AccT& acc, const Unit& u, int wr, int wc, int fr, int fq) const {
;     ...
;                     for (int m = 0; m < 4; ++m) {
;                         const f32x2 zz = {0.f, 0.f}; const f32x2 Gp = m ? G[m - 1] : zz, Vp = m ? V[m - 1] : zz;
;                         const f32x2 gp1 = {dpp_prev1(G[m].x, Gp.x), dpp_prev1(G[m].y, Gp.y)}, gp2 = {dpp_prev2(G[m].x, Gp.x), dpp_prev2(G[m].y, Gp.y)};
;                         const f32x2 vp1 = {dpp_prev1(V[m].x, Vp.x), dpp_prev1(V[m].y, Vp.y)}, vp2 = {dpp_prev2(V[m].x, Vp.x), dpp_prev2(V[m].y, Vp.y)};
;                         const f32x2 gc = bg + g0 * gp2 + g1 * gp1 + g2 * G[m];
;                         const f32x2 vc = bv + v0 * vp2 + v1 * vp1 + v2 * V[m];
;                         const f32x2 xe = gc * (-LOG2E);
;                         f32x2 dn = {__builtin_amdgcn_exp2f(xe.x), __builtin_amdgcn_exp2f(xe.y)}; dn = dn + 1.0f;
;                         const f32x2 rc = {__builtin_amdgcn_rcpf(dn.x), __builtin_amdgcn_rcpf(dn.y)};
;                         const f32x2 rr = gc * rc * vc;
;                         wpk[m][jp] = pk2(rr.x, rr.y); }
;                 }
; #pragma unroll
;                 for (int m = 0; m < 4; ++m) { const int row = m ? tok0 + 16 * m : row0;
;                     *(u32x2*)(ACT + (size_t)row * 2816 + cl + 4 * n) = (u32x2){wpk[m][0], wpk[m][1]}; }
	v_pk_fma_f32 v[88:89], v[122:123], v[88:89], v[90:91]
	v_pk_fma_f32 v[88:89], v[86:87], v[126:127], v[88:89]
	v_pk_mul_f32 v[90:91], v[88:89], s[2:3] op_sel_hi:[1,0]
	v_exp_f32_e32 v90, v90
	v_exp_f32_e32 v91, v91
	v_mov_b32_dpp v80, v84 row_ror:1 row_mask:0xf bank_mask:0xf
	v_mov_b32_dpp v81, v85 row_ror:1 row_mask:0xf bank_mask:0xf
	v_mov_b32_dpp v92, v84 row_ror:2 row_mask:0xf bank_mask:0xf
	v_mov_b32_dpp v93, v85 row_ror:2 row_mask:0xf bank_mask:0xf
	v_pk_add_f32 v[84:85], v[90:91], 1.0 op_sel_hi:[1,0]
	v_pk_mul_f32 v[82:83], v[82:83], v[184:185] op_sel_hi:[1,0]
	v_rcp_f32_e32 v84, v84
	v_rcp_f32_e32 v85, v85
	v_mov_b32_dpp v92, v82 row_shr:2 row_mask:0xf bank_mask:0xf
	v_mov_b32_dpp v93, v83 row_shr:2 row_mask:0xf bank_mask:0xf
	v_mov_b32_dpp v80, v82 row_shr:1 row_mask:0xf bank_mask:0xf
	v_mov_b32_dpp v81, v83 row_shr:1 row_mask:0xf bank_mask:0xf
	v_pk_fma_f32 v[90:91], v[102:103], v[92:93], v[98:99]
	v_pk_mul_f32 v[84:85], v[88:89], v[84:85]
	v_pk_fma_f32 v[80:81], v[110:111], v[80:81], v[90:91]
	v_cvt_pk_bf16_f32 v234, v68, v69
	v_pk_fma_f32 v[80:81], v[82:83], v[114:115], v[80:81]
	v_pk_mul_f32 v[78:79], v[78:79], v[182:183] op_sel_hi:[1,0]
	v_pk_mul_f32 v[80:81], v[80:81], v[84:85]
	v_cvt_pk_bf16_f32 v235, v80, v81
	v_mov_b32_dpp v84, v86 row_ror:2 row_mask:0xf bank_mask:0xf
	v_mov_b32_dpp v85, v87 row_ror:2 row_mask:0xf bank_mask:0xf
	v_mov_b32_dpp v80, v86 row_ror:1 row_mask:0xf bank_mask:0xf
	v_mov_b32_dpp v81, v87 row_ror:1 row_mask:0xf bank_mask:0xf
	v_mov_b32_dpp v84, v78 row_shr:2 row_mask:0xf bank_mask:0xf
	v_mov_b32_dpp v85, v79 row_shr:2 row_mask:0xf bank_mask:0xf
	v_mov_b32_dpp v80, v78 row_shr:1 row_mask:0xf bank_mask:0xf
	v_mov_b32_dpp v81, v79 row_shr:1 row_mask:0xf bank_mask:0xf
	v_pk_fma_f32 v[84:85], v[118:119], v[84:85], v[106:107]
	v_pk_fma_f32 v[80:81], v[122:123], v[80:81], v[84:85]
	v_pk_fma_f32 v[80:81], v[78:79], v[126:127], v[80:81]
	v_pk_mul_f32 v[84:85], v[80:81], s[2:3] op_sel_hi:[1,0]
	v_exp_f32_e32 v84, v84
	v_exp_f32_e32 v85, v85
	v_mov_b32_dpp v86, v82 row_ror:1 row_mask:0xf bank_mask:0xf
	v_mov_b32_dpp v87, v83 row_ror:1 row_mask:0xf bank_mask:0xf
	v_mov_b32_dpp v88, v82 row_ror:2 row_mask:0xf bank_mask:0xf
	v_mov_b32_dpp v89, v83 row_ror:2 row_mask:0xf bank_mask:0xf
	v_pk_add_f32 v[82:83], v[84:85], 1.0 op_sel_hi:[1,0]
	v_pk_mul_f32 v[74:75], v[74:75], v[182:183] op_sel_hi:[1,0]
	v_rcp_f32_e32 v82, v82
	v_rcp_f32_e32 v83, v83
	v_mov_b32_dpp v88, v74 row_shr:2 row_mask:0xf bank_mask:0xf
	v_mov_b32_dpp v89, v75 row_shr:2 row_mask:0xf bank_mask:0xf
	v_mov_b32_dpp v86, v74 row_shr:1 row_mask:0xf bank_mask:0xf
	v_mov_b32_dpp v87, v75 row_shr:1 row_mask:0xf bank_mask:0xf
	v_pk_fma_f32 v[84:85], v[102:103], v[88:89], v[98:99]
	v_pk_mul_f32 v[80:81], v[80:81], v[82:83]
	v_pk_fma_f32 v[84:85], v[110:111], v[86:87], v[84:85]
	v_pk_fma_f32 v[84:85], v[74:75], v[114:115], v[84:85]
	v_pk_mul_f32 v[80:81], v[84:85], v[80:81]
	v_cvt_pk_bf16_f32 v238, v72, v73
	v_pk_mul_f32 v[70:71], v[70:71], v[180:181] op_sel_hi:[1,0]
	v_cvt_pk_bf16_f32 v239, v80, v81
	v_mov_b32_dpp v82, v78 row_ror:2 row_mask:0xf bank_mask:0xf
	v_mov_b32_dpp v83, v79 row_ror:2 row_mask:0xf bank_mask:0xf
	v_mov_b32_dpp v80, v78 row_ror:1 row_mask:0xf bank_mask:0xf
	v_mov_b32_dpp v81, v79 row_ror:1 row_mask:0xf bank_mask:0xf
	v_mov_b32_dpp v82, v70 row_shr:2 row_mask:0xf bank_mask:0xf
	v_mov_b32_dpp v83, v71 row_shr:2 row_mask:0xf bank_mask:0xf
	v_mov_b32_dpp v80, v70 row_shr:1 row_mask:0xf bank_mask:0xf
	v_mov_b32_dpp v81, v71 row_shr:1 row_mask:0xf bank_mask:0xf
	v_pk_fma_f32 v[82:83], v[118:119], v[82:83], v[106:107]
	v_pk_fma_f32 v[80:81], v[122:123], v[80:81], v[82:83]
	v_pk_fma_f32 v[70:71], v[70:71], v[126:127], v[80:81]
	v_pk_mul_f32 v[80:81], v[70:71], s[2:3] op_sel_hi:[1,0]
	v_exp_f32_e32 v80, v80
	v_exp_f32_e32 v81, v81
	v_mov_b32_dpp v78, v74 row_ror:1 row_mask:0xf bank_mask:0xf
	v_mov_b32_dpp v79, v75 row_ror:1 row_mask:0xf bank_mask:0xf
	v_mov_b32_dpp v84, v74 row_ror:2 row_mask:0xf bank_mask:0xf
	v_mov_b32_dpp v85, v75 row_ror:2 row_mask:0xf bank_mask:0xf
	v_pk_add_f32 v[74:75], v[80:81], 1.0 op_sel_hi:[1,0]
	v_pk_mul_f32 v[66:67], v[66:67], v[180:181] op_sel_hi:[1,0]
	v_rcp_f32_e32 v74, v74
	v_rcp_f32_e32 v75, v75
	v_mov_b32_dpp v84, v66 row_shr:2 row_mask:0xf bank_mask:0xf
	v_mov_b32_dpp v85, v67 row_shr:2 row_mask:0xf bank_mask:0xf
	v_mov_b32_dpp v78, v66 row_shr:1 row_mask:0xf bank_mask:0xf
	v_mov_b32_dpp v79, v67 row_shr:1 row_mask:0xf bank_mask:0xf
	v_pk_fma_f32 v[80:81], v[102:103], v[84:85], v[98:99]
	v_pk_mul_f32 v[70:71], v[70:71], v[74:75]
	v_pk_fma_f32 v[78:79], v[110:111], v[78:79], v[80:81]
	v_cvt_pk_bf16_f32 v254, v76, v77
	v_pk_fma_f32 v[66:67], v[66:67], v[114:115], v[78:79]
	s_nop 0
	v_pk_mul_f32 v[66:67], v[66:67], v[70:71]
	s_nop 0
	v_cvt_pk_bf16_f32 v255, v66, v67
	global_store_dwordx4 v[132:133], v[228:231], off
	global_store_dwordx4 v[134:135], v[232:235], off
	global_store_dwordx4 v[136:137], v[236:239], off
	global_store_dwordx4 v[138:139], v[252:255], off
	v_add_u32_e32 v96, 0x7c, v197
	v_med3_i32 v64, v96, 0, s51
	v_add_u32_e32 v97, 0x8c, v197
	v_add_u32_e32 v99, 0x9c, v197
	v_add_u32_e32 v101, 0xac, v197
	v_lshlrev_b32_e32 v64, 3, v64
	v_med3_i32 v65, v97, 0, s51
	v_med3_i32 v66, v99, 0, s51
	v_med3_i32 v67, v101, 0, s51
	v_lshlrev_b32_e32 v65, 3, v65
	v_lshlrev_b32_e32 v66, 3, v66
	v_lshlrev_b32_e32 v67, 3, v67
	v_cndmask_b32_e64 v103, v96, v190, s[4:5]
	v_mov_b32_e32 v112, v181
	v_mov_b32_e32 v113, v181
	ds_read_b128 v[72:75], v193
	ds_read_b128 v[84:87], v193 offset:128
	ds_read_b128 v[88:91], v193 offset:256
	ds_read_b128 v[92:95], v193 offset:384
	ds_read_b128 v[64:67], v193 offset:512
	ds_read_b128 v[68:71], v193 offset:640
	ds_read_b128 v[76:79], v193 offset:768
	ds_read_b128 v[80:83], v193 offset:896
	s_waitcnt vmcnt(4)
; #define LAS __attribute__((address_space(3)))
; DI float rs_from_ss(u64 ssq) { return rsqrtf((float)ssq * (1.f / (1048576.f * 1024.f)) + EPS); }
;     DI void operator()(const AccT& acc, const Unit& u, int wr, int wc, int fr, int fq) const {
;     ...
;             for (int m = 0; m < 4; ++m) { const int t = tok0 + 16 * m; const int tc = t < 0 ? 0 : (t >= S ? S - 1 : t); const float r = rs_from_ss(rowss[tc]); rs[m] = t < 0 ? 0.f : r; }
;             const int row0 = fr < 2 ? (S + 236 + fr) : tok0;
; #pragma unroll
;             for (int n = 0; n < 2; ++n) {
;                 const int lc = 8 * fq + 4 * n;
;                 unsigned wpk[4][2];
; #pragma unroll
;                 for (int jp = 0; jp < 2; ++jp) {
;                     const f32x2 bg = *(const LAS f32x2*)(P + lc + 2 * jp), g0 = *(const LAS f32x2*)(P + 32 + lc + 2 * jp), g1 = *(const LAS f32x2*)(P + 64 + lc + 2 * jp), g2 = *(const LAS f32x2*)(P + 96 + lc + 2 * jp);
;                     const f32x2 bv = *(const LAS f32x2*)(P + 128 + lc + 2 * jp), v0 = *(const LAS f32x2*)(P + 160 + lc + 2 * jp), v1 = *(const LAS f32x2*)(P + 192 + lc + 2 * jp), v2 = *(const LAS f32x2*)(P + 224 + lc + 2 * jp);
;                     f32x2 G[4], V[4];
; #pragma unroll
;                     for (int m = 0; m < 4; ++m) { G[m] = (f32x2){acc[ai][0][m][n][2 * jp], acc[ai][0][m][n][2 * jp + 1]} * rs[m]; V[m] = (f32x2){acc[ai][1][m][n][2 * jp], acc[ai][1][m][n][2 * jp + 1]} * rs[m]; }
; #pragma unroll
;                     for (int m = 0; m < 4; ++m) {
;                         const f32x2 zz = {0.f, 0.f}; const f32x2 Gp = m ? G[m - 1] : zz, Vp = m ? V[m - 1] : zz;
;                         const f32x2 gp1 = {dpp_prev1(G[m].x, Gp.x), dpp_prev1(G[m].y, Gp.y)}, gp2 = {dpp_prev2(G[m].x, Gp.x), dpp_prev2(G[m].y, Gp.y)};
;                         const f32x2 vp1 = {dpp_prev1(V[m].x, Vp.x), dpp_prev1(V[m].y, Vp.y)}, vp2 = {dpp_prev2(V[m].x, Vp.x), dpp_prev2(V[m].y, Vp.y)};
;                         const f32x2 gc = bg + g0 * gp2 + g1 * gp1 + g2 * G[m];
;                         const f32x2 vc = bv + v0 * vp2 + v1 * vp1 + v2 * V[m];
	v_mov_b32_e32 v104, v242
	v_mov_b32_e32 v105, v243
	v_mov_b32_e32 v106, v244
	v_mov_b32_e32 v107, v245
	v_mov_b32_e32 v108, v246
	v_mov_b32_e32 v109, v247
	v_mov_b32_e32 v110, v248
	v_mov_b32_e32 v111, v249
	v_ffbh_u32_e32 v98, v105
	v_ffbh_u32_e32 v100, v107
	v_ffbh_u32_e32 v102, v109
	v_min_u32_e32 v98, 32, v98
	v_min_u32_e32 v100, 32, v100
	v_min_u32_e32 v102, 32, v102
	v_lshlrev_b64 v[104:105], v98, v[104:105]
	v_ffbh_u32_e32 v114, v111
	v_lshlrev_b64 v[106:107], v100, v[106:107]
	v_lshlrev_b64 v[108:109], v102, v[108:109]
	v_min_u32_e32 v104, 1, v104
	v_min_u32_e32 v114, 32, v114
	v_min_u32_e32 v106, 1, v106
	v_min_u32_e32 v108, 1, v108
	v_or_b32_e32 v104, v105, v104
	v_lshlrev_b64 v[110:111], v114, v[110:111]
	v_or_b32_e32 v105, v107, v106
	v_or_b32_e32 v106, v109, v108
	v_cvt_f32_u32_e32 v104, v104
	v_min_u32_e32 v110, 1, v110
	v_cvt_f32_u32_e32 v105, v105
	v_cvt_f32_u32_e32 v106, v106
	v_or_b32_e32 v107, v111, v110
	v_sub_u32_e32 v98, 32, v98
	v_cvt_f32_u32_e32 v107, v107
	v_sub_u32_e32 v100, 32, v100
	v_sub_u32_e32 v102, 32, v102
	v_ldexp_f32 v98, v104, v98
	v_ldexp_f32 v100, v105, v100
	v_ldexp_f32 v102, v106, v102
	v_fmamk_f32 v98, v98, 0x30800000, v196
	v_sub_u32_e32 v114, 32, v114
	v_fmamk_f32 v100, v100, 0x30800000, v196
	v_fmamk_f32 v102, v102, 0x30800000, v196
	v_mul_f32_e32 v105, 0x4b800000, v98
	v_cmp_gt_f32_e32 vcc, s52, v98
	v_ldexp_f32 v104, v107, v114
	v_mul_f32_e32 v106, 0x4b800000, v100
	v_mul_f32_e32 v107, 0x4b800000, v102
	v_cndmask_b32_e32 v98, v98, v105, vcc
	v_cmp_gt_f32_e64 s[8:9], s52, v100
	v_cmp_gt_f32_e64 s[10:11], s52, v102
	v_fmamk_f32 v104, v104, 0x30800000, v196
	v_cndmask_b32_e64 v100, v100, v106, s[8:9]
	v_cndmask_b32_e64 v102, v102, v107, s[10:11]
	v_rsq_f32_e32 v98, v98
	v_mul_f32_e32 v108, 0x4b800000, v104
	v_cmp_gt_f32_e64 s[12:13], s52, v104
	v_rsq_f32_e32 v100, v100
	v_rsq_f32_e32 v102, v102
	v_cndmask_b32_e64 v104, v104, v108, s[12:13]
	v_rsq_f32_e32 v104, v104
	v_mul_f32_e32 v105, 0x45800000, v98
	v_mul_f32_e32 v106, 0x45800000, v100
	v_mul_f32_e32 v107, 0x45800000, v102
	v_cndmask_b32_e32 v98, v98, v105, vcc
	v_cmp_lt_i32_e32 vcc, -1, v96
	v_cndmask_b32_e64 v100, v100, v106, s[8:9]
	v_cndmask_b32_e64 v105, v102, v107, s[10:11]
	v_cndmask_b32_e32 v102, 0, v98, vcc
	v_cmp_lt_i32_e32 vcc, s53, v96
	v_mul_f32_e32 v108, 0x45800000, v104
	v_cndmask_b32_e64 v104, v104, v108, s[12:13]
	v_cndmask_b32_e32 v100, 0, v100, vcc
	v_cmp_lt_i32_e32 vcc, s54, v96
	v_pk_mul_f32 v[60:61], v[60:61], v[102:103] op_sel_hi:[1,0]
	v_pk_mul_f32 v[56:57], v[56:57], v[102:103] op_sel_hi:[1,0]
	v_cndmask_b32_e32 v98, 0, v105, vcc
	v_cmp_lt_i32_e32 vcc, s55, v96
	v_mov_b32_dpp v112, v60 row_shr:1 row_mask:0xf bank_mask:0xf
	v_mov_b32_dpp v113, v61 row_shr:1 row_mask:0xf bank_mask:0xf
	v_cndmask_b32_e32 v96, 0, v104, vcc
	v_pk_mul_f32 v[108:109], v[32:33], v[96:97] op_sel_hi:[1,0]
	v_mov_b32_e32 v32, v183
	v_mov_b32_e32 v33, v183
	v_pk_mul_f32 v[104:105], v[40:41], v[98:99] op_sel_hi:[1,0]
	v_mov_b32_dpp v32, v60 row_shr:2 row_mask:0xf bank_mask:0xf
	v_mov_b32_dpp v33, v61 row_shr:2 row_mask:0xf bank_mask:0xf
	s_waitcnt lgkmcnt(6)
	v_pk_fma_f32 v[32:33], v[84:85], v[32:33], v[72:73]
	v_mov_b32_e32 v40, v183
	s_waitcnt lgkmcnt(5)
	v_pk_fma_f32 v[32:33], v[88:89], v[112:113], v[32:33]
	v_mov_b32_e32 v41, v183
	s_waitcnt lgkmcnt(4)
	v_pk_fma_f32 v[32:33], v[92:93], v[60:61], v[32:33]
	v_pk_mul_f32 v[106:107], v[36:37], v[96:97] op_sel_hi:[1,0]
	v_pk_mul_f32 v[110:111], v[32:33], s[2:3] op_sel_hi:[1,0]
	v_mov_b32_e32 v36, v181
	v_exp_f32_e32 v110, v110
	v_exp_f32_e32 v111, v111
	v_mov_b32_e32 v37, v181
	v_mov_b32_dpp v40, v56 row_shr:2 row_mask:0xf bank_mask:0xf
	v_mov_b32_dpp v41, v57 row_shr:2 row_mask:0xf bank_mask:0xf
	v_pk_add_f32 v[110:111], v[110:111], 1.0 op_sel_hi:[1,0]
	v_mov_b32_dpp v36, v56 row_shr:1 row_mask:0xf bank_mask:0xf
	v_rcp_f32_e32 v110, v110
	v_rcp_f32_e32 v111, v111
	v_mov_b32_dpp v37, v57 row_shr:1 row_mask:0xf bank_mask:0xf
	s_waitcnt lgkmcnt(2)
	v_pk_fma_f32 v[40:41], v[68:69], v[40:41], v[64:65]
	v_pk_mul_f32 v[52:53], v[52:53], v[100:101] op_sel_hi:[1,0]
	s_waitcnt lgkmcnt(1)
	v_pk_fma_f32 v[36:37], v[76:77], v[36:37], v[40:41]
	v_pk_mul_f32 v[32:33], v[32:33], v[110:111]
	s_waitcnt lgkmcnt(0)
	v_pk_fma_f32 v[36:37], v[80:81], v[56:57], v[36:37]
	v_pk_mul_f32 v[32:33], v[36:37], v[32:33]
	v_mov_b32_dpp v40, v60 row_ror:2 row_mask:0xf bank_mask:0xf
	v_mov_b32_dpp v41, v61 row_ror:2 row_mask:0xf bank_mask:0xf
	v_mov_b32_dpp v36, v60 row_ror:1 row_mask:0xf bank_mask:0xf
	v_mov_b32_dpp v37, v61 row_ror:1 row_mask:0xf bank_mask:0xf
	v_mov_b32_dpp v40, v52 row_shr:2 row_mask:0xf bank_mask:0xf
	v_mov_b32_dpp v41, v53 row_shr:2 row_mask:0xf bank_mask:0xf
	v_mov_b32_dpp v36, v52 row_shr:1 row_mask:0xf bank_mask:0xf
	v_mov_b32_dpp v37, v53 row_shr:1 row_mask:0xf bank_mask:0xf
	v_pk_fma_f32 v[40:41], v[84:85], v[40:41], v[72:73]
	v_pk_fma_f32 v[36:37], v[88:89], v[36:37], v[40:41]
	v_pk_fma_f32 v[36:37], v[92:93], v[52:53], v[36:37]
	v_pk_mul_f32 v[48:49], v[48:49], v[100:101] op_sel_hi:[1,0]
	v_pk_mul_f32 v[40:41], v[36:37], s[2:3] op_sel_hi:[1,0]
	v_exp_f32_e32 v40, v40
	v_exp_f32_e32 v41, v41
	v_mov_b32_dpp v110, v56 row_ror:2 row_mask:0xf bank_mask:0xf
	v_mov_b32_dpp v111, v57 row_ror:2 row_mask:0xf bank_mask:0xf
	v_pk_add_f32 v[40:41], v[40:41], 1.0 op_sel_hi:[1,0]
	v_mov_b32_dpp v60, v56 row_ror:1 row_mask:0xf bank_mask:0xf
	v_rcp_f32_e32 v40, v40
	v_rcp_f32_e32 v41, v41
	v_mov_b32_dpp v61, v57 row_ror:1 row_mask:0xf bank_mask:0xf
	v_mov_b32_dpp v110, v48 row_shr:2 row_mask:0xf bank_mask:0xf
	v_mov_b32_dpp v111, v49 row_shr:2 row_mask:0xf bank_mask:0xf
	v_mov_b32_dpp v60, v48 row_shr:1 row_mask:0xf bank_mask:0xf
; DI unsigned pk2(float lo, float hi) { f32x2 v = {lo, hi}; bf16x2_t b = __builtin_convertvector(v, bf16x2_t); return __builtin_bit_cast(unsigned, b); }
;     DI void operator()(const AccT& acc, const Unit& u, int wr, int wc, int fr, int fq) const {
;     ...
;                     for (int m = 0; m < 4; ++m) { G[m] = (f32x2){acc[ai][0][m][n][2 * jp], acc[ai][0][m][n][2 * jp + 1]} * rs[m]; V[m] = (f32x2){acc[ai][1][m][n][2 * jp], acc[ai][1][m][n][2 * jp + 1]} * rs[m]; }
; #pragma unroll
;                     for (int m = 0; m < 4; ++m) {
;                         const f32x2 zz = {0.f, 0.f}; const f32x2 Gp = m ? G[m - 1] : zz, Vp = m ? V[m - 1] : zz;
;                         const f32x2 gp1 = {dpp_prev1(G[m].x, Gp.x), dpp_prev1(G[m].y, Gp.y)}, gp2 = {dpp_prev2(G[m].x, Gp.x), dpp_prev2(G[m].y, Gp.y)};
;                         const f32x2 vp1 = {dpp_prev1(V[m].x, Vp.x), dpp_prev1(V[m].y, Vp.y)}, vp2 = {dpp_prev2(V[m].x, Vp.x), dpp_prev2(V[m].y, Vp.y)};
;                         const f32x2 gc = bg + g0 * gp2 + g1 * gp1 + g2 * G[m];
;                         const f32x2 vc = bv + v0 * vp2 + v1 * vp1 + v2 * V[m];
;                         const f32x2 xe = gc * (-LOG2E);
;                         f32x2 dn = {__builtin_amdgcn_exp2f(xe.x), __builtin_amdgcn_exp2f(xe.y)}; dn = dn + 1.0f;
;                         const f32x2 rc = {__builtin_amdgcn_rcpf(dn.x), __builtin_amdgcn_rcpf(dn.y)};
;                         const f32x2 rr = gc * rc * vc;
;                         wpk[m][jp] = pk2(rr.x, rr.y); }
	v_mov_b32_dpp v61, v49 row_shr:1 row_mask:0xf bank_mask:0xf
	v_pk_fma_f32 v[56:57], v[68:69], v[110:111], v[64:65]
	v_pk_mul_f32 v[36:37], v[36:37], v[40:41]
	v_pk_fma_f32 v[56:57], v[76:77], v[60:61], v[56:57]
	v_pk_mul_f32 v[44:45], v[44:45], v[98:99] op_sel_hi:[1,0]
	v_pk_fma_f32 v[56:57], v[80:81], v[48:49], v[56:57]
	v_pk_mul_f32 v[36:37], v[56:57], v[36:37]
	v_mov_b32_dpp v56, v52 row_ror:2 row_mask:0xf bank_mask:0xf
	v_mov_b32_dpp v57, v53 row_ror:2 row_mask:0xf bank_mask:0xf
	v_mov_b32_dpp v40, v52 row_ror:1 row_mask:0xf bank_mask:0xf
	v_mov_b32_dpp v41, v53 row_ror:1 row_mask:0xf bank_mask:0xf
	v_mov_b32_dpp v56, v44 row_shr:2 row_mask:0xf bank_mask:0xf
	v_mov_b32_dpp v57, v45 row_shr:2 row_mask:0xf bank_mask:0xf
	v_mov_b32_dpp v40, v44 row_shr:1 row_mask:0xf bank_mask:0xf
	v_mov_b32_dpp v41, v45 row_shr:1 row_mask:0xf bank_mask:0xf
	v_pk_fma_f32 v[56:57], v[84:85], v[56:57], v[72:73]
	v_pk_fma_f32 v[40:41], v[88:89], v[40:41], v[56:57]
	v_pk_fma_f32 v[40:41], v[92:93], v[44:45], v[40:41]
	v_pk_mul_f32 v[56:57], v[40:41], s[2:3] op_sel_hi:[1,0]
	v_exp_f32_e32 v56, v56
	v_exp_f32_e32 v57, v57
	v_mov_b32_dpp v52, v48 row_ror:1 row_mask:0xf bank_mask:0xf
	v_mov_b32_dpp v53, v49 row_ror:1 row_mask:0xf bank_mask:0xf
	v_mov_b32_dpp v60, v48 row_ror:2 row_mask:0xf bank_mask:0xf
	v_mov_b32_dpp v61, v49 row_ror:2 row_mask:0xf bank_mask:0xf
	v_pk_add_f32 v[48:49], v[56:57], 1.0 op_sel_hi:[1,0]
	v_mov_b32_dpp v60, v104 row_shr:2 row_mask:0xf bank_mask:0xf
	v_rcp_f32_e32 v48, v48
	v_rcp_f32_e32 v49, v49
	v_mov_b32_dpp v61, v105 row_shr:2 row_mask:0xf bank_mask:0xf
	v_mov_b32_dpp v52, v104 row_shr:1 row_mask:0xf bank_mask:0xf
	v_mov_b32_dpp v53, v105 row_shr:1 row_mask:0xf bank_mask:0xf
	v_pk_fma_f32 v[56:57], v[68:69], v[60:61], v[64:65]
	v_pk_mul_f32 v[40:41], v[40:41], v[48:49]
	v_pk_fma_f32 v[52:53], v[76:77], v[52:53], v[56:57]
	v_pk_fma_f32 v[52:53], v[80:81], v[104:105], v[52:53]
	v_pk_mul_f32 v[40:41], v[52:53], v[40:41]
	v_mov_b32_dpp v48, v44 row_ror:1 row_mask:0xf bank_mask:0xf
	v_mov_b32_dpp v52, v44 row_ror:2 row_mask:0xf bank_mask:0xf
	v_mov_b32_dpp v53, v45 row_ror:2 row_mask:0xf bank_mask:0xf
	v_mov_b32_dpp v49, v45 row_ror:1 row_mask:0xf bank_mask:0xf
	v_mov_b32_dpp v52, v106 row_shr:2 row_mask:0xf bank_mask:0xf
	v_mov_b32_dpp v53, v107 row_shr:2 row_mask:0xf bank_mask:0xf
	v_mov_b32_dpp v48, v106 row_shr:1 row_mask:0xf bank_mask:0xf
	v_mov_b32_dpp v49, v107 row_shr:1 row_mask:0xf bank_mask:0xf
	v_pk_fma_f32 v[52:53], v[84:85], v[52:53], v[72:73]
	v_pk_fma_f32 v[48:49], v[88:89], v[48:49], v[52:53]
	v_pk_fma_f32 v[48:49], v[92:93], v[106:107], v[48:49]
	v_pk_mul_f32 v[52:53], v[48:49], s[2:3] op_sel_hi:[1,0]
	v_exp_f32_e32 v52, v52
	v_exp_f32_e32 v53, v53
	v_mov_b32_dpp v56, v104 row_ror:2 row_mask:0xf bank_mask:0xf
	v_mov_b32_dpp v57, v105 row_ror:2 row_mask:0xf bank_mask:0xf
	v_mov_b32_dpp v44, v104 row_ror:1 row_mask:0xf bank_mask:0xf
	v_pk_add_f32 v[52:53], v[52:53], 1.0 op_sel_hi:[1,0]
	v_mov_b32_dpp v45, v105 row_ror:1 row_mask:0xf bank_mask:0xf
	v_rcp_f32_e32 v52, v52
	v_rcp_f32_e32 v53, v53
	v_mov_b32_dpp v56, v108 row_shr:2 row_mask:0xf bank_mask:0xf
	v_mov_b32_dpp v57, v109 row_shr:2 row_mask:0xf bank_mask:0xf
	v_mov_b32_dpp v44, v108 row_shr:1 row_mask:0xf bank_mask:0xf
	v_mov_b32_dpp v45, v109 row_shr:1 row_mask:0xf bank_mask:0xf
	v_pk_fma_f32 v[56:57], v[68:69], v[56:57], v[64:65]
	v_pk_mul_f32 v[48:49], v[48:49], v[52:53]
	v_pk_fma_f32 v[44:45], v[76:77], v[44:45], v[56:57]
	v_pk_mul_f32 v[52:53], v[58:59], v[102:103] op_sel_hi:[1,0]
	v_pk_fma_f32 v[44:45], v[80:81], v[108:109], v[44:45]
	v_mov_b32_e32 v58, v183
	v_pk_mul_f32 v[44:45], v[44:45], v[48:49]
	v_pk_mul_f32 v[48:49], v[62:63], v[102:103] op_sel_hi:[1,0]
	v_mov_b32_e32 v59, v183
	v_mov_b32_e32 v56, v181
	v_mov_b32_e32 v57, v181
	v_mov_b32_dpp v58, v48 row_shr:2 row_mask:0xf bank_mask:0xf
	v_mov_b32_dpp v59, v49 row_shr:2 row_mask:0xf bank_mask:0xf
	v_mov_b32_dpp v56, v48 row_shr:1 row_mask:0xf bank_mask:0xf
	v_mov_b32_dpp v57, v49 row_shr:1 row_mask:0xf bank_mask:0xf
	v_pk_fma_f32 v[58:59], v[86:87], v[58:59], v[74:75]
	v_mov_b32_e32 v62, v183
	v_pk_fma_f32 v[56:57], v[90:91], v[56:57], v[58:59]
	v_mov_b32_e32 v63, v183
	v_pk_fma_f32 v[56:57], v[48:49], v[94:95], v[56:57]
	v_mov_b32_e32 v60, v181
	v_pk_mul_f32 v[58:59], v[56:57], s[2:3] op_sel_hi:[1,0]
	v_mov_b32_e32 v61, v181
	v_exp_f32_e32 v58, v58
	v_exp_f32_e32 v59, v59
	v_mov_b32_dpp v62, v52 row_shr:2 row_mask:0xf bank_mask:0xf
	v_mov_b32_dpp v63, v53 row_shr:2 row_mask:0xf bank_mask:0xf
	v_mov_b32_dpp v60, v52 row_shr:1 row_mask:0xf bank_mask:0xf
	v_pk_add_f32 v[58:59], v[58:59], 1.0 op_sel_hi:[1,0]
	v_mov_b32_dpp v61, v53 row_shr:1 row_mask:0xf bank_mask:0xf
	v_rcp_f32_e32 v58, v58
	v_rcp_f32_e32 v59, v59
	v_pk_fma_f32 v[62:63], v[70:71], v[62:63], v[66:67]
	v_cvt_pk_bf16_f32 v236, v32, v33
	v_pk_fma_f32 v[60:61], v[78:79], v[60:61], v[62:63]
	v_pk_mul_f32 v[56:57], v[56:57], v[58:59]
	v_pk_fma_f32 v[60:61], v[52:53], v[82:83], v[60:61]
	v_pk_mul_f32 v[56:57], v[60:61], v[56:57]
	v_pk_mul_f32 v[54:55], v[54:55], v[100:101] op_sel_hi:[1,0]
	v_cvt_pk_bf16_f32 v237, v56, v57
	v_mov_b32_dpp v58, v48 row_ror:2 row_mask:0xf bank_mask:0xf
	v_mov_b32_dpp v59, v49 row_ror:2 row_mask:0xf bank_mask:0xf
	v_mov_b32_dpp v56, v48 row_ror:1 row_mask:0xf bank_mask:0xf
	v_mov_b32_dpp v57, v49 row_ror:1 row_mask:0xf bank_mask:0xf
	v_mov_b32_dpp v58, v54 row_shr:2 row_mask:0xf bank_mask:0xf
	v_mov_b32_dpp v59, v55 row_shr:2 row_mask:0xf bank_mask:0xf
	v_mov_b32_dpp v56, v54 row_shr:1 row_mask:0xf bank_mask:0xf
	v_mov_b32_dpp v57, v55 row_shr:1 row_mask:0xf bank_mask:0xf
	v_pk_fma_f32 v[58:59], v[86:87], v[58:59], v[74:75]
; DI unsigned pk2(float lo, float hi) { f32x2 v = {lo, hi}; bf16x2_t b = __builtin_convertvector(v, bf16x2_t); return __builtin_bit_cast(unsigned, b); }
;     DI void operator()(const AccT& acc, const Unit& u, int wr, int wc, int fr, int fq) const {
;     ...
;                     for (int m = 0; m < 4; ++m) {
;                         const f32x2 zz = {0.f, 0.f}; const f32x2 Gp = m ? G[m - 1] : zz, Vp = m ? V[m - 1] : zz;
;                         const f32x2 gp1 = {dpp_prev1(G[m].x, Gp.x), dpp_prev1(G[m].y, Gp.y)}, gp2 = {dpp_prev2(G[m].x, Gp.x), dpp_prev2(G[m].y, Gp.y)};
;                         const f32x2 vp1 = {dpp_prev1(V[m].x, Vp.x), dpp_prev1(V[m].y, Vp.y)}, vp2 = {dpp_prev2(V[m].x, Vp.x), dpp_prev2(V[m].y, Vp.y)};
;                         const f32x2 gc = bg + g0 * gp2 + g1 * gp1 + g2 * G[m];
;                         const f32x2 vc = bv + v0 * vp2 + v1 * vp1 + v2 * V[m];
;                         const f32x2 xe = gc * (-LOG2E);
;                         f32x2 dn = {__builtin_amdgcn_exp2f(xe.x), __builtin_amdgcn_exp2f(xe.y)}; dn = dn + 1.0f;
;                         const f32x2 rc = {__builtin_amdgcn_rcpf(dn.x), __builtin_amdgcn_rcpf(dn.y)};
;                         const f32x2 rr = gc * rc * vc;
;                         wpk[m][jp] = pk2(rr.x, rr.y); }
;                 }
; #pragma unroll
;                 for (int m = 0; m < 4; ++m) { const int row = m ? tok0 + 16 * m : row0;
;                     *(u32x2*)(ACT + (size_t)row * 2816 + cl + 4 * n) = (u32x2){wpk[m][0], wpk[m][1]}; }
	v_pk_fma_f32 v[56:57], v[90:91], v[56:57], v[58:59]
	v_pk_fma_f32 v[56:57], v[54:55], v[94:95], v[56:57]
	v_pk_mul_f32 v[58:59], v[56:57], s[2:3] op_sel_hi:[1,0]
	v_exp_f32_e32 v58, v58
	v_exp_f32_e32 v59, v59
	v_mov_b32_dpp v48, v52 row_ror:1 row_mask:0xf bank_mask:0xf
	v_mov_b32_dpp v49, v53 row_ror:1 row_mask:0xf bank_mask:0xf
	v_mov_b32_dpp v60, v52 row_ror:2 row_mask:0xf bank_mask:0xf
	v_mov_b32_dpp v61, v53 row_ror:2 row_mask:0xf bank_mask:0xf
	v_pk_add_f32 v[52:53], v[58:59], 1.0 op_sel_hi:[1,0]
	v_pk_mul_f32 v[50:51], v[50:51], v[100:101] op_sel_hi:[1,0]
	v_rcp_f32_e32 v52, v52
	v_rcp_f32_e32 v53, v53
	v_mov_b32_dpp v60, v50 row_shr:2 row_mask:0xf bank_mask:0xf
	v_mov_b32_dpp v61, v51 row_shr:2 row_mask:0xf bank_mask:0xf
	v_mov_b32_dpp v48, v50 row_shr:1 row_mask:0xf bank_mask:0xf
	v_mov_b32_dpp v49, v51 row_shr:1 row_mask:0xf bank_mask:0xf
	v_pk_fma_f32 v[58:59], v[70:71], v[60:61], v[66:67]
	v_pk_mul_f32 v[52:53], v[56:57], v[52:53]
	v_pk_fma_f32 v[48:49], v[78:79], v[48:49], v[58:59]
	v_cvt_pk_bf16_f32 v244, v36, v37
	v_pk_fma_f32 v[48:49], v[50:51], v[82:83], v[48:49]
	v_pk_mul_f32 v[46:47], v[46:47], v[98:99] op_sel_hi:[1,0]
	v_pk_mul_f32 v[48:49], v[48:49], v[52:53]
	v_cvt_pk_bf16_f32 v245, v48, v49
	v_mov_b32_dpp v52, v54 row_ror:2 row_mask:0xf bank_mask:0xf
	v_mov_b32_dpp v53, v55 row_ror:2 row_mask:0xf bank_mask:0xf
	v_mov_b32_dpp v48, v54 row_ror:1 row_mask:0xf bank_mask:0xf
	v_mov_b32_dpp v49, v55 row_ror:1 row_mask:0xf bank_mask:0xf
	v_mov_b32_dpp v52, v46 row_shr:2 row_mask:0xf bank_mask:0xf
	v_mov_b32_dpp v53, v47 row_shr:2 row_mask:0xf bank_mask:0xf
	v_mov_b32_dpp v48, v46 row_shr:1 row_mask:0xf bank_mask:0xf
	v_mov_b32_dpp v49, v47 row_shr:1 row_mask:0xf bank_mask:0xf
	v_pk_fma_f32 v[52:53], v[86:87], v[52:53], v[74:75]
	v_pk_fma_f32 v[48:49], v[90:91], v[48:49], v[52:53]
	v_pk_fma_f32 v[48:49], v[46:47], v[94:95], v[48:49]
	v_pk_mul_f32 v[52:53], v[48:49], s[2:3] op_sel_hi:[1,0]
	v_exp_f32_e32 v52, v52
	v_exp_f32_e32 v53, v53
	v_mov_b32_dpp v54, v50 row_ror:1 row_mask:0xf bank_mask:0xf
	v_mov_b32_dpp v55, v51 row_ror:1 row_mask:0xf bank_mask:0xf
	v_mov_b32_dpp v56, v50 row_ror:2 row_mask:0xf bank_mask:0xf
	v_mov_b32_dpp v57, v51 row_ror:2 row_mask:0xf bank_mask:0xf
	v_pk_add_f32 v[50:51], v[52:53], 1.0 op_sel_hi:[1,0]
	v_pk_mul_f32 v[42:43], v[42:43], v[98:99] op_sel_hi:[1,0]
	v_rcp_f32_e32 v50, v50
	v_rcp_f32_e32 v51, v51
	v_mov_b32_dpp v56, v42 row_shr:2 row_mask:0xf bank_mask:0xf
	v_mov_b32_dpp v57, v43 row_shr:2 row_mask:0xf bank_mask:0xf
	v_mov_b32_dpp v54, v42 row_shr:1 row_mask:0xf bank_mask:0xf
	v_mov_b32_dpp v55, v43 row_shr:1 row_mask:0xf bank_mask:0xf
	v_pk_fma_f32 v[52:53], v[70:71], v[56:57], v[66:67]
	v_pk_mul_f32 v[48:49], v[48:49], v[50:51]
	v_pk_fma_f32 v[52:53], v[78:79], v[54:55], v[52:53]
	v_pk_fma_f32 v[52:53], v[42:43], v[82:83], v[52:53]
	v_pk_mul_f32 v[48:49], v[52:53], v[48:49]
	v_cvt_pk_bf16_f32 v248, v40, v41
	v_pk_mul_f32 v[38:39], v[38:39], v[96:97] op_sel_hi:[1,0]
	v_cvt_pk_bf16_f32 v249, v48, v49
	v_mov_b32_dpp v50, v46 row_ror:2 row_mask:0xf bank_mask:0xf
	v_mov_b32_dpp v51, v47 row_ror:2 row_mask:0xf bank_mask:0xf
	v_mov_b32_dpp v48, v46 row_ror:1 row_mask:0xf bank_mask:0xf
	v_mov_b32_dpp v49, v47 row_ror:1 row_mask:0xf bank_mask:0xf
	v_mov_b32_dpp v50, v38 row_shr:2 row_mask:0xf bank_mask:0xf
	v_mov_b32_dpp v51, v39 row_shr:2 row_mask:0xf bank_mask:0xf
	v_mov_b32_dpp v48, v38 row_shr:1 row_mask:0xf bank_mask:0xf
	v_mov_b32_dpp v49, v39 row_shr:1 row_mask:0xf bank_mask:0xf
	v_pk_fma_f32 v[50:51], v[86:87], v[50:51], v[74:75]
	v_pk_fma_f32 v[48:49], v[90:91], v[48:49], v[50:51]
	v_pk_fma_f32 v[38:39], v[38:39], v[94:95], v[48:49]
	v_pk_mul_f32 v[48:49], v[38:39], s[2:3] op_sel_hi:[1,0]
	v_exp_f32_e32 v48, v48
	v_exp_f32_e32 v49, v49
	v_mov_b32_dpp v46, v42 row_ror:1 row_mask:0xf bank_mask:0xf
	v_mov_b32_dpp v47, v43 row_ror:1 row_mask:0xf bank_mask:0xf
	v_mov_b32_dpp v52, v42 row_ror:2 row_mask:0xf bank_mask:0xf
	v_mov_b32_dpp v53, v43 row_ror:2 row_mask:0xf bank_mask:0xf
	v_pk_add_f32 v[42:43], v[48:49], 1.0 op_sel_hi:[1,0]
	v_pk_mul_f32 v[34:35], v[34:35], v[96:97] op_sel_hi:[1,0]
	v_rcp_f32_e32 v42, v42
	v_rcp_f32_e32 v43, v43
	v_mov_b32_dpp v52, v34 row_shr:2 row_mask:0xf bank_mask:0xf
	v_mov_b32_dpp v53, v35 row_shr:2 row_mask:0xf bank_mask:0xf
	v_mov_b32_dpp v46, v34 row_shr:1 row_mask:0xf bank_mask:0xf
	v_mov_b32_dpp v47, v35 row_shr:1 row_mask:0xf bank_mask:0xf
	v_pk_fma_f32 v[48:49], v[70:71], v[52:53], v[66:67]
	v_pk_mul_f32 v[38:39], v[38:39], v[42:43]
	v_pk_fma_f32 v[46:47], v[78:79], v[46:47], v[48:49]
	v_cvt_pk_bf16_f32 v252, v44, v45
	v_pk_fma_f32 v[34:35], v[34:35], v[82:83], v[46:47]
	s_nop 0
	v_pk_mul_f32 v[34:35], v[34:35], v[38:39]
	s_nop 0
	v_cvt_pk_bf16_f32 v253, v34, v35
	v_mad_i64_i32 v[34:35], s[8:9], v103, s48, v[128:129]
	v_lshl_add_u64 v[64:65], v[34:35], 0, v[130:131]
	v_mad_i64_i32 v[32:33], s[8:9], v97, s48, v[128:129]
	v_lshl_add_u64 v[66:67], v[32:33], 0, v[130:131]
	v_mad_i64_i32 v[32:33], s[8:9], v99, s48, v[128:129]
	v_lshl_add_u64 v[68:69], v[32:33], 0, v[130:131]
	v_mad_i64_i32 v[32:33], s[8:9], v101, s48, v[128:129]
	v_lshl_add_u64 v[70:71], v[32:33], 0, v[130:131]
	v_pk_mul_f32 v[30:31], v[30:31], v[102:103] op_sel_hi:[1,0]
	v_pk_mul_f32 v[22:23], v[22:23], v[100:101] op_sel_hi:[1,0]
	s_nop 0
	v_mov_b32_dpp v114, v30 row_ror:2 row_mask:0xf bank_mask:0xf
	v_mov_b32_dpp v115, v31 row_ror:2 row_mask:0xf bank_mask:0xf
	v_mov_b32_dpp v112, v30 row_ror:1 row_mask:0xf bank_mask:0xf
	v_mov_b32_dpp v113, v31 row_ror:1 row_mask:0xf bank_mask:0xf
	v_mov_b32_dpp v114, v22 row_shr:2 row_mask:0xf bank_mask:0xf
	v_mov_b32_dpp v115, v23 row_shr:2 row_mask:0xf bank_mask:0xf
	ds_read_b128 v[40:43], v193 offset:16
	ds_read_b128 v[52:55], v193 offset:144
	ds_read_b128 v[56:59], v193 offset:272
	ds_read_b128 v[60:63], v193 offset:400
	ds_read_b128 v[32:35], v193 offset:528
	ds_read_b128 v[36:39], v193 offset:656
	ds_read_b128 v[44:47], v193 offset:784
	ds_read_b128 v[48:51], v193 offset:912
	v_mov_b32_dpp v112, v22 row_shr:1 row_mask:0xf bank_mask:0xf
	v_mov_b32_dpp v113, v23 row_shr:1 row_mask:0xf bank_mask:0xf
	s_waitcnt lgkmcnt(6)
; #define LAS __attribute__((address_space(3)))
; DI unsigned pk2(float lo, float hi) { f32x2 v = {lo, hi}; bf16x2_t b = __builtin_convertvector(v, bf16x2_t); return __builtin_bit_cast(unsigned, b); }
;     DI void operator()(const AccT& acc, const Unit& u, int wr, int wc, int fr, int fq) const {
;     ...
;                     const f32x2 bg = *(const LAS f32x2*)(P + lc + 2 * jp), g0 = *(const LAS f32x2*)(P + 32 + lc + 2 * jp), g1 = *(const LAS f32x2*)(P + 64 + lc + 2 * jp), g2 = *(const LAS f32x2*)(P + 96 + lc + 2 * jp);
;                     const f32x2 bv = *(const LAS f32x2*)(P + 128 + lc + 2 * jp), v0 = *(const LAS f32x2*)(P + 160 + lc + 2 * jp), v1 = *(const LAS f32x2*)(P + 192 + lc + 2 * jp), v2 = *(const LAS f32x2*)(P + 224 + lc + 2 * jp);
;                     f32x2 G[4], V[4];
; #pragma unroll
;                     for (int m = 0; m < 4; ++m) { G[m] = (f32x2){acc[ai][0][m][n][2 * jp], acc[ai][0][m][n][2 * jp + 1]} * rs[m]; V[m] = (f32x2){acc[ai][1][m][n][2 * jp], acc[ai][1][m][n][2 * jp + 1]} * rs[m]; }
; #pragma unroll
;                     for (int m = 0; m < 4; ++m) {
;                         const f32x2 zz = {0.f, 0.f}; const f32x2 Gp = m ? G[m - 1] : zz, Vp = m ? V[m - 1] : zz;
;                         const f32x2 gp1 = {dpp_prev1(G[m].x, Gp.x), dpp_prev1(G[m].y, Gp.y)}, gp2 = {dpp_prev2(G[m].x, Gp.x), dpp_prev2(G[m].y, Gp.y)};
;                         const f32x2 vp1 = {dpp_prev1(V[m].x, Vp.x), dpp_prev1(V[m].y, Vp.y)}, vp2 = {dpp_prev2(V[m].x, Vp.x), dpp_prev2(V[m].y, Vp.y)};
;                         const f32x2 gc = bg + g0 * gp2 + g1 * gp1 + g2 * G[m];
;                         const f32x2 vc = bv + v0 * vp2 + v1 * vp1 + v2 * V[m];
;                         const f32x2 xe = gc * (-LOG2E);
;                         f32x2 dn = {__builtin_amdgcn_exp2f(xe.x), __builtin_amdgcn_exp2f(xe.y)}; dn = dn + 1.0f;
;                         const f32x2 rc = {__builtin_amdgcn_rcpf(dn.x), __builtin_amdgcn_rcpf(dn.y)};
;                         const f32x2 rr = gc * rc * vc;
;                         wpk[m][jp] = pk2(rr.x, rr.y); }
	v_pk_fma_f32 v[114:115], v[54:55], v[114:115], v[42:43]
	v_pk_mul_f32 v[28:29], v[28:29], v[102:103] op_sel_hi:[1,0]
	v_pk_mul_f32 v[24:25], v[24:25], v[102:103] op_sel_hi:[1,0]
	v_pk_mul_f32 v[20:21], v[20:21], v[100:101] op_sel_hi:[1,0]
	v_pk_mul_f32 v[16:17], v[16:17], v[100:101] op_sel_hi:[1,0]
	v_pk_mul_f32 v[26:27], v[26:27], v[102:103] op_sel_hi:[1,0]
	v_pk_mul_f32 v[100:101], v[18:19], v[100:101] op_sel_hi:[1,0]
	v_mov_b32_e32 v102, v183
	v_mov_b32_e32 v103, v183
	s_waitcnt lgkmcnt(5)
	v_pk_fma_f32 v[112:113], v[58:59], v[112:113], v[114:115]
	v_pk_mul_f32 v[76:77], v[12:13], v[98:99] op_sel_hi:[1,0]
	v_pk_mul_f32 v[72:73], v[8:9], v[98:99] op_sel_hi:[1,0]
	v_pk_mul_f32 v[14:15], v[14:15], v[98:99] op_sel_hi:[1,0]
	v_pk_mul_f32 v[10:11], v[10:11], v[98:99] op_sel_hi:[1,0]
	v_mov_b32_e32 v98, v181
	v_mov_b32_e32 v99, v181
	v_mov_b32_dpp v102, v30 row_shr:2 row_mask:0xf bank_mask:0xf
	v_mov_b32_dpp v103, v31 row_shr:2 row_mask:0xf bank_mask:0xf
	v_mov_b32_dpp v18, v22 row_ror:1 row_mask:0xf bank_mask:0xf
	v_mov_b32_dpp v19, v23 row_ror:1 row_mask:0xf bank_mask:0xf
	v_mov_b32_dpp v120, v22 row_ror:2 row_mask:0xf bank_mask:0xf
	v_mov_b32_dpp v121, v23 row_ror:2 row_mask:0xf bank_mask:0xf
	s_waitcnt lgkmcnt(4)
	v_pk_fma_f32 v[22:23], v[22:23], v[62:63], v[112:113]
	v_mov_b32_dpp v98, v30 row_shr:1 row_mask:0xf bank_mask:0xf
	v_mov_b32_dpp v99, v31 row_shr:1 row_mask:0xf bank_mask:0xf
	v_pk_mul_f32 v[112:113], v[22:23], s[2:3] op_sel_hi:[1,0]
	v_pk_fma_f32 v[102:103], v[54:55], v[102:103], v[42:43]
	v_exp_f32_e32 v112, v112
	v_exp_f32_e32 v113, v113
	v_pk_fma_f32 v[98:99], v[58:59], v[98:99], v[102:103]
	v_pk_fma_f32 v[30:31], v[30:31], v[62:63], v[98:99]
	v_pk_mul_f32 v[98:99], v[30:31], s[2:3] op_sel_hi:[1,0]
	v_pk_add_f32 v[112:113], v[112:113], 1.0 op_sel_hi:[1,0]
	v_exp_f32_e32 v98, v98
	v_exp_f32_e32 v99, v99
	v_mov_b32_dpp v118, v26 row_ror:2 row_mask:0xf bank_mask:0xf
	v_mov_b32_dpp v119, v27 row_ror:2 row_mask:0xf bank_mask:0xf
	v_rcp_f32_e32 v112, v112
	v_rcp_f32_e32 v113, v113
	v_mov_b32_dpp v116, v26 row_ror:1 row_mask:0xf bank_mask:0xf
	v_mov_b32_dpp v117, v27 row_ror:1 row_mask:0xf bank_mask:0xf
	v_mov_b32_dpp v118, v100 row_shr:2 row_mask:0xf bank_mask:0xf
	v_mov_b32_dpp v119, v101 row_shr:2 row_mask:0xf bank_mask:0xf
	v_mov_b32_dpp v116, v100 row_shr:1 row_mask:0xf bank_mask:0xf
	v_mov_b32_dpp v117, v101 row_shr:1 row_mask:0xf bank_mask:0xf
	s_waitcnt lgkmcnt(2)
	v_pk_fma_f32 v[114:115], v[38:39], v[118:119], v[34:35]
	v_pk_add_f32 v[98:99], v[98:99], 1.0 op_sel_hi:[1,0]
	v_mov_b32_e32 v182, v183
	s_waitcnt lgkmcnt(1)
	v_pk_fma_f32 v[114:115], v[46:47], v[116:117], v[114:115]
	v_rcp_f32_e32 v98, v98
	v_rcp_f32_e32 v99, v99
	v_pk_mul_f32 v[86:87], v[4:5], v[96:97] op_sel_hi:[1,0]
	v_mov_b32_e32 v12, v183
	v_mov_b32_e32 v13, v183
	v_mov_b32_e32 v4, v183
	v_mov_b32_e32 v5, v183
	v_mov_b32_e32 v180, v181
	v_mov_b32_dpp v182, v26 row_shr:2 row_mask:0xf bank_mask:0xf
	v_mov_b32_dpp v183, v27 row_shr:2 row_mask:0xf bank_mask:0xf
	v_mov_b32_dpp v122, v100 row_ror:1 row_mask:0xf bank_mask:0xf
	v_mov_b32_dpp v123, v101 row_ror:1 row_mask:0xf bank_mask:0xf
	v_mov_b32_dpp v124, v100 row_ror:2 row_mask:0xf bank_mask:0xf
	v_mov_b32_dpp v125, v101 row_ror:2 row_mask:0xf bank_mask:0xf
	s_waitcnt lgkmcnt(0)
	v_pk_fma_f32 v[100:101], v[100:101], v[50:51], v[114:115]
	v_pk_mul_f32 v[22:23], v[22:23], v[112:113]
	v_pk_mul_f32 v[84:85], v[0:1], v[96:97] op_sel_hi:[1,0]
	v_mov_b32_e32 v8, v181
	v_mov_b32_e32 v9, v181
	v_mov_b32_e32 v0, v181
	v_mov_b32_e32 v1, v181
	v_mov_b32_dpp v180, v26 row_shr:1 row_mask:0xf bank_mask:0xf
	v_mov_b32_dpp v181, v27 row_shr:1 row_mask:0xf bank_mask:0xf
	v_pk_mul_f32 v[22:23], v[100:101], v[22:23]
	v_pk_fma_f32 v[100:101], v[38:39], v[182:183], v[34:35]
	v_mov_b32_dpp v106, v76 row_ror:2 row_mask:0xf bank_mask:0xf
	v_mov_b32_dpp v107, v77 row_ror:2 row_mask:0xf bank_mask:0xf
	v_pk_fma_f32 v[100:101], v[46:47], v[180:181], v[100:101]
	v_mov_b32_dpp v104, v76 row_ror:1 row_mask:0xf bank_mask:0xf
	v_mov_b32_dpp v105, v77 row_ror:1 row_mask:0xf bank_mask:0xf
	v_mov_b32_dpp v106, v86 row_shr:2 row_mask:0xf bank_mask:0xf
	v_mov_b32_dpp v107, v87 row_shr:2 row_mask:0xf bank_mask:0xf
	v_pk_fma_f32 v[26:27], v[26:27], v[50:51], v[100:101]
	v_pk_mul_f32 v[30:31], v[30:31], v[98:99]
	v_mov_b32_dpp v104, v86 row_shr:1 row_mask:0xf bank_mask:0xf
	v_mov_b32_dpp v105, v87 row_shr:1 row_mask:0xf bank_mask:0xf
	v_pk_mul_f32 v[26:27], v[26:27], v[30:31]
	v_pk_fma_f32 v[30:31], v[52:53], v[106:107], v[40:41]
	v_mov_b32_dpp v12, v28 row_shr:2 row_mask:0xf bank_mask:0xf
	v_pk_fma_f32 v[30:31], v[56:57], v[104:105], v[30:31]
	v_mov_b32_dpp v13, v29 row_shr:2 row_mask:0xf bank_mask:0xf
	v_pk_fma_f32 v[30:31], v[86:87], v[60:61], v[30:31]
	v_pk_mul_f32 v[86:87], v[30:31], s[2:3] op_sel_hi:[1,0]
	v_mov_b32_dpp v8, v28 row_shr:1 row_mask:0xf bank_mask:0xf
	v_mov_b32_dpp v9, v29 row_shr:1 row_mask:0xf bank_mask:0xf
	v_mov_b32_dpp v92, v20 row_ror:2 row_mask:0xf bank_mask:0xf
	v_mov_b32_dpp v93, v21 row_ror:2 row_mask:0xf bank_mask:0xf
	v_exp_f32_e32 v86, v86
	v_exp_f32_e32 v87, v87
	v_pk_fma_f32 v[12:13], v[52:53], v[12:13], v[40:41]
	v_mov_b32_dpp v88, v20 row_ror:1 row_mask:0xf bank_mask:0xf
	v_mov_b32_dpp v89, v21 row_ror:1 row_mask:0xf bank_mask:0xf
	v_mov_b32_dpp v92, v76 row_shr:2 row_mask:0xf bank_mask:0xf
	v_mov_b32_dpp v93, v77 row_shr:2 row_mask:0xf bank_mask:0xf
	v_mov_b32_dpp v120, v14 row_shr:2 row_mask:0xf bank_mask:0xf
	v_mov_b32_dpp v121, v15 row_shr:2 row_mask:0xf bank_mask:0xf
	v_pk_fma_f32 v[8:9], v[56:57], v[8:9], v[12:13]
	v_mov_b32_dpp v88, v76 row_shr:1 row_mask:0xf bank_mask:0xf
; #define LAS __attribute__((address_space(3)))
; DI unsigned pk2(float lo, float hi) { f32x2 v = {lo, hi}; bf16x2_t b = __builtin_convertvector(v, bf16x2_t); return __builtin_bit_cast(unsigned, b); }
;     DI void operator()(const AccT& acc, const Unit& u, int wr, int wc, int fr, int fq) const {
;     ...
;                     const f32x2 bg = *(const LAS f32x2*)(P + lc + 2 * jp), g0 = *(const LAS f32x2*)(P + 32 + lc + 2 * jp), g1 = *(const LAS f32x2*)(P + 64 + lc + 2 * jp), g2 = *(const LAS f32x2*)(P + 96 + lc + 2 * jp);
;                     const f32x2 bv = *(const LAS f32x2*)(P + 128 + lc + 2 * jp), v0 = *(const LAS f32x2*)(P + 160 + lc + 2 * jp), v1 = *(const LAS f32x2*)(P + 192 + lc + 2 * jp), v2 = *(const LAS f32x2*)(P + 224 + lc + 2 * jp);
;                     f32x2 G[4], V[4];
; #pragma unroll
;                     for (int m = 0; m < 4; ++m) { G[m] = (f32x2){acc[ai][0][m][n][2 * jp], acc[ai][0][m][n][2 * jp + 1]} * rs[m]; V[m] = (f32x2){acc[ai][1][m][n][2 * jp], acc[ai][1][m][n][2 * jp + 1]} * rs[m]; }
; #pragma unroll
;                     for (int m = 0; m < 4; ++m) {
;                         const f32x2 zz = {0.f, 0.f}; const f32x2 Gp = m ? G[m - 1] : zz, Vp = m ? V[m - 1] : zz;
;                         const f32x2 gp1 = {dpp_prev1(G[m].x, Gp.x), dpp_prev1(G[m].y, Gp.y)}, gp2 = {dpp_prev2(G[m].x, Gp.x), dpp_prev2(G[m].y, Gp.y)};
;                         const f32x2 vp1 = {dpp_prev1(V[m].x, Vp.x), dpp_prev1(V[m].y, Vp.y)}, vp2 = {dpp_prev2(V[m].x, Vp.x), dpp_prev2(V[m].y, Vp.y)};
;                         const f32x2 gc = bg + g0 * gp2 + g1 * gp1 + g2 * G[m];
;                         const f32x2 vc = bv + v0 * vp2 + v1 * vp1 + v2 * V[m];
;                         const f32x2 xe = gc * (-LOG2E);
;                         f32x2 dn = {__builtin_amdgcn_exp2f(xe.x), __builtin_amdgcn_exp2f(xe.y)}; dn = dn + 1.0f;
;                         const f32x2 rc = {__builtin_amdgcn_rcpf(dn.x), __builtin_amdgcn_rcpf(dn.y)};
;                         const f32x2 rr = gc * rc * vc;
;                         wpk[m][jp] = pk2(rr.x, rr.y); }
	v_mov_b32_dpp v89, v77 row_shr:1 row_mask:0xf bank_mask:0xf
	v_mov_b32_dpp v18, v14 row_shr:1 row_mask:0xf bank_mask:0xf
	v_mov_b32_dpp v19, v15 row_shr:1 row_mask:0xf bank_mask:0xf
	v_pk_fma_f32 v[120:121], v[54:55], v[120:121], v[42:43]
	v_pk_fma_f32 v[92:93], v[52:53], v[92:93], v[40:41]
	v_pk_fma_f32 v[8:9], v[28:29], v[60:61], v[8:9]
	v_pk_fma_f32 v[18:19], v[58:59], v[18:19], v[120:121]
	v_pk_fma_f32 v[88:89], v[56:57], v[88:89], v[92:93]
	v_pk_mul_f32 v[12:13], v[8:9], s[2:3] op_sel_hi:[1,0]
	v_pk_fma_f32 v[18:19], v[14:15], v[62:63], v[18:19]
	v_pk_add_f32 v[86:87], v[86:87], 1.0 op_sel_hi:[1,0]
	v_pk_fma_f32 v[76:77], v[76:77], v[60:61], v[88:89]
	v_exp_f32_e32 v12, v12
	v_exp_f32_e32 v13, v13
	v_mov_b32_dpp v110, v72 row_ror:2 row_mask:0xf bank_mask:0xf
	v_mov_b32_dpp v111, v73 row_ror:2 row_mask:0xf bank_mask:0xf
	v_pk_mul_f32 v[120:121], v[18:19], s[2:3] op_sel_hi:[1,0]
	v_rcp_f32_e32 v86, v86
	v_rcp_f32_e32 v87, v87
	v_pk_mul_f32 v[88:89], v[76:77], s[2:3] op_sel_hi:[1,0]
	v_mov_b32_dpp v108, v72 row_ror:1 row_mask:0xf bank_mask:0xf
	v_mov_b32_dpp v109, v73 row_ror:1 row_mask:0xf bank_mask:0xf
	v_mov_b32_dpp v110, v84 row_shr:2 row_mask:0xf bank_mask:0xf
	v_mov_b32_dpp v111, v85 row_shr:2 row_mask:0xf bank_mask:0xf
	v_exp_f32_e32 v120, v120
	v_exp_f32_e32 v121, v121
	v_exp_f32_e32 v88, v88
	v_exp_f32_e32 v89, v89
	v_mov_b32_dpp v108, v84 row_shr:1 row_mask:0xf bank_mask:0xf
	v_mov_b32_dpp v109, v85 row_shr:1 row_mask:0xf bank_mask:0xf
	v_pk_mul_f32 v[2:3], v[2:3], v[96:97] op_sel_hi:[1,0]
	v_pk_mul_f32 v[6:7], v[6:7], v[96:97] op_sel_hi:[1,0]
	v_pk_fma_f32 v[96:97], v[36:37], v[110:111], v[32:33]
	v_pk_add_f32 v[12:13], v[12:13], 1.0 op_sel_hi:[1,0]
	v_pk_fma_f32 v[96:97], v[44:45], v[108:109], v[96:97]
	v_pk_mul_f32 v[30:31], v[30:31], v[86:87]
	v_pk_fma_f32 v[84:85], v[84:85], v[48:49], v[96:97]
	v_rcp_f32_e32 v12, v12
	v_rcp_f32_e32 v13, v13
	v_mov_b32_dpp v4, v24 row_shr:2 row_mask:0xf bank_mask:0xf
	v_mov_b32_dpp v5, v25 row_shr:2 row_mask:0xf bank_mask:0xf
	v_pk_add_f32 v[120:121], v[120:121], 1.0 op_sel_hi:[1,0]
	v_pk_mul_f32 v[30:31], v[84:85], v[30:31]
	v_pk_add_f32 v[84:85], v[88:89], 1.0 op_sel_hi:[1,0]
	v_mov_b32_dpp v0, v24 row_shr:1 row_mask:0xf bank_mask:0xf
	v_mov_b32_dpp v1, v25 row_shr:1 row_mask:0xf bank_mask:0xf
	v_mov_b32_dpp v94, v16 row_ror:2 row_mask:0xf bank_mask:0xf
	v_mov_b32_dpp v95, v17 row_ror:2 row_mask:0xf bank_mask:0xf
	v_rcp_f32_e32 v120, v120
	v_rcp_f32_e32 v121, v121
	v_rcp_f32_e32 v84, v84
	v_rcp_f32_e32 v85, v85
	v_pk_fma_f32 v[4:5], v[36:37], v[4:5], v[32:33]
	v_mov_b32_dpp v90, v16 row_ror:1 row_mask:0xf bank_mask:0xf
	v_mov_b32_dpp v91, v17 row_ror:1 row_mask:0xf bank_mask:0xf
	v_mov_b32_dpp v94, v72 row_shr:2 row_mask:0xf bank_mask:0xf
	v_mov_b32_dpp v95, v73 row_shr:2 row_mask:0xf bank_mask:0xf
	v_mov_b32_dpp v124, v10 row_shr:2 row_mask:0xf bank_mask:0xf
	v_mov_b32_dpp v125, v11 row_shr:2 row_mask:0xf bank_mask:0xf
	v_pk_fma_f32 v[0:1], v[44:45], v[0:1], v[4:5]
	v_mov_b32_dpp v90, v72 row_shr:1 row_mask:0xf bank_mask:0xf
	v_mov_b32_dpp v91, v73 row_shr:1 row_mask:0xf bank_mask:0xf
	v_mov_b32_dpp v122, v10 row_shr:1 row_mask:0xf bank_mask:0xf
	v_mov_b32_dpp v123, v11 row_shr:1 row_mask:0xf bank_mask:0xf
	v_pk_fma_f32 v[124:125], v[38:39], v[124:125], v[34:35]
	v_pk_fma_f32 v[86:87], v[36:37], v[94:95], v[32:33]
	v_pk_fma_f32 v[0:1], v[24:25], v[48:49], v[0:1]
	v_pk_mul_f32 v[4:5], v[8:9], v[12:13]
	v_pk_fma_f32 v[122:123], v[46:47], v[122:123], v[124:125]
	v_pk_fma_f32 v[86:87], v[44:45], v[90:91], v[86:87]
	v_pk_mul_f32 v[0:1], v[0:1], v[4:5]
	v_mov_b32_dpp v78, v28 row_ror:2 row_mask:0xf bank_mask:0xf
	v_mov_b32_dpp v79, v29 row_ror:2 row_mask:0xf bank_mask:0xf
	v_pk_fma_f32 v[122:123], v[10:11], v[50:51], v[122:123]
	v_pk_mul_f32 v[18:19], v[18:19], v[120:121]
; DI unsigned pk2(float lo, float hi) { f32x2 v = {lo, hi}; bf16x2_t b = __builtin_convertvector(v, bf16x2_t); return __builtin_bit_cast(unsigned, b); }
;     DI void operator()(const AccT& acc, const Unit& u, int wr, int wc, int fr, int fq) const {
;     ...
;                     for (int m = 0; m < 4; ++m) { G[m] = (f32x2){acc[ai][0][m][n][2 * jp], acc[ai][0][m][n][2 * jp + 1]} * rs[m]; V[m] = (f32x2){acc[ai][1][m][n][2 * jp], acc[ai][1][m][n][2 * jp + 1]} * rs[m]; }
; #pragma unroll
;                     for (int m = 0; m < 4; ++m) {
;                         const f32x2 zz = {0.f, 0.f}; const f32x2 Gp = m ? G[m - 1] : zz, Vp = m ? V[m - 1] : zz;
;                         const f32x2 gp1 = {dpp_prev1(G[m].x, Gp.x), dpp_prev1(G[m].y, Gp.y)}, gp2 = {dpp_prev2(G[m].x, Gp.x), dpp_prev2(G[m].y, Gp.y)};
;                         const f32x2 vp1 = {dpp_prev1(V[m].x, Vp.x), dpp_prev1(V[m].y, Vp.y)}, vp2 = {dpp_prev2(V[m].x, Vp.x), dpp_prev2(V[m].y, Vp.y)};
;                         const f32x2 gc = bg + g0 * gp2 + g1 * gp1 + g2 * G[m];
;                         const f32x2 vc = bv + v0 * vp2 + v1 * vp1 + v2 * V[m];
;                         const f32x2 xe = gc * (-LOG2E);
;                         f32x2 dn = {__builtin_amdgcn_exp2f(xe.x), __builtin_amdgcn_exp2f(xe.y)}; dn = dn + 1.0f;
;                         const f32x2 rc = {__builtin_amdgcn_rcpf(dn.x), __builtin_amdgcn_rcpf(dn.y)};
;                         const f32x2 rr = gc * rc * vc;
;                         wpk[m][jp] = pk2(rr.x, rr.y); }
;                 }
; #pragma unroll
;                 for (int m = 0; m < 4; ++m) { const int row = m ? tok0 + 16 * m : row0;
;                     *(u32x2*)(ACT + (size_t)row * 2816 + cl + 4 * n) = (u32x2){wpk[m][0], wpk[m][1]}; }
;                 __builtin_amdgcn_sched_barrier(0);
	v_cvt_pk_bf16_f32 v239, v26, v27
	v_pk_fma_f32 v[72:73], v[72:73], v[48:49], v[86:87]
	v_pk_mul_f32 v[76:77], v[76:77], v[84:85]
	v_cvt_pk_bf16_f32 v238, v0, v1
	v_mov_b32_dpp v4, v14 row_ror:2 row_mask:0xf bank_mask:0xf
	v_mov_b32_dpp v5, v15 row_ror:2 row_mask:0xf bank_mask:0xf
	v_mov_b32_dpp v74, v28 row_ror:1 row_mask:0xf bank_mask:0xf
	v_mov_b32_dpp v75, v29 row_ror:1 row_mask:0xf bank_mask:0xf
	v_mov_b32_dpp v78, v20 row_shr:2 row_mask:0xf bank_mask:0xf
	v_mov_b32_dpp v79, v21 row_shr:2 row_mask:0xf bank_mask:0xf
	v_pk_mul_f32 v[18:19], v[122:123], v[18:19]
	v_pk_mul_f32 v[72:73], v[72:73], v[76:77]
	v_mov_b32_dpp v0, v14 row_ror:1 row_mask:0xf bank_mask:0xf
	v_mov_b32_dpp v1, v15 row_ror:1 row_mask:0xf bank_mask:0xf
	v_mov_b32_dpp v4, v6 row_shr:2 row_mask:0xf bank_mask:0xf
	v_mov_b32_dpp v5, v7 row_shr:2 row_mask:0xf bank_mask:0xf
	v_mov_b32_dpp v74, v20 row_shr:1 row_mask:0xf bank_mask:0xf
	v_mov_b32_dpp v75, v21 row_shr:1 row_mask:0xf bank_mask:0xf
	v_cvt_pk_bf16_f32 v251, v18, v19
	v_cvt_pk_bf16_f32 v250, v72, v73
	v_pk_fma_f32 v[72:73], v[52:53], v[78:79], v[40:41]
	v_mov_b32_dpp v0, v6 row_shr:1 row_mask:0xf bank_mask:0xf
	v_mov_b32_dpp v1, v7 row_shr:1 row_mask:0xf bank_mask:0xf
	v_pk_fma_f32 v[4:5], v[54:55], v[4:5], v[42:43]
	v_pk_fma_f32 v[72:73], v[56:57], v[74:75], v[72:73]
	v_pk_fma_f32 v[0:1], v[58:59], v[0:1], v[4:5]
	v_pk_fma_f32 v[20:21], v[20:21], v[60:61], v[72:73]
	v_pk_fma_f32 v[0:1], v[6:7], v[62:63], v[0:1]
	v_pk_mul_f32 v[72:73], v[20:21], s[2:3] op_sel_hi:[1,0]
	v_pk_mul_f32 v[4:5], v[0:1], s[2:3] op_sel_hi:[1,0]
	v_exp_f32_e32 v72, v72
	v_exp_f32_e32 v73, v73
	v_exp_f32_e32 v4, v4
	v_exp_f32_e32 v5, v5
	v_pk_add_f32 v[72:73], v[72:73], 1.0 op_sel_hi:[1,0]
	v_pk_add_f32 v[4:5], v[4:5], 1.0 op_sel_hi:[1,0]
	v_mov_b32_dpp v82, v24 row_ror:2 row_mask:0xf bank_mask:0xf
	v_mov_b32_dpp v83, v25 row_ror:2 row_mask:0xf bank_mask:0xf
	v_rcp_f32_e32 v72, v72
	v_rcp_f32_e32 v73, v73
	v_mov_b32_dpp v12, v10 row_ror:2 row_mask:0xf bank_mask:0xf
	v_mov_b32_dpp v13, v11 row_ror:2 row_mask:0xf bank_mask:0xf
	v_rcp_f32_e32 v4, v4
	v_rcp_f32_e32 v5, v5
	v_mov_b32_dpp v80, v24 row_ror:1 row_mask:0xf bank_mask:0xf
	v_mov_b32_dpp v81, v25 row_ror:1 row_mask:0xf bank_mask:0xf
	v_mov_b32_dpp v82, v16 row_shr:2 row_mask:0xf bank_mask:0xf
	v_mov_b32_dpp v83, v17 row_shr:2 row_mask:0xf bank_mask:0xf
	v_mov_b32_dpp v8, v10 row_ror:1 row_mask:0xf bank_mask:0xf
	v_mov_b32_dpp v9, v11 row_ror:1 row_mask:0xf bank_mask:0xf
	v_mov_b32_dpp v12, v2 row_shr:2 row_mask:0xf bank_mask:0xf
	v_mov_b32_dpp v13, v3 row_shr:2 row_mask:0xf bank_mask:0xf
	v_mov_b32_dpp v80, v16 row_shr:1 row_mask:0xf bank_mask:0xf
	v_mov_b32_dpp v81, v17 row_shr:1 row_mask:0xf bank_mask:0xf
	v_pk_fma_f32 v[74:75], v[36:37], v[82:83], v[32:33]
	v_mov_b32_dpp v8, v2 row_shr:1 row_mask:0xf bank_mask:0xf
	v_mov_b32_dpp v9, v3 row_shr:1 row_mask:0xf bank_mask:0xf
	v_pk_fma_f32 v[6:7], v[38:39], v[12:13], v[34:35]
	v_pk_fma_f32 v[74:75], v[44:45], v[80:81], v[74:75]
	v_pk_fma_f32 v[6:7], v[46:47], v[8:9], v[6:7]
	v_pk_fma_f32 v[16:17], v[16:17], v[48:49], v[74:75]
	v_pk_mul_f32 v[20:21], v[20:21], v[72:73]
	v_pk_fma_f32 v[2:3], v[2:3], v[50:51], v[6:7]
	v_pk_mul_f32 v[0:1], v[0:1], v[4:5]
	v_pk_mul_f32 v[16:17], v[16:17], v[20:21]
	v_pk_mul_f32 v[0:1], v[2:3], v[0:1]
	v_cvt_pk_bf16_f32 v247, v22, v23
	v_cvt_pk_bf16_f32 v254, v30, v31
	v_cvt_pk_bf16_f32 v246, v16, v17
	v_cvt_pk_bf16_f32 v255, v0, v1
	global_store_dwordx4 v[64:65], v[236:239], off
	global_store_dwordx4 v[66:67], v[244:247], off
	global_store_dwordx4 v[68:69], v[248:251], off
	global_store_dwordx4 v[70:71], v[252:255], off
	s_and_b64 vcc, exec, s[6:7]
	s_mov_b64 s[6:7], -1
	s_cbranch_vccnz .LBB0_1817
	s_andn2_b64 vcc, exec, s[14:15]
	s_cbranch_vccnz .LBB0_1816
	s_barrier
	s_branch .LBB0_1816
